# attention loop: 4x unrolled steady loop with constant ring offsets, paired waits, original XCD item order
# speedup vs baseline: 1.0148x; 1.0148x over previous
; #define LAS __attribute__((address_space(3)))
; __device__ __forceinline__ void attn_block(LAS unsigned char* lds, const bf16_t* P, bf16_t* mix, int b, int h, int qb, float lam, float outscale, const float* subln) {
;     ...
;     const int tid = tid_, lane = tid & 63, wave = __builtin_amdgcn_readfirstlane(tid >> 6), r32 = lane & 31, hi = lane >> 5;
;     const int comp = wave >> 2, wq = wave & 3;
;     const int rb = b * SEQ, q0 = qb * 128, qw0 = q0 + wq * 32, qrow = qw0 + r32;
;     const float C1 = 0.125f * 1.4426950408889634f;
;     bf16x8 qf[4];
;     { const bf16_t* qp = P + (size_t)(rb + qrow) * INC + COL_AQ + h * 128 + comp * 64 + hi * 8;
; #pragma unroll
;       for (int ks = 0; ks < 4; ++ks) qf[ks] = *(const bf16x8*)(qp + 16 * ks); }
;     const int ntiles = 2 * qb + 2;
;     const int srow = tid >> 4, sch = tid & 15;
;     const bf16_t* kg = P + (size_t)rb * INC + COL_AK + h * 128 + sch * 8;
;     const bf16_t* vg = P + (size_t)rb * INC + COL_AV + h * 128 + sch * 8;
;     const unsigned so0 = off_b(srow, sch), so1 = off_b(srow + 32, sch);
;     u32x4 kr0, kr1, vr0, vr1;
;     kr0 = *(const u32x4*)(kg + (size_t)srow * INC); kr1 = *(const u32x4*)(kg + (size_t)(srow + 32) * INC);
;     vr0 = *(const u32x4*)(vg + (size_t)srow * INC); vr1 = *(const u32x4*)(vg + (size_t)(srow + 32) * INC);
;     *(LAS u32x4*)(lds + ATT_K0 + so0) = kr0; *(LAS u32x4*)(lds + ATT_K0 + so1) = kr1;
;     *(LAS u32x4*)(lds + ATT_V0 + so0) = vr0; *(LAS u32x4*)(lds + ATT_V0 + so1) = vr1;
; __device__ __forceinline__ void attn_phase(LAS unsigned char* lds, const Params& p, int layer) {
;     ...
;     for (int it0 = bid; it0 < 512; it0 += nblk) {
;         int it = it0;
;         if (nblk == 256) { const int x = bid & 7, j = bid >> 3, r = it0 >> 8; it = (2 * x + r) * 32 + j; }
;         const int bh = it >> 5, pr = it & 31, b = bh >> 3, h = bh & 7;
;         attn_block(lds, P, mix, b, h, pr, lam, 1.0f - lambda_init, subln);
.LBB0_98:
	s_ashr_i32 s2, s66, 8
	s_add_i32 s2, s2, s68
	s_lshl_b32 s2, s2, 5
	s_add_i32 s2, s2, s67
	s_and_b64 s[38:39], s[46:47], exec
	v_mov_b32_e32 v20, v212
	s_cselect_b32 s72, s2, s66
	s_and_b32 s33, s72, 31
	v_readfirstlane_b32 s42, v20
	s_lshr_b32 s36, s42, 1
	s_lshl_b32 s73, s33, 7
	s_and_b32 s60, s36, 0x60
	v_and_b32_e32 v166, 31, v20
	s_lshl_b32 s2, s72, 5
	s_or_b32 s61, s73, s60
	v_readlane_b32 s52, v255, 12
	s_and_b32 s2, s2, 0xffffe000
	v_or_b32_e32 v176, s61, v166
	v_readlane_b32 s53, v255, 13
	v_or_b32_e32 v130, s2, v176
	s_movk_i32 s74, 0x3800
	v_mov_b64_e32 v[2:3], s[52:53]
	v_mad_i64_i32 v[2:3], s[38:39], v130, s74, v[2:3]
	s_lshl_b32 s36, s72, 2
	s_ashr_i32 s43, s42, 8
	s_and_b32 s38, s36, 0x380
	s_lshl_b32 s36, s38, 1
	s_lshl_b32 s50, s43, 6
	v_lshl_add_u64 v[2:3], v[2:3], 0, s[36:37]
	s_ashr_i32 s51, s50, 31
	v_lshl_add_u64 v[2:3], s[50:51], 1, v[2:3]
	s_mul_i32 s50, s2, 0x3800
	s_mul_hi_i32 s51, s2, 0x3800
	s_add_u32 s39, s52, s50
	v_bfe_u32 v165, v20, 5, 1
	s_addc_u32 s63, s53, s51
	v_lshlrev_b32_e32 v0, 4, v165
	v_and_b32_e32 v22, 15, v20
	s_add_u32 s62, s39, s36
	v_lshl_add_u64 v[18:19], v[2:3], 0, v[0:1]
	v_ashrrev_i32_e32 v21, 4, v20
	s_addc_u32 s63, s63, 0
	v_lshlrev_b32_e32 v0, 4, v22
	v_lshl_add_u64 v[2:3], s[62:63], 0, v[0:1]
	v_add_u32_e32 v23, 32, v21
	v_mad_i64_i32 v[4:5], s[70:71], v21, s74, v[2:3]
	v_mad_i64_i32 v[6:7], s[70:71], v23, s74, v[2:3]
	s_add_u32 s64, s62, 0x1000
	global_load_dwordx4 v[2:5], v[4:5], off offset:2048
	s_nop 0
	global_load_dwordx4 v[6:9], v[6:7], off offset:2048
	s_addc_u32 s65, s63, 0
	v_lshl_add_u64 v[10:11], s[64:65], 0, v[0:1]
	v_mad_i64_i32 v[12:13], s[70:71], v21, s74, v[10:11]
	v_mad_i64_i32 v[14:15], s[70:71], v23, s74, v[10:11]
	global_load_dwordx4 v[10:13], v[12:13], off
	s_nop 0
	global_load_dwordx4 v[14:17], v[14:15], off
	s_nop 0
	global_load_dwordx4 v[110:113], v[18:19], off
	global_load_dwordx4 v[106:109], v[18:19], off offset:32
	global_load_dwordx4 v[102:105], v[18:19], off offset:64
	global_load_dwordx4 v[98:101], v[18:19], off offset:96
	v_lshlrev_b32_e32 v26, 2, v21
	v_bfe_u32 v27, v21, 2, 2
	v_and_b32_e32 v26, 12, v26
	v_lshlrev_b32_e32 v29, 8, v23
	v_lshlrev_b32_e32 v23, 2, v23
	v_lshlrev_b32_e32 v25, 8, v21
	v_bitop3_b32 v26, v26, v22, v27 bitop3:0x36
	v_and_b32_e32 v23, 12, v23
	v_lshl_or_b32 v179, v26, 4, v25
	v_bitop3_b32 v22, v23, v22, v27 bitop3:0x36
	v_lshl_or_b32 v182, v22, 4, v29
	v_add_u32_e32 v22, 0, v179
	v_bfe_u32 v19, v20, 2, 2
	v_lshrrev_b32_e32 v24, 3, v20
	v_add_u32_e32 v23, 0, v182
	v_lshlrev_b32_e32 v164, 2, v165
	v_lshlrev_b32_e32 v18, 2, v20
	v_and_or_b32 v18, v18, 12, v19
	s_lshl_b32 s36, s43, 3
	s_lshl_b32 s39, s72, 3
	v_lshlrev_b32_e32 v28, 8, v166
	v_or_b32_e32 v25, s36, v165
	v_bitop3_b32 v26, s36, v18, v165 bitop3:0x36
	s_and_b32 s39, s39, 0x700
	v_lshl_add_u32 v180, v26, 4, v28
	v_bitop3_b32 v26, v25, v18, 2 bitop3:0x36
	v_bitop3_b32 v27, v25, v18, 4 bitop3:0x36
	v_bitop3_b32 v18, v25, v18, 6 bitop3:0x36
	v_lshl_add_u32 v181, v26, 4, v28
	v_lshl_add_u32 v178, v27, 4, v28
	v_lshl_add_u32 v177, v18, 4, v28
	v_lshlrev_b32_e32 v132, 3, v165
	v_ashrrev_i32_e32 v131, 31, v130
	s_or_b32 s69, s61, 31
	s_or_b32 s36, s73, 64
	v_mov_b32_e32 v175, 0xff800000
	v_mov_b32_e32 v167, 0
	s_waitcnt vmcnt(7)
	ds_write_b128 v22, v[2:5]
	s_waitcnt vmcnt(6)
	ds_write_b128 v23, v[6:9]
	s_waitcnt vmcnt(5)
	ds_write_b128 v22, v[10:13] offset:32768
	s_waitcnt vmcnt(4)
; #define LAS __attribute__((address_space(3)))
; __device__ __forceinline__ void attn_block(LAS unsigned char* lds, const bf16_t* P, bf16_t* mix, int b, int h, int qb, float lam, float outscale, const float* subln) {
;     ...
;     *(LAS u32x4*)(lds + ATT_K0 + so0) = kr0; *(LAS u32x4*)(lds + ATT_K0 + so1) = kr1;
;     *(LAS u32x4*)(lds + ATT_V0 + so0) = vr0; *(LAS u32x4*)(lds + ATT_V0 + so1) = vr1;
;     float mrun = -INFINITY, lrun = 0.f;
;     f32x16 o[4];
; #pragma unroll
;     for (int c = 0; c < 4; ++c)
; #pragma unroll
;         for (int j = 0; j < 16; ++j) o[c][j] = 0.f;
;     const int blk = (lane >> 4) & 1, qq = (lane & 15) >> 2, pp = lane & 3;
;     unsigned kbase[4], vbase[4][2];
; #pragma unroll
;     for (int ks = 0; ks < 4; ++ks) kbase[ks] = off_b(r32, comp * 8 + 2 * ks + hi);
; #pragma unroll
;     for (int c = 0; c < 4; ++c)
; #pragma unroll
;         for (int t = 0; t < 2; ++t) vbase[c][t] = off_b(8 * t + 4 * hi + qq, 4 * c + 2 * blk + (pp >> 1)) + 8 * (pp & 1);
;     asm volatile("" :: "v"(qf[0]), "v"(qf[1]), "v"(qf[2]), "v"(qf[3]));
;     for (int kt = 0; kt < ntiles; ++kt) {
;         __syncthreads();
;         const int buf = kt & 1;
;         if (kt + 1 < ntiles) {
;             const size_t ro = (size_t)(64 * (kt + 1)) * INC;
;             kr0 = *(const u32x4*)(kg + ro + (size_t)srow * INC); kr1 = *(const u32x4*)(kg + ro + (size_t)(srow + 32) * INC);
;             vr0 = *(const u32x4*)(vg + ro + (size_t)srow * INC); vr1 = *(const u32x4*)(vg + ro + (size_t)(srow + 32) * INC);
;         }
	ds_write_b128 v23, v[14:17] offset:32768
	v_bfe_u32 v2, v20, 1, 1
	v_and_or_b32 v2, v24, 2, v2
	v_lshlrev_b32_e32 v3, 2, v19
	v_lshlrev_b32_e32 v4, 3, v20
	v_or_b32_e32 v5, v164, v19
	v_bitop3_b32 v6, v3, v2, v165 bitop3:0x36
	v_and_b32_e32 v4, 8, v4
	v_lshlrev_b32_e32 v5, 8, v5
	v_lshlrev_b32_e32 v6, 4, v6
	v_or3_b32 v173, v6, v5, v4
	v_or_b32_e32 v6, 8, v164
	v_or_b32_e32 v7, v6, v19
	v_lshrrev_b32_e32 v6, 2, v6
	v_lshlrev_b32_e32 v7, 8, v7
	v_bitop3_b32 v8, v6, v2, v3 bitop3:0x36
	v_lshl_add_u32 v8, v8, 4, v7
	v_or_b32_e32 v174, v8, v4
	v_or_b32_e32 v8, 4, v2
	v_bitop3_b32 v9, v3, v8, v165 bitop3:0x36
	v_bitop3_b32 v8, v6, v8, v3 bitop3:0x36
	v_lshl_add_u32 v8, v8, 4, v7
	v_lshlrev_b32_e32 v9, 4, v9
	v_or_b32_e32 v172, v8, v4
	v_or_b32_e32 v8, 8, v2
	v_or3_b32 v170, v9, v5, v4
	v_bitop3_b32 v9, v3, v8, v165 bitop3:0x36
	v_bitop3_b32 v8, v6, v8, v3 bitop3:0x36
	v_lshl_add_u32 v8, v8, 4, v7
	v_or_b32_e32 v2, 12, v2
	v_or_b32_e32 v171, v8, v4
	v_bitop3_b32 v8, v3, v2, v165 bitop3:0x36
	v_bitop3_b32 v2, v6, v2, v3 bitop3:0x36
	v_lshl_add_u32 v2, v2, 4, v7
	v_or_b32_e32 v169, v2, v4
	v_mov_b64_e32 v[2:3], s[50:51]
	v_mad_i64_i32 v[2:3], s[70:71], v21, s74, v[2:3]
	v_lshlrev_b32_e32 v9, 4, v9
	v_lshlrev_b32_e32 v8, 4, v8
	v_or3_b32 v2, v2, s39, v0
	v_mov_b32_e32 v14, v1
	v_mov_b32_e32 v15, v1
	v_or3_b32 v168, v9, v5, v4
	v_or3_b32 v145, v8, v5, v4
	v_lshl_add_u64 v[134:135], s[48:49], 0, v[2:3]
	v_mov_b32_e32 v0, v1
	v_mov_b32_e32 v2, v1
	v_mov_b32_e32 v3, v1
	v_mov_b32_e32 v4, v1
	v_mov_b32_e32 v5, v1
	v_mov_b32_e32 v6, v1
	v_mov_b32_e32 v7, v1
	v_mov_b32_e32 v8, v1
	v_mov_b32_e32 v9, v1
	v_mov_b32_e32 v10, v1
	v_mov_b32_e32 v11, v1
	v_mov_b32_e32 v12, v1
	v_mov_b32_e32 v13, v1
	v_mov_b64_e32 v[64:65], v[14:15]
	v_mov_b64_e32 v[48:49], v[14:15]
	v_mov_b64_e32 v[32:33], v[14:15]
	v_mov_b64_e32 v[62:63], v[12:13]
	v_mov_b64_e32 v[60:61], v[10:11]
	v_mov_b64_e32 v[58:59], v[8:9]
	v_mov_b64_e32 v[56:57], v[6:7]
	v_mov_b64_e32 v[54:55], v[4:5]
	v_mov_b64_e32 v[52:53], v[2:3]
	v_mov_b64_e32 v[50:51], v[0:1]
	v_mov_b64_e32 v[46:47], v[12:13]
	v_mov_b64_e32 v[44:45], v[10:11]
	v_mov_b64_e32 v[42:43], v[8:9]
	v_mov_b64_e32 v[40:41], v[6:7]
	v_mov_b64_e32 v[38:39], v[4:5]
	v_mov_b64_e32 v[36:37], v[2:3]
	v_mov_b64_e32 v[34:35], v[0:1]
	v_mov_b64_e32 v[30:31], v[12:13]
	v_mov_b64_e32 v[28:29], v[10:11]
	v_mov_b64_e32 v[26:27], v[8:9]
	v_mov_b64_e32 v[24:25], v[6:7]
	v_mov_b64_e32 v[22:23], v[4:5]
	v_mov_b64_e32 v[20:21], v[2:3]
	v_mov_b64_e32 v[18:19], v[0:1]
	v_mov_b64_e32 v[16:17], v[14:15]
	s_mov_b32 s70, 0
	s_mov_b32 s71, 0
	v_mov_b64_e32 v[14:15], v[12:13]
	v_mov_b64_e32 v[12:13], v[10:11]
	v_mov_b64_e32 v[10:11], v[8:9]
	v_mov_b64_e32 v[8:9], v[6:7]
	v_mov_b64_e32 v[6:7], v[4:5]
	v_mov_b64_e32 v[4:5], v[2:3]
	v_mov_b64_e32 v[2:3], v[0:1]
	s_waitcnt vmcnt(0)
	v_lshrrev_b32_e32 v0, 4, v212
	v_and_b32_e32 v203, 3, v0
	v_lshlrev_b32_e32 v203, 2, v203
	v_bfe_u32 v0, v0, 2, 2
	v_or_b32_e32 v0, v203, v0
	v_lshlrev_b32_e32 v0, 4, v0
	v_xor_b32_e32 v134, v134, v0
	s_nop 0
	v_add_co_u32_e32 v200, vcc, 0x70000, v134
	s_nop 1
	v_addc_co_u32_e32 v201, vcc, 0, v135, vcc
	s_nop 0
	s_movk_i32 s73, 0x4000
	s_lshl_b32 s70, s42, 4
	s_and_b32 s70, s70, 0x1c00
	s_add_i32 s73, s73, s70
	s_add_i32 m0, s73, 0x0
	s_nop 0
	global_load_lds_dwordx4 v[134:135], off
	s_add_i32 m0, s73, 0x2000
	s_nop 0
	global_load_lds_dwordx4 v[200:201], off
	s_add_i32 m0, s73, 0x7800
	s_nop 0
	global_load_lds_dwordx4 v[134:135], off offset:2048
	s_add_i32 m0, s73, 0x9800
	s_nop 0
	global_load_lds_dwordx4 v[200:201], off offset:2048
	v_lshl_add_u64 v[134:135], v[134:135], 0, s[40:41]
	v_lshl_add_u64 v[200:201], v[200:201], 0, s[40:41]
	s_cmpk_lt_u32 s36, 0x80
	s_cbranch_scc1 .Lat1_pre_t2
	s_mov_b32 s73, 0x10000
	s_lshl_b32 s70, s42, 4
	s_and_b32 s70, s70, 0x1c00
	s_add_i32 s73, s73, s70
	s_add_i32 m0, s73, 0x0
	s_nop 0
	global_load_lds_dwordx4 v[134:135], off
	s_add_i32 m0, s73, 0x2000
	s_nop 0
	global_load_lds_dwordx4 v[200:201], off
	s_add_i32 m0, s73, 0x7800
	s_nop 0
	global_load_lds_dwordx4 v[134:135], off offset:2048
	s_add_i32 m0, s73, 0x9800
	s_nop 0
	global_load_lds_dwordx4 v[200:201], off offset:2048
	v_lshl_add_u64 v[134:135], v[134:135], 0, s[40:41]
	v_lshl_add_u64 v[200:201], v[200:201], 0, s[40:41]
	v_mov_b32_e32 v222, 0
	v_mov_b32_e32 v223, 0
	v_mov_b32_e32 v224, 0
	v_mov_b32_e32 v225, 0
	v_mov_b32_e32 v226, 0
	v_mov_b32_e32 v227, 0
	v_mov_b32_e32 v228, 0
	v_mov_b32_e32 v229, 0
	v_mov_b32_e32 v230, 0
	v_mov_b32_e32 v231, 0
	v_mov_b32_e32 v232, 0
	v_mov_b32_e32 v233, 0
	v_mov_b32_e32 v234, 0
	v_mov_b32_e32 v235, 0
	v_mov_b32_e32 v236, 0
	v_mov_b32_e32 v237, 0
	s_waitcnt vmcnt(6)
	s_branch .Lat1_pre_done

; #define LAS __attribute__((address_space(3)))
; __device__ __forceinline__ void attn_block(LAS unsigned char* lds, const bf16_t* P, bf16_t* mix, int b, int h, int qb, float lam, float outscale, const float* subln) {
;     ...
;     for (int kt = 0; kt < ntiles; ++kt) {
;         __syncthreads();
;         const int buf = kt & 1;
;         if (kt + 1 < ntiles) {
;             const size_t ro = (size_t)(64 * (kt + 1)) * INC;
;             kr0 = *(const u32x4*)(kg + ro + (size_t)srow * INC); kr1 = *(const u32x4*)(kg + ro + (size_t)(srow + 32) * INC);
;             vr0 = *(const u32x4*)(vg + ro + (size_t)srow * INC); vr1 = *(const u32x4*)(vg + ro + (size_t)(srow + 32) * INC);
;         }
;         const int kb = 64 * kt;
;         if (kb <= qw0 + 31) {
;             LAS const unsigned char* Kb = lds + ATT_K0 + buf * 16384;
;             LAS const unsigned char* Vb = lds + ATT_V0 + buf * 16384;
;             f32x16 s0, s1;
; #pragma unroll
;             for (int j = 0; j < 16; ++j) { s0[j] = 0.f; s1[j] = 0.f; }
;             bf16x8 ka[4][2];
; #pragma unroll
;             for (int ks = 0; ks < 4; ++ks) { ka[ks][0] = *(const LAS bf16x8*)(Kb + kbase[ks]); ka[ks][1] = *(const LAS bf16x8*)(Kb + kbase[ks] + 8192); }
;             __builtin_amdgcn_sched_barrier(0);
; #pragma unroll
;             for (int ks = 0; ks < 4; ++ks) {
;                 s0 = __builtin_amdgcn_mfma_f32_32x32x16_bf16(ka[ks][0], qf[ks], s0, 0, 0, 0);
;                 s1 = __builtin_amdgcn_mfma_f32_32x32x16_bf16(ka[ks][1], qf[ks], s1, 0, 0, 0);
;             }
;             if (kb + 63 > qw0) {
; #pragma unroll
;                 for (int j = 0; j < 16; ++j) { const int key = kb + crow(j, hi); if (key > qrow) s0[j] = -INFINITY; if (key + 32 > qrow) s1[j] = -INFINITY; }
;             }
;             float mxa = max3f(s0[0], s1[0], s0[1]), mxb = max3f(s1[1], s0[2], s1[2]), mxc = max3f(s0[3], s1[3], s0[4]), mxd = max3f(s1[4], s0[5], s1[5]);
;             mxa = max3f(mxa, s0[6], s1[6]); mxb = max3f(mxb, s0[7], s1[7]); mxc = max3f(mxc, s0[8], s1[8]); mxd = max3f(mxd, s0[9], s1[9]);
;             mxa = max3f(mxa, s0[10], s1[10]); mxb = max3f(mxb, s0[11], s1[11]); mxc = max3f(mxc, s0[12], s1[12]); mxd = max3f(mxd, s0[13], s1[13]);
;             mxa = max3f(mxa, s0[14], s1[14]); mxb = max3f(mxb, s0[15], s1[15]);
;             float mx = max3f(mxa, mxb, max3f(mxc, mxd, mxd));
.Lat1_pre_done:
	s_waitcnt lgkmcnt(0)
	s_barrier
	ds_read_b128 v[136:139], v180
	ds_read_b128 v[140:143], v180 offset:8192
	ds_read_b128 v[204:207], v181
	ds_read_b128 v[208:211], v181 offset:8192
	ds_read_b128 v[238:241], v178
	ds_read_b128 v[242:245], v178 offset:8192
	ds_read_b128 v[246:249], v177
	ds_read_b128 v[250:253], v177 offset:8192
	s_add_i32 s73, s71, 384
	s_cmp_le_u32 s73, s36
	s_cbranch_scc0 .Lat1_U_none
	v_add_u32_e32 v114, 0x10000, v173
	v_add_u32_e32 v115, 0x10000, v174
	v_add_u32_e32 v116, 0x10000, v170
	v_add_u32_e32 v117, 0x10000, v172
	v_add_u32_e32 v118, 0x10000, v168
	v_add_u32_e32 v119, 0x10000, v171
	v_add_u32_e32 v120, 0x10000, v145
	v_add_u32_e32 v121, 0x10000, v169
	v_add_u32_e32 v126, 0x10000, v180
	v_add_u32_e32 v127, 0x10000, v181
	v_add_u32_e32 v128, 0x10000, v178
	v_add_u32_e32 v129, 0x10000, v177
	s_lshl_b32 s70, s42, 4
	s_and_b32 s70, s70, 0x1c00
	s_mov_b32 s73, s70
.Lat1_U_top:
	s_add_i32 m0, s73, 0x14000
	s_nop 0
	global_load_lds_dwordx4 v[134:135], off
	s_add_i32 m0, s73, 0x16000
	s_nop 0
	global_load_lds_dwordx4 v[200:201], off
	s_waitcnt lgkmcnt(6)
	v_mfma_f32_32x32x16_bf16 v[82:97], v[136:139], v[110:113], v[222:237]
	v_mfma_f32_32x32x16_bf16 v[66:81], v[140:143], v[110:113], v[222:237]
	s_waitcnt lgkmcnt(4)
	v_mfma_f32_32x32x16_bf16 v[82:97], v[204:207], v[106:109], v[82:97]
	v_mfma_f32_32x32x16_bf16 v[66:81], v[208:211], v[106:109], v[66:81]
	s_waitcnt lgkmcnt(2)
	v_mfma_f32_32x32x16_bf16 v[82:97], v[238:241], v[102:105], v[82:97]
	v_mfma_f32_32x32x16_bf16 v[66:81], v[242:245], v[102:105], v[66:81]
	s_waitcnt lgkmcnt(0)
	v_mfma_f32_32x32x16_bf16 v[82:97], v[246:249], v[98:101], v[82:97]
	v_mfma_f32_32x32x16_bf16 v[66:81], v[250:253], v[98:101], v[66:81]
	ds_read_b64_tr_b16 v[136:137], v173 offset:32768
	ds_read_b64_tr_b16 v[138:139], v174 offset:32768
	ds_read_b64_tr_b16 v[140:141], v170 offset:32768
	ds_read_b64_tr_b16 v[142:143], v172 offset:32768
	ds_read_b64_tr_b16 v[204:205], v168 offset:32768
	ds_read_b64_tr_b16 v[206:207], v171 offset:32768
	ds_read_b64_tr_b16 v[208:209], v145 offset:32768
	ds_read_b64_tr_b16 v[210:211], v169 offset:32768
	ds_read_b64_tr_b16 v[238:239], v173 offset:36864
	ds_read_b64_tr_b16 v[240:241], v174 offset:36864
	ds_read_b64_tr_b16 v[242:243], v170 offset:36864
	ds_read_b64_tr_b16 v[244:245], v172 offset:36864
	v_max3_f32 v122, v82, v66, v83
	v_max3_f32 v123, v67, v84, v68
	v_max3_f32 v124, v85, v69, v86
	v_max3_f32 v125, v70, v87, v71
	v_max3_f32 v122, v122, v88, v72
	v_max3_f32 v123, v123, v89, v73
	v_max3_f32 v124, v124, v90, v74
	v_max3_f32 v125, v125, v91, v75
	v_max3_f32 v122, v122, v92, v76
	v_max3_f32 v123, v123, v93, v77
	v_max3_f32 v124, v124, v94, v78
	v_max3_f32 v125, v125, v95, v79
	v_max3_f32 v122, v122, v96, v80
	v_max3_f32 v123, v123, v97, v81
	v_max3_f32 v122, v122, v123, v124
	v_max_f32_e32 v122, v122, v125
	v_mov_b32_e32 v203, v122
	s_nop 1
	v_permlane32_swap_b32_e32 v122, v203
	s_nop 1
	v_max_f32_e32 v122, v122, v203
	s_mov_b32 s70, 0
	v_cmp_lt_f32_e32 vcc, 0x41000000, v122
	s_cmp_eq_u32 s71, 0
	s_cbranch_scc1 .Lat1_u0_first
	s_cbranch_vccz .Lat1_u0_norescale
	s_branch .Lat1_u0_rescale

; __device__ __forceinline__ unsigned pk2(float lo, float hi) { f32x2 v = {lo, hi}; bf16x2_t b = __builtin_convertvector(v, bf16x2_t); return __builtin_bit_cast(unsigned, b); }
; __device__ __forceinline__ s16x4 vtr(LAS const unsigned char* p) { return __builtin_bit_cast(s16x4, __builtin_amdgcn_ds_read_tr16_b64_v4i16((LAS v4i16_t*)p)); }
; __device__ __forceinline__ bf16x8 cat8(s16x4 a, s16x4 b) { return (bf16x8){a[0], a[1], a[2], a[3], b[0], b[1], b[2], b[3]}; }
; __device__ __forceinline__ void attn_block(LAS unsigned char* lds, const bf16_t* P, bf16_t* mix, int b, int h, int qb, float lam, float outscale, const float* subln) {
;     ...
;             if (__any(mx > mrun + 8.0f)) {
;                 const float mnew = fmaxf(mrun, mx); const float alpha = __builtin_amdgcn_exp2f(mrun - mnew); mrun = mnew; lrun *= alpha;
; #pragma unroll
;                 for (int c = 0; c < 4; ++c)
; #pragma unroll
;                     for (int j = 0; j < 16; ++j) o[c][j] *= alpha;
;             }
; #pragma unroll
;             for (int j = 0; j < 16; ++j) { s0[j] = __builtin_amdgcn_exp2f(s0[j] - mrun); s1[j] = __builtin_amdgcn_exp2f(s1[j] - mrun); }
;             float ps0 = 0.f, ps1 = 0.f, ps2 = 0.f, ps3 = 0.f;
; #pragma unroll
;             for (int j = 0; j < 16; j += 2) { ps0 += s0[j]; ps1 += s1[j]; ps2 += s0[j + 1]; ps3 += s1[j + 1]; }
;             lrun += (ps0 + ps1) + (ps2 + ps3);
;             bf16x8 pb[4];
; #pragma unroll
;             for (int s2 = 0; s2 < 2; ++s2) {
;                 u32x4 w0, w1;
;                 w0.x = pk2(s0[8 * s2 + 0], s0[8 * s2 + 1]); w0.y = pk2(s0[8 * s2 + 2], s0[8 * s2 + 3]); w0.z = pk2(s0[8 * s2 + 4], s0[8 * s2 + 5]); w0.w = pk2(s0[8 * s2 + 6], s0[8 * s2 + 7]);
;                 w1.x = pk2(s1[8 * s2 + 0], s1[8 * s2 + 1]); w1.y = pk2(s1[8 * s2 + 2], s1[8 * s2 + 3]); w1.z = pk2(s1[8 * s2 + 4], s1[8 * s2 + 5]); w1.w = pk2(s1[8 * s2 + 6], s1[8 * s2 + 7]);
;                 pb[s2] = __builtin_bit_cast(bf16x8, w0); pb[2 + s2] = __builtin_bit_cast(bf16x8, w1);
;             }
; #pragma unroll
;             for (int s = 0; s < 4; ++s) {
; #pragma unroll
;                 for (int c = 0; c < 4; ++c) {
;                     const s16x4 v0 = vtr(Vb + vbase[c][0] + 4096 * s);
;                     const s16x4 v1 = vtr(Vb + vbase[c][1] + 4096 * s);
;                     o[c] = __builtin_amdgcn_mfma_f32_32x32x16_bf16(cat8(v0, v1), pb[s], o[c], 0, 0, 0);
.Lat1_u0_rescale:
	v_max_f32_e32 v0, s70, v122
	v_sub_f32_e32 v203, 0, v0
	v_min_f32_e32 v203, 0x42fc0000, v203
	v_exp_f32_e32 v203, v203
	v_sub_f32_e32 v82, v82, v0
	v_sub_f32_e32 v83, v83, v0
	v_sub_f32_e32 v84, v84, v0
	v_sub_f32_e32 v85, v85, v0
	v_sub_f32_e32 v86, v86, v0
	v_sub_f32_e32 v87, v87, v0
	v_sub_f32_e32 v88, v88, v0
	v_sub_f32_e32 v89, v89, v0
	v_sub_f32_e32 v90, v90, v0
	v_sub_f32_e32 v91, v91, v0
	v_sub_f32_e32 v92, v92, v0
	v_sub_f32_e32 v93, v93, v0
	v_sub_f32_e32 v94, v94, v0
	v_sub_f32_e32 v95, v95, v0
	v_sub_f32_e32 v96, v96, v0
	v_sub_f32_e32 v97, v97, v0
	v_sub_f32_e32 v66, v66, v0
	v_sub_f32_e32 v67, v67, v0
	v_sub_f32_e32 v68, v68, v0
	v_sub_f32_e32 v69, v69, v0
	v_sub_f32_e32 v70, v70, v0
	v_sub_f32_e32 v71, v71, v0
	v_sub_f32_e32 v72, v72, v0
	v_sub_f32_e32 v73, v73, v0
	v_sub_f32_e32 v74, v74, v0
	v_sub_f32_e32 v75, v75, v0
	v_sub_f32_e32 v76, v76, v0
	v_sub_f32_e32 v77, v77, v0
	v_sub_f32_e32 v78, v78, v0
	v_sub_f32_e32 v79, v79, v0
	v_sub_f32_e32 v80, v80, v0
	v_sub_f32_e32 v81, v81, v0
	v_sub_f32_e32 v222, v222, v0
	v_mov_b32_e32 v223, v222
	v_mov_b32_e32 v224, v222
	v_mov_b32_e32 v225, v222
	v_mov_b32_e32 v226, v222
	v_mov_b32_e32 v227, v222
	v_mov_b32_e32 v228, v222
	v_mov_b32_e32 v229, v222
	v_mov_b32_e32 v230, v222
	v_mov_b32_e32 v231, v222
	v_mov_b32_e32 v232, v222
	v_mov_b32_e32 v233, v222
	v_mov_b32_e32 v234, v222
	v_mov_b32_e32 v235, v222
	v_mov_b32_e32 v236, v222
	v_mov_b32_e32 v237, v222
	v_mul_f32_e32 v50, v50, v203
	v_mul_f32_e32 v51, v51, v203
	v_mul_f32_e32 v52, v52, v203
	v_mul_f32_e32 v53, v53, v203
	v_mul_f32_e32 v54, v54, v203
	v_mul_f32_e32 v55, v55, v203
	v_mul_f32_e32 v56, v56, v203
	v_mul_f32_e32 v57, v57, v203
	v_mul_f32_e32 v58, v58, v203
	v_mul_f32_e32 v59, v59, v203
	v_mul_f32_e32 v60, v60, v203
	v_mul_f32_e32 v61, v61, v203
	v_mul_f32_e32 v62, v62, v203
	v_mul_f32_e32 v63, v63, v203
	v_mul_f32_e32 v64, v64, v203
	v_mul_f32_e32 v65, v65, v203
	v_mul_f32_e32 v34, v34, v203
	v_mul_f32_e32 v35, v35, v203
	v_mul_f32_e32 v36, v36, v203
	v_mul_f32_e32 v37, v37, v203
	v_mul_f32_e32 v38, v38, v203
	v_mul_f32_e32 v39, v39, v203
	v_mul_f32_e32 v40, v40, v203
	v_mul_f32_e32 v41, v41, v203
	v_mul_f32_e32 v42, v42, v203
	v_mul_f32_e32 v43, v43, v203
	v_mul_f32_e32 v44, v44, v203
	v_mul_f32_e32 v45, v45, v203
	v_mul_f32_e32 v46, v46, v203
	v_mul_f32_e32 v47, v47, v203
	v_mul_f32_e32 v48, v48, v203
	v_mul_f32_e32 v49, v49, v203
	v_mul_f32_e32 v18, v18, v203
	v_mul_f32_e32 v19, v19, v203
	v_mul_f32_e32 v20, v20, v203
	v_mul_f32_e32 v21, v21, v203
	v_mul_f32_e32 v22, v22, v203
	v_mul_f32_e32 v23, v23, v203
	v_mul_f32_e32 v24, v24, v203
	v_mul_f32_e32 v25, v25, v203
	v_mul_f32_e32 v26, v26, v203
	v_mul_f32_e32 v27, v27, v203
	v_mul_f32_e32 v28, v28, v203
	v_mul_f32_e32 v29, v29, v203
	v_mul_f32_e32 v30, v30, v203
	v_mul_f32_e32 v31, v31, v203
	v_mul_f32_e32 v32, v32, v203
	v_mul_f32_e32 v33, v33, v203
	v_mul_f32_e32 v2, v2, v203
	v_mul_f32_e32 v3, v3, v203
	v_mul_f32_e32 v4, v4, v203
	v_mul_f32_e32 v5, v5, v203
	v_mul_f32_e32 v6, v6, v203
	v_mul_f32_e32 v7, v7, v203
	v_mul_f32_e32 v8, v8, v203
	v_mul_f32_e32 v9, v9, v203
	v_mul_f32_e32 v10, v10, v203
	v_mul_f32_e32 v11, v11, v203
	v_mul_f32_e32 v12, v12, v203
	v_mul_f32_e32 v13, v13, v203
	v_mul_f32_e32 v14, v14, v203
	v_mul_f32_e32 v15, v15, v203
	v_mul_f32_e32 v16, v16, v203
	v_mul_f32_e32 v17, v17, v203
	v_mul_f32_e32 v167, v167, v203
.Lat1_u0_norescale:
	v_exp_f32_e32 v82, v82
	v_exp_f32_e32 v83, v83
	v_exp_f32_e32 v84, v84
	v_exp_f32_e32 v85, v85
	v_exp_f32_e32 v86, v86
	v_exp_f32_e32 v87, v87
	v_exp_f32_e32 v88, v88
	v_exp_f32_e32 v89, v89
	v_exp_f32_e32 v90, v90
	v_exp_f32_e32 v91, v91
	v_exp_f32_e32 v92, v92
	v_exp_f32_e32 v93, v93
	v_exp_f32_e32 v94, v94
	v_exp_f32_e32 v95, v95
	v_exp_f32_e32 v96, v96
	v_exp_f32_e32 v97, v97
	v_cvt_pk_bf16_f32 v184, v82, v83
	v_cvt_pk_bf16_f32 v185, v84, v85
	v_cvt_pk_bf16_f32 v186, v86, v87
	v_cvt_pk_bf16_f32 v187, v88, v89
	v_cvt_pk_bf16_f32 v188, v90, v91
	v_cvt_pk_bf16_f32 v189, v92, v93
	v_cvt_pk_bf16_f32 v190, v94, v95
	v_cvt_pk_bf16_f32 v191, v96, v97
	v_add_f32_e32 v122, v82, v83
	v_add_f32_e32 v123, v84, v85
	v_add_f32_e32 v122, v122, v86
	v_add_f32_e32 v123, v123, v87
	v_add_f32_e32 v122, v122, v88
	v_add_f32_e32 v123, v123, v89
	v_add_f32_e32 v122, v122, v123
	v_add_f32_e32 v167, v167, v122
	v_add_f32_e32 v124, v90, v91
	v_add_f32_e32 v125, v92, v93
	v_add_f32_e32 v124, v124, v94
	v_add_f32_e32 v125, v125, v95
	v_add_f32_e32 v124, v124, v96
	v_add_f32_e32 v125, v125, v97
	v_add_f32_e32 v124, v124, v125
	v_add_f32_e32 v167, v167, v124
	s_add_i32 m0, s73, 0x1b800
	s_nop 0
	global_load_lds_dwordx4 v[134:135], off offset:2048
	s_add_i32 m0, s73, 0x1d800
	s_nop 0
	global_load_lds_dwordx4 v[200:201], off offset:2048
	v_lshl_add_u64 v[134:135], v[134:135], 0, s[40:41]
	v_lshl_add_u64 v[200:201], v[200:201], 0, s[40:41]
	s_waitcnt lgkmcnt(8)
	v_mfma_f32_32x32x16_bf16 v[50:65], v[136:139], v[184:187], v[50:65]
	ds_read_b64_tr_b16 v[246:247], v168 offset:36864
	ds_read_b64_tr_b16 v[248:249], v171 offset:36864
	v_exp_f32_e32 v66, v66
	v_exp_f32_e32 v67, v67
	v_exp_f32_e32 v68, v68
	v_mfma_f32_32x32x16_bf16 v[34:49], v[140:143], v[184:187], v[34:49]
	ds_read_b64_tr_b16 v[250:251], v145 offset:36864
	ds_read_b64_tr_b16 v[252:253], v169 offset:36864
	v_exp_f32_e32 v69, v69
	v_exp_f32_e32 v70, v70
	v_exp_f32_e32 v71, v71
	s_waitcnt lgkmcnt(8)
; #define LAS __attribute__((address_space(3)))
; __device__ __forceinline__ void attn_block(LAS unsigned char* lds, const bf16_t* P, bf16_t* mix, int b, int h, int qb, float lam, float outscale, const float* subln) {
;     ...
;         if (kt + 1 < ntiles) {
;             const size_t ro = (size_t)(64 * (kt + 1)) * INC;
;             kr0 = *(const u32x4*)(kg + ro + (size_t)srow * INC); kr1 = *(const u32x4*)(kg + ro + (size_t)(srow + 32) * INC);
;             vr0 = *(const u32x4*)(vg + ro + (size_t)srow * INC); vr1 = *(const u32x4*)(vg + ro + (size_t)(srow + 32) * INC);
;         }
;         const int kb = 64 * kt;
;         if (kb <= qw0 + 31) {
;             LAS const unsigned char* Kb = lds + ATT_K0 + buf * 16384;
;             LAS const unsigned char* Vb = lds + ATT_V0 + buf * 16384;
;             f32x16 s0, s1;
; #pragma unroll
;             for (int j = 0; j < 16; ++j) { s0[j] = 0.f; s1[j] = 0.f; }
;             bf16x8 ka[4][2];
; #pragma unroll
;             for (int ks = 0; ks < 4; ++ks) { ka[ks][0] = *(const LAS bf16x8*)(Kb + kbase[ks]); ka[ks][1] = *(const LAS bf16x8*)(Kb + kbase[ks] + 8192); }
;             __builtin_amdgcn_sched_barrier(0);
; #pragma unroll
;             for (int ks = 0; ks < 4; ++ks) {
;                 s0 = __builtin_amdgcn_mfma_f32_32x32x16_bf16(ka[ks][0], qf[ks], s0, 0, 0, 0);
;                 s1 = __builtin_amdgcn_mfma_f32_32x32x16_bf16(ka[ks][1], qf[ks], s1, 0, 0, 0);
;             }
;             if (kb + 63 > qw0) {
; #pragma unroll
;                 for (int j = 0; j < 16; ++j) { const int key = kb + crow(j, hi); if (key > qrow) s0[j] = -INFINITY; if (key + 32 > qrow) s1[j] = -INFINITY; }
;             }
;             float mxa = max3f(s0[0], s1[0], s0[1]), mxb = max3f(s1[1], s0[2], s1[2]), mxc = max3f(s0[3], s1[3], s0[4]), mxd = max3f(s1[4], s0[5], s1[5]);
;             mxa = max3f(mxa, s0[6], s1[6]); mxb = max3f(mxb, s0[7], s1[7]); mxc = max3f(mxc, s0[8], s1[8]); mxd = max3f(mxd, s0[9], s1[9]);
;     ...
;             for (int s = 0; s < 4; ++s) {
; #pragma unroll
;                 for (int c = 0; c < 4; ++c) {
;                     const s16x4 v0 = vtr(Vb + vbase[c][0] + 4096 * s);
;                     const s16x4 v1 = vtr(Vb + vbase[c][1] + 4096 * s);
;                     o[c] = __builtin_amdgcn_mfma_f32_32x32x16_bf16(cat8(v0, v1), pb[s], o[c], 0, 0, 0);
;                 }
;             }
	v_mfma_f32_32x32x16_bf16 v[18:33], v[204:207], v[184:187], v[18:33]
	ds_read_b64_tr_b16 v[136:137], v173 offset:40960
	ds_read_b64_tr_b16 v[138:139], v174 offset:40960
	v_exp_f32_e32 v72, v72
	v_exp_f32_e32 v73, v73
	v_cvt_pk_bf16_f32 v192, v66, v67
	v_mfma_f32_32x32x16_bf16 v[2:17], v[208:211], v[184:187], v[2:17]
	ds_read_b64_tr_b16 v[140:141], v170 offset:40960
	ds_read_b64_tr_b16 v[142:143], v172 offset:40960
	v_cvt_pk_bf16_f32 v193, v68, v69
	v_cvt_pk_bf16_f32 v194, v70, v71
	v_cvt_pk_bf16_f32 v195, v72, v73
	s_waitcnt lgkmcnt(8)
	v_mfma_f32_32x32x16_bf16 v[50:65], v[238:241], v[188:191], v[50:65]
	ds_read_b64_tr_b16 v[204:205], v168 offset:40960
	ds_read_b64_tr_b16 v[206:207], v171 offset:40960
	v_exp_f32_e32 v74, v74
	v_exp_f32_e32 v75, v75
	v_exp_f32_e32 v76, v76
	v_mfma_f32_32x32x16_bf16 v[34:49], v[242:245], v[188:191], v[34:49]
	ds_read_b64_tr_b16 v[208:209], v145 offset:40960
	ds_read_b64_tr_b16 v[210:211], v169 offset:40960
	v_exp_f32_e32 v77, v77
	v_exp_f32_e32 v78, v78
	v_exp_f32_e32 v79, v79
	s_waitcnt lgkmcnt(8)
	v_mfma_f32_32x32x16_bf16 v[18:33], v[246:249], v[188:191], v[18:33]
	ds_read_b64_tr_b16 v[238:239], v173 offset:45056
	ds_read_b64_tr_b16 v[240:241], v174 offset:45056
	v_exp_f32_e32 v80, v80
	v_exp_f32_e32 v81, v81
	v_cvt_pk_bf16_f32 v196, v74, v75
	v_mfma_f32_32x32x16_bf16 v[2:17], v[250:253], v[188:191], v[2:17]
	ds_read_b64_tr_b16 v[242:243], v170 offset:45056
	ds_read_b64_tr_b16 v[244:245], v172 offset:45056
	v_cvt_pk_bf16_f32 v197, v76, v77
	v_cvt_pk_bf16_f32 v198, v78, v79
	v_cvt_pk_bf16_f32 v199, v80, v81
	s_waitcnt lgkmcnt(8)
	v_mfma_f32_32x32x16_bf16 v[50:65], v[136:139], v[192:195], v[50:65]
	ds_read_b64_tr_b16 v[246:247], v168 offset:45056
	ds_read_b64_tr_b16 v[248:249], v171 offset:45056
	v_add_f32_e32 v0, v66, v67
	v_add_f32_e32 v203, v68, v69
	v_add_f32_e32 v0, v0, v70
	v_mfma_f32_32x32x16_bf16 v[34:49], v[140:143], v[192:195], v[34:49]
	ds_read_b64_tr_b16 v[250:251], v145 offset:45056
	ds_read_b64_tr_b16 v[252:253], v169 offset:45056
	v_add_f32_e32 v203, v203, v71
	v_add_f32_e32 v0, v0, v72
	v_add_f32_e32 v203, v203, v73
	s_waitcnt lgkmcnt(8)
	v_mfma_f32_32x32x16_bf16 v[18:33], v[204:207], v[192:195], v[18:33]
	v_add_f32_e32 v0, v0, v203
	v_add_f32_e32 v167, v167, v0
	v_add_f32_e32 v0, v74, v75
	v_mfma_f32_32x32x16_bf16 v[2:17], v[208:211], v[192:195], v[2:17]
	v_add_f32_e32 v203, v76, v77
	v_add_f32_e32 v0, v0, v78
	v_add_f32_e32 v203, v203, v79
	s_waitcnt lgkmcnt(4)
	v_mfma_f32_32x32x16_bf16 v[50:65], v[238:241], v[196:199], v[50:65]
	v_add_f32_e32 v0, v0, v80
	v_add_f32_e32 v203, v203, v81
	v_add_f32_e32 v0, v0, v203
	v_mfma_f32_32x32x16_bf16 v[34:49], v[242:245], v[196:199], v[34:49]
	v_add_f32_e32 v167, v167, v0
	s_waitcnt lgkmcnt(0)
	v_mfma_f32_32x32x16_bf16 v[18:33], v[246:249], v[196:199], v[18:33]
	v_mfma_f32_32x32x16_bf16 v[2:17], v[250:253], v[196:199], v[2:17]
	ds_read_b128 v[136:139], v180 offset:16384
	ds_read_b128 v[140:143], v180 offset:24576
	ds_read_b128 v[204:207], v181 offset:16384
	ds_read_b128 v[208:211], v181 offset:24576
	ds_read_b128 v[238:241], v178 offset:16384
	ds_read_b128 v[242:245], v178 offset:24576
	ds_read_b128 v[246:249], v177 offset:16384
	ds_read_b128 v[250:253], v177 offset:24576
	s_waitcnt vmcnt(6)
	s_add_i32 s71, s71, 64
	s_barrier
	s_add_i32 m0, s73, 0x0
	s_nop 0
	global_load_lds_dwordx4 v[134:135], off
	s_add_i32 m0, s73, 0x2000
	s_nop 0
	global_load_lds_dwordx4 v[200:201], off
	s_waitcnt lgkmcnt(6)
	v_mfma_f32_32x32x16_bf16 v[82:97], v[136:139], v[110:113], v[222:237]
	v_mfma_f32_32x32x16_bf16 v[66:81], v[140:143], v[110:113], v[222:237]
	s_waitcnt lgkmcnt(4)
	v_mfma_f32_32x32x16_bf16 v[82:97], v[204:207], v[106:109], v[82:97]
	v_mfma_f32_32x32x16_bf16 v[66:81], v[208:211], v[106:109], v[66:81]
	s_waitcnt lgkmcnt(2)
	v_mfma_f32_32x32x16_bf16 v[82:97], v[238:241], v[102:105], v[82:97]
	v_mfma_f32_32x32x16_bf16 v[66:81], v[242:245], v[102:105], v[66:81]
	s_waitcnt lgkmcnt(0)
	v_mfma_f32_32x32x16_bf16 v[82:97], v[246:249], v[98:101], v[82:97]
	v_mfma_f32_32x32x16_bf16 v[66:81], v[250:253], v[98:101], v[66:81]
	ds_read_b64_tr_b16 v[136:137], v173 offset:49152
	ds_read_b64_tr_b16 v[138:139], v174 offset:49152
	ds_read_b64_tr_b16 v[140:141], v170 offset:49152
	ds_read_b64_tr_b16 v[142:143], v172 offset:49152
	ds_read_b64_tr_b16 v[204:205], v168 offset:49152
	ds_read_b64_tr_b16 v[206:207], v171 offset:49152
	ds_read_b64_tr_b16 v[208:209], v145 offset:49152
	ds_read_b64_tr_b16 v[210:211], v169 offset:49152
	ds_read_b64_tr_b16 v[238:239], v173 offset:53248
	ds_read_b64_tr_b16 v[240:241], v174 offset:53248
	ds_read_b64_tr_b16 v[242:243], v170 offset:53248
	ds_read_b64_tr_b16 v[244:245], v172 offset:53248
	v_max3_f32 v122, v82, v66, v83
	v_max3_f32 v123, v67, v84, v68
	v_max3_f32 v124, v85, v69, v86
	v_max3_f32 v125, v70, v87, v71
	v_max3_f32 v122, v122, v88, v72
	v_max3_f32 v123, v123, v89, v73
	v_max3_f32 v124, v124, v90, v74
	v_max3_f32 v125, v125, v91, v75
	v_max3_f32 v122, v122, v92, v76
	v_max3_f32 v123, v123, v93, v77
	v_max3_f32 v124, v124, v94, v78
	v_max3_f32 v125, v125, v95, v79
	v_max3_f32 v122, v122, v96, v80
	v_max3_f32 v123, v123, v97, v81
	v_max3_f32 v122, v122, v123, v124
	v_max_f32_e32 v122, v122, v125
	v_mov_b32_e32 v203, v122
	s_nop 1
	v_permlane32_swap_b32_e32 v122, v203
	s_nop 1
	v_max_f32_e32 v122, v122, v203
	s_mov_b32 s70, 0
	v_cmp_lt_f32_e32 vcc, 0x41000000, v122
	s_cmp_eq_u32 s71, 0
	s_cbranch_scc1 .Lat1_u1_first
	s_cbranch_vccz .Lat1_u1_norescale
	s_branch .Lat1_u1_rescale

; __device__ __forceinline__ unsigned pk2(float lo, float hi) { f32x2 v = {lo, hi}; bf16x2_t b = __builtin_convertvector(v, bf16x2_t); return __builtin_bit_cast(unsigned, b); }
; __device__ __forceinline__ s16x4 vtr(LAS const unsigned char* p) { return __builtin_bit_cast(s16x4, __builtin_amdgcn_ds_read_tr16_b64_v4i16((LAS v4i16_t*)p)); }
; __device__ __forceinline__ bf16x8 cat8(s16x4 a, s16x4 b) { return (bf16x8){a[0], a[1], a[2], a[3], b[0], b[1], b[2], b[3]}; }
; __device__ __forceinline__ void attn_block(LAS unsigned char* lds, const bf16_t* P, bf16_t* mix, int b, int h, int qb, float lam, float outscale, const float* subln) {
;     ...
;             for (int j = 0; j < 16; ++j) { s0[j] = __builtin_amdgcn_exp2f(s0[j] - mrun); s1[j] = __builtin_amdgcn_exp2f(s1[j] - mrun); }
;             float ps0 = 0.f, ps1 = 0.f, ps2 = 0.f, ps3 = 0.f;
; #pragma unroll
;             for (int j = 0; j < 16; j += 2) { ps0 += s0[j]; ps1 += s1[j]; ps2 += s0[j + 1]; ps3 += s1[j + 1]; }
;             lrun += (ps0 + ps1) + (ps2 + ps3);
;             bf16x8 pb[4];
; #pragma unroll
;             for (int s2 = 0; s2 < 2; ++s2) {
;                 u32x4 w0, w1;
;                 w0.x = pk2(s0[8 * s2 + 0], s0[8 * s2 + 1]); w0.y = pk2(s0[8 * s2 + 2], s0[8 * s2 + 3]); w0.z = pk2(s0[8 * s2 + 4], s0[8 * s2 + 5]); w0.w = pk2(s0[8 * s2 + 6], s0[8 * s2 + 7]);
;                 w1.x = pk2(s1[8 * s2 + 0], s1[8 * s2 + 1]); w1.y = pk2(s1[8 * s2 + 2], s1[8 * s2 + 3]); w1.z = pk2(s1[8 * s2 + 4], s1[8 * s2 + 5]); w1.w = pk2(s1[8 * s2 + 6], s1[8 * s2 + 7]);
;                 pb[s2] = __builtin_bit_cast(bf16x8, w0); pb[2 + s2] = __builtin_bit_cast(bf16x8, w1);
;             }
; #pragma unroll
;             for (int s = 0; s < 4; ++s) {
; #pragma unroll
;                 for (int c = 0; c < 4; ++c) {
;                     const s16x4 v0 = vtr(Vb + vbase[c][0] + 4096 * s);
;                     const s16x4 v1 = vtr(Vb + vbase[c][1] + 4096 * s);
;                     o[c] = __builtin_amdgcn_mfma_f32_32x32x16_bf16(cat8(v0, v1), pb[s], o[c], 0, 0, 0);
;                 }
;             }
.Lat1_u1_norescale:
	v_exp_f32_e32 v82, v82
	v_exp_f32_e32 v83, v83
	v_exp_f32_e32 v84, v84
	v_exp_f32_e32 v85, v85
	v_exp_f32_e32 v86, v86
	v_exp_f32_e32 v87, v87
	v_exp_f32_e32 v88, v88
	v_exp_f32_e32 v89, v89
	v_exp_f32_e32 v90, v90
	v_exp_f32_e32 v91, v91
	v_exp_f32_e32 v92, v92
	v_exp_f32_e32 v93, v93
	v_exp_f32_e32 v94, v94
	v_exp_f32_e32 v95, v95
	v_exp_f32_e32 v96, v96
	v_exp_f32_e32 v97, v97
	v_cvt_pk_bf16_f32 v184, v82, v83
	v_cvt_pk_bf16_f32 v185, v84, v85
	v_cvt_pk_bf16_f32 v186, v86, v87
	v_cvt_pk_bf16_f32 v187, v88, v89
	v_cvt_pk_bf16_f32 v188, v90, v91
	v_cvt_pk_bf16_f32 v189, v92, v93
	v_cvt_pk_bf16_f32 v190, v94, v95
	v_cvt_pk_bf16_f32 v191, v96, v97
	v_add_f32_e32 v122, v82, v83
	v_add_f32_e32 v123, v84, v85
	v_add_f32_e32 v122, v122, v86
	v_add_f32_e32 v123, v123, v87
	v_add_f32_e32 v122, v122, v88
	v_add_f32_e32 v123, v123, v89
	v_add_f32_e32 v122, v122, v123
	v_add_f32_e32 v167, v167, v122
	v_add_f32_e32 v124, v90, v91
	v_add_f32_e32 v125, v92, v93
	v_add_f32_e32 v124, v124, v94
	v_add_f32_e32 v125, v125, v95
	v_add_f32_e32 v124, v124, v96
	v_add_f32_e32 v125, v125, v97
	v_add_f32_e32 v124, v124, v125
	v_add_f32_e32 v167, v167, v124
	s_add_i32 m0, s73, 0x7800
	s_nop 0
	global_load_lds_dwordx4 v[134:135], off offset:2048
	s_add_i32 m0, s73, 0x9800
	s_nop 0
	global_load_lds_dwordx4 v[200:201], off offset:2048
	v_lshl_add_u64 v[134:135], v[134:135], 0, s[40:41]
	v_lshl_add_u64 v[200:201], v[200:201], 0, s[40:41]
	s_waitcnt lgkmcnt(8)
	v_mfma_f32_32x32x16_bf16 v[50:65], v[136:139], v[184:187], v[50:65]
	ds_read_b64_tr_b16 v[246:247], v168 offset:53248
	ds_read_b64_tr_b16 v[248:249], v171 offset:53248
	v_exp_f32_e32 v66, v66
	v_exp_f32_e32 v67, v67
	v_exp_f32_e32 v68, v68
	v_mfma_f32_32x32x16_bf16 v[34:49], v[140:143], v[184:187], v[34:49]
	ds_read_b64_tr_b16 v[250:251], v145 offset:53248
	ds_read_b64_tr_b16 v[252:253], v169 offset:53248
	v_exp_f32_e32 v69, v69
	v_exp_f32_e32 v70, v70
	v_exp_f32_e32 v71, v71
	s_waitcnt lgkmcnt(8)
	v_mfma_f32_32x32x16_bf16 v[18:33], v[204:207], v[184:187], v[18:33]
	ds_read_b64_tr_b16 v[136:137], v173 offset:57344
	ds_read_b64_tr_b16 v[138:139], v174 offset:57344
	v_exp_f32_e32 v72, v72
	v_exp_f32_e32 v73, v73
	v_cvt_pk_bf16_f32 v192, v66, v67
	v_mfma_f32_32x32x16_bf16 v[2:17], v[208:211], v[184:187], v[2:17]
	ds_read_b64_tr_b16 v[140:141], v170 offset:57344
	ds_read_b64_tr_b16 v[142:143], v172 offset:57344
	v_cvt_pk_bf16_f32 v193, v68, v69
	v_cvt_pk_bf16_f32 v194, v70, v71
	v_cvt_pk_bf16_f32 v195, v72, v73
	s_waitcnt lgkmcnt(8)
	v_mfma_f32_32x32x16_bf16 v[50:65], v[238:241], v[188:191], v[50:65]
	ds_read_b64_tr_b16 v[204:205], v168 offset:57344
	ds_read_b64_tr_b16 v[206:207], v171 offset:57344
	v_exp_f32_e32 v74, v74
	v_exp_f32_e32 v75, v75
	v_exp_f32_e32 v76, v76
	v_mfma_f32_32x32x16_bf16 v[34:49], v[242:245], v[188:191], v[34:49]
	ds_read_b64_tr_b16 v[208:209], v145 offset:57344
	ds_read_b64_tr_b16 v[210:211], v169 offset:57344
	v_exp_f32_e32 v77, v77
	v_exp_f32_e32 v78, v78
	v_exp_f32_e32 v79, v79
	s_waitcnt lgkmcnt(8)
	v_mfma_f32_32x32x16_bf16 v[18:33], v[246:249], v[188:191], v[18:33]
	ds_read_b64_tr_b16 v[238:239], v173 offset:61440
	ds_read_b64_tr_b16 v[240:241], v174 offset:61440
	v_exp_f32_e32 v80, v80
	v_exp_f32_e32 v81, v81
	v_cvt_pk_bf16_f32 v196, v74, v75
	v_mfma_f32_32x32x16_bf16 v[2:17], v[250:253], v[188:191], v[2:17]
	ds_read_b64_tr_b16 v[242:243], v170 offset:61440
	ds_read_b64_tr_b16 v[244:245], v172 offset:61440
	v_cvt_pk_bf16_f32 v197, v76, v77
	v_cvt_pk_bf16_f32 v198, v78, v79
	v_cvt_pk_bf16_f32 v199, v80, v81
	s_waitcnt lgkmcnt(8)
	v_mfma_f32_32x32x16_bf16 v[50:65], v[136:139], v[192:195], v[50:65]
	ds_read_b64_tr_b16 v[246:247], v168 offset:61440
	ds_read_b64_tr_b16 v[248:249], v171 offset:61440
	v_add_f32_e32 v0, v66, v67
	v_add_f32_e32 v203, v68, v69
	v_add_f32_e32 v0, v0, v70
	v_mfma_f32_32x32x16_bf16 v[34:49], v[140:143], v[192:195], v[34:49]
	ds_read_b64_tr_b16 v[250:251], v145 offset:61440
	ds_read_b64_tr_b16 v[252:253], v169 offset:61440
	v_add_f32_e32 v203, v203, v71
	v_add_f32_e32 v0, v0, v72
	v_add_f32_e32 v203, v203, v73
	s_waitcnt lgkmcnt(8)
	v_mfma_f32_32x32x16_bf16 v[18:33], v[204:207], v[192:195], v[18:33]
	v_add_f32_e32 v0, v0, v203
	v_add_f32_e32 v167, v167, v0
	v_add_f32_e32 v0, v74, v75
	v_mfma_f32_32x32x16_bf16 v[2:17], v[208:211], v[192:195], v[2:17]
	v_add_f32_e32 v203, v76, v77
	v_add_f32_e32 v0, v0, v78
	v_add_f32_e32 v203, v203, v79
	s_waitcnt lgkmcnt(4)
	v_mfma_f32_32x32x16_bf16 v[50:65], v[238:241], v[196:199], v[50:65]
	v_add_f32_e32 v0, v0, v80
	v_add_f32_e32 v203, v203, v81
	v_add_f32_e32 v0, v0, v203
	v_mfma_f32_32x32x16_bf16 v[34:49], v[242:245], v[196:199], v[34:49]
	v_add_f32_e32 v167, v167, v0
	s_waitcnt lgkmcnt(0)
	v_mfma_f32_32x32x16_bf16 v[18:33], v[246:249], v[196:199], v[18:33]
	v_mfma_f32_32x32x16_bf16 v[2:17], v[250:253], v[196:199], v[2:17]
	ds_read_b128 v[136:139], v126 offset:0
	ds_read_b128 v[140:143], v126 offset:8192
	ds_read_b128 v[204:207], v127 offset:0
	ds_read_b128 v[208:211], v127 offset:8192
	ds_read_b128 v[238:241], v128 offset:0
	ds_read_b128 v[242:245], v128 offset:8192
	ds_read_b128 v[246:249], v129 offset:0
	ds_read_b128 v[250:253], v129 offset:8192
	s_waitcnt vmcnt(6)
	s_add_i32 s71, s71, 64
	s_barrier
; #define LAS __attribute__((address_space(3)))
; __device__ __forceinline__ void attn_block(LAS unsigned char* lds, const bf16_t* P, bf16_t* mix, int b, int h, int qb, float lam, float outscale, const float* subln) {
;     ...
;         if (kt + 1 < ntiles) {
;             const size_t ro = (size_t)(64 * (kt + 1)) * INC;
;             kr0 = *(const u32x4*)(kg + ro + (size_t)srow * INC); kr1 = *(const u32x4*)(kg + ro + (size_t)(srow + 32) * INC);
;             vr0 = *(const u32x4*)(vg + ro + (size_t)srow * INC); vr1 = *(const u32x4*)(vg + ro + (size_t)(srow + 32) * INC);
;         }
;         const int kb = 64 * kt;
;         if (kb <= qw0 + 31) {
;             LAS const unsigned char* Kb = lds + ATT_K0 + buf * 16384;
;             LAS const unsigned char* Vb = lds + ATT_V0 + buf * 16384;
;             f32x16 s0, s1;
; #pragma unroll
;             for (int j = 0; j < 16; ++j) { s0[j] = 0.f; s1[j] = 0.f; }
;             bf16x8 ka[4][2];
; #pragma unroll
;             for (int ks = 0; ks < 4; ++ks) { ka[ks][0] = *(const LAS bf16x8*)(Kb + kbase[ks]); ka[ks][1] = *(const LAS bf16x8*)(Kb + kbase[ks] + 8192); }
;             __builtin_amdgcn_sched_barrier(0);
; #pragma unroll
;             for (int ks = 0; ks < 4; ++ks) {
;                 s0 = __builtin_amdgcn_mfma_f32_32x32x16_bf16(ka[ks][0], qf[ks], s0, 0, 0, 0);
;                 s1 = __builtin_amdgcn_mfma_f32_32x32x16_bf16(ka[ks][1], qf[ks], s1, 0, 0, 0);
;             }
;             if (kb + 63 > qw0) {
; #pragma unroll
;                 for (int j = 0; j < 16; ++j) { const int key = kb + crow(j, hi); if (key > qrow) s0[j] = -INFINITY; if (key + 32 > qrow) s1[j] = -INFINITY; }
;             }
;             float mxa = max3f(s0[0], s1[0], s0[1]), mxb = max3f(s1[1], s0[2], s1[2]), mxc = max3f(s0[3], s1[3], s0[4]), mxd = max3f(s1[4], s0[5], s1[5]);
;             mxa = max3f(mxa, s0[6], s1[6]); mxb = max3f(mxb, s0[7], s1[7]); mxc = max3f(mxc, s0[8], s1[8]); mxd = max3f(mxd, s0[9], s1[9]);
;             mxa = max3f(mxa, s0[10], s1[10]); mxb = max3f(mxb, s0[11], s1[11]); mxc = max3f(mxc, s0[12], s1[12]); mxd = max3f(mxd, s0[13], s1[13]);
;             mxa = max3f(mxa, s0[14], s1[14]); mxb = max3f(mxb, s0[15], s1[15]);
;             float mx = max3f(mxa, mxb, max3f(mxc, mxd, mxd));
;             { auto rr = __builtin_amdgcn_permlane32_swap(__builtin_bit_cast(unsigned, mx), __builtin_bit_cast(unsigned, mx), false, false);
	s_add_i32 m0, s73, 0x4000
	s_nop 0
	global_load_lds_dwordx4 v[134:135], off
	s_add_i32 m0, s73, 0x6000
	s_nop 0
	global_load_lds_dwordx4 v[200:201], off
	s_waitcnt lgkmcnt(6)
	v_mfma_f32_32x32x16_bf16 v[82:97], v[136:139], v[110:113], v[222:237]
	v_mfma_f32_32x32x16_bf16 v[66:81], v[140:143], v[110:113], v[222:237]
	s_waitcnt lgkmcnt(4)
	v_mfma_f32_32x32x16_bf16 v[82:97], v[204:207], v[106:109], v[82:97]
	v_mfma_f32_32x32x16_bf16 v[66:81], v[208:211], v[106:109], v[66:81]
	s_waitcnt lgkmcnt(2)
	v_mfma_f32_32x32x16_bf16 v[82:97], v[238:241], v[102:105], v[82:97]
	v_mfma_f32_32x32x16_bf16 v[66:81], v[242:245], v[102:105], v[66:81]
	s_waitcnt lgkmcnt(0)
	v_mfma_f32_32x32x16_bf16 v[82:97], v[246:249], v[98:101], v[82:97]
	v_mfma_f32_32x32x16_bf16 v[66:81], v[250:253], v[98:101], v[66:81]
	ds_read_b64_tr_b16 v[136:137], v114 offset:32768
	ds_read_b64_tr_b16 v[138:139], v115 offset:32768
	ds_read_b64_tr_b16 v[140:141], v116 offset:32768
	ds_read_b64_tr_b16 v[142:143], v117 offset:32768
	ds_read_b64_tr_b16 v[204:205], v118 offset:32768
	ds_read_b64_tr_b16 v[206:207], v119 offset:32768
	ds_read_b64_tr_b16 v[208:209], v120 offset:32768
	ds_read_b64_tr_b16 v[210:211], v121 offset:32768
	ds_read_b64_tr_b16 v[238:239], v114 offset:36864
	ds_read_b64_tr_b16 v[240:241], v115 offset:36864
	ds_read_b64_tr_b16 v[242:243], v116 offset:36864
	ds_read_b64_tr_b16 v[244:245], v117 offset:36864
	v_max3_f32 v122, v82, v66, v83
	v_max3_f32 v123, v67, v84, v68
	v_max3_f32 v124, v85, v69, v86
	v_max3_f32 v125, v70, v87, v71
	v_max3_f32 v122, v122, v88, v72
	v_max3_f32 v123, v123, v89, v73
	v_max3_f32 v124, v124, v90, v74
	v_max3_f32 v125, v125, v91, v75
	v_max3_f32 v122, v122, v92, v76
	v_max3_f32 v123, v123, v93, v77
	v_max3_f32 v124, v124, v94, v78
	v_max3_f32 v125, v125, v95, v79
	v_max3_f32 v122, v122, v96, v80
	v_max3_f32 v123, v123, v97, v81
	v_max3_f32 v122, v122, v123, v124
	v_max_f32_e32 v122, v122, v125
	v_mov_b32_e32 v203, v122
	s_nop 1
	v_permlane32_swap_b32_e32 v122, v203
	s_nop 1
	v_max_f32_e32 v122, v122, v203
	s_mov_b32 s70, 0
	v_cmp_lt_f32_e32 vcc, 0x41000000, v122
	s_cmp_eq_u32 s71, 0
	s_cbranch_scc1 .Lat1_u2_first
	s_cbranch_vccz .Lat1_u2_norescale
	s_branch .Lat1_u2_rescale

; __device__ __forceinline__ unsigned pk2(float lo, float hi) { f32x2 v = {lo, hi}; bf16x2_t b = __builtin_convertvector(v, bf16x2_t); return __builtin_bit_cast(unsigned, b); }
; __device__ __forceinline__ s16x4 vtr(LAS const unsigned char* p) { return __builtin_bit_cast(s16x4, __builtin_amdgcn_ds_read_tr16_b64_v4i16((LAS v4i16_t*)p)); }
; __device__ __forceinline__ bf16x8 cat8(s16x4 a, s16x4 b) { return (bf16x8){a[0], a[1], a[2], a[3], b[0], b[1], b[2], b[3]}; }
; __device__ __forceinline__ void attn_block(LAS unsigned char* lds, const bf16_t* P, bf16_t* mix, int b, int h, int qb, float lam, float outscale, const float* subln) {
;     ...
;             for (int j = 0; j < 16; ++j) { s0[j] = __builtin_amdgcn_exp2f(s0[j] - mrun); s1[j] = __builtin_amdgcn_exp2f(s1[j] - mrun); }
;             float ps0 = 0.f, ps1 = 0.f, ps2 = 0.f, ps3 = 0.f;
; #pragma unroll
;             for (int j = 0; j < 16; j += 2) { ps0 += s0[j]; ps1 += s1[j]; ps2 += s0[j + 1]; ps3 += s1[j + 1]; }
;             lrun += (ps0 + ps1) + (ps2 + ps3);
;             bf16x8 pb[4];
; #pragma unroll
;             for (int s2 = 0; s2 < 2; ++s2) {
;                 u32x4 w0, w1;
;                 w0.x = pk2(s0[8 * s2 + 0], s0[8 * s2 + 1]); w0.y = pk2(s0[8 * s2 + 2], s0[8 * s2 + 3]); w0.z = pk2(s0[8 * s2 + 4], s0[8 * s2 + 5]); w0.w = pk2(s0[8 * s2 + 6], s0[8 * s2 + 7]);
;                 w1.x = pk2(s1[8 * s2 + 0], s1[8 * s2 + 1]); w1.y = pk2(s1[8 * s2 + 2], s1[8 * s2 + 3]); w1.z = pk2(s1[8 * s2 + 4], s1[8 * s2 + 5]); w1.w = pk2(s1[8 * s2 + 6], s1[8 * s2 + 7]);
;                 pb[s2] = __builtin_bit_cast(bf16x8, w0); pb[2 + s2] = __builtin_bit_cast(bf16x8, w1);
;             }
; #pragma unroll
;             for (int s = 0; s < 4; ++s) {
; #pragma unroll
;                 for (int c = 0; c < 4; ++c) {
;                     const s16x4 v0 = vtr(Vb + vbase[c][0] + 4096 * s);
;                     const s16x4 v1 = vtr(Vb + vbase[c][1] + 4096 * s);
;                     o[c] = __builtin_amdgcn_mfma_f32_32x32x16_bf16(cat8(v0, v1), pb[s], o[c], 0, 0, 0);
;                 }
;             }
.Lat1_u2_norescale:
	v_exp_f32_e32 v82, v82
	v_exp_f32_e32 v83, v83
	v_exp_f32_e32 v84, v84
	v_exp_f32_e32 v85, v85
	v_exp_f32_e32 v86, v86
	v_exp_f32_e32 v87, v87
	v_exp_f32_e32 v88, v88
	v_exp_f32_e32 v89, v89
	v_exp_f32_e32 v90, v90
	v_exp_f32_e32 v91, v91
	v_exp_f32_e32 v92, v92
	v_exp_f32_e32 v93, v93
	v_exp_f32_e32 v94, v94
	v_exp_f32_e32 v95, v95
	v_exp_f32_e32 v96, v96
	v_exp_f32_e32 v97, v97
	v_cvt_pk_bf16_f32 v184, v82, v83
	v_cvt_pk_bf16_f32 v185, v84, v85
	v_cvt_pk_bf16_f32 v186, v86, v87
	v_cvt_pk_bf16_f32 v187, v88, v89
	v_cvt_pk_bf16_f32 v188, v90, v91
	v_cvt_pk_bf16_f32 v189, v92, v93
	v_cvt_pk_bf16_f32 v190, v94, v95
	v_cvt_pk_bf16_f32 v191, v96, v97
	v_add_f32_e32 v122, v82, v83
	v_add_f32_e32 v123, v84, v85
	v_add_f32_e32 v122, v122, v86
	v_add_f32_e32 v123, v123, v87
	v_add_f32_e32 v122, v122, v88
	v_add_f32_e32 v123, v123, v89
	v_add_f32_e32 v122, v122, v123
	v_add_f32_e32 v167, v167, v122
	v_add_f32_e32 v124, v90, v91
	v_add_f32_e32 v125, v92, v93
	v_add_f32_e32 v124, v124, v94
	v_add_f32_e32 v125, v125, v95
	v_add_f32_e32 v124, v124, v96
	v_add_f32_e32 v125, v125, v97
	v_add_f32_e32 v124, v124, v125
	v_add_f32_e32 v167, v167, v124
	s_add_i32 m0, s73, 0xb800
	s_nop 0
	global_load_lds_dwordx4 v[134:135], off offset:2048
	s_add_i32 m0, s73, 0xd800
	s_nop 0
	global_load_lds_dwordx4 v[200:201], off offset:2048
	v_lshl_add_u64 v[134:135], v[134:135], 0, s[40:41]
	v_lshl_add_u64 v[200:201], v[200:201], 0, s[40:41]
	s_waitcnt lgkmcnt(8)
	v_mfma_f32_32x32x16_bf16 v[50:65], v[136:139], v[184:187], v[50:65]
	ds_read_b64_tr_b16 v[246:247], v118 offset:36864
	ds_read_b64_tr_b16 v[248:249], v119 offset:36864
	v_exp_f32_e32 v66, v66
	v_exp_f32_e32 v67, v67
	v_exp_f32_e32 v68, v68
	v_mfma_f32_32x32x16_bf16 v[34:49], v[140:143], v[184:187], v[34:49]
	ds_read_b64_tr_b16 v[250:251], v120 offset:36864
	ds_read_b64_tr_b16 v[252:253], v121 offset:36864
	v_exp_f32_e32 v69, v69
	v_exp_f32_e32 v70, v70
	v_exp_f32_e32 v71, v71
	s_waitcnt lgkmcnt(8)
	v_mfma_f32_32x32x16_bf16 v[18:33], v[204:207], v[184:187], v[18:33]
	ds_read_b64_tr_b16 v[136:137], v114 offset:40960
	ds_read_b64_tr_b16 v[138:139], v115 offset:40960
	v_exp_f32_e32 v72, v72
	v_exp_f32_e32 v73, v73
	v_cvt_pk_bf16_f32 v192, v66, v67
	v_mfma_f32_32x32x16_bf16 v[2:17], v[208:211], v[184:187], v[2:17]
	ds_read_b64_tr_b16 v[140:141], v116 offset:40960
	ds_read_b64_tr_b16 v[142:143], v117 offset:40960
	v_cvt_pk_bf16_f32 v193, v68, v69
	v_cvt_pk_bf16_f32 v194, v70, v71
	v_cvt_pk_bf16_f32 v195, v72, v73
	s_waitcnt lgkmcnt(8)
	v_mfma_f32_32x32x16_bf16 v[50:65], v[238:241], v[188:191], v[50:65]
	ds_read_b64_tr_b16 v[204:205], v118 offset:40960
	ds_read_b64_tr_b16 v[206:207], v119 offset:40960
	v_exp_f32_e32 v74, v74
	v_exp_f32_e32 v75, v75
	v_exp_f32_e32 v76, v76
	v_mfma_f32_32x32x16_bf16 v[34:49], v[242:245], v[188:191], v[34:49]
	ds_read_b64_tr_b16 v[208:209], v120 offset:40960
	ds_read_b64_tr_b16 v[210:211], v121 offset:40960
	v_exp_f32_e32 v77, v77
	v_exp_f32_e32 v78, v78
	v_exp_f32_e32 v79, v79
	s_waitcnt lgkmcnt(8)
	v_mfma_f32_32x32x16_bf16 v[18:33], v[246:249], v[188:191], v[18:33]
	ds_read_b64_tr_b16 v[238:239], v114 offset:45056
	ds_read_b64_tr_b16 v[240:241], v115 offset:45056
	v_exp_f32_e32 v80, v80
	v_exp_f32_e32 v81, v81
	v_cvt_pk_bf16_f32 v196, v74, v75
	v_mfma_f32_32x32x16_bf16 v[2:17], v[250:253], v[188:191], v[2:17]
	ds_read_b64_tr_b16 v[242:243], v116 offset:45056
	ds_read_b64_tr_b16 v[244:245], v117 offset:45056
	v_cvt_pk_bf16_f32 v197, v76, v77
	v_cvt_pk_bf16_f32 v198, v78, v79
	v_cvt_pk_bf16_f32 v199, v80, v81
	s_waitcnt lgkmcnt(8)
	v_mfma_f32_32x32x16_bf16 v[50:65], v[136:139], v[192:195], v[50:65]
	ds_read_b64_tr_b16 v[246:247], v118 offset:45056
	ds_read_b64_tr_b16 v[248:249], v119 offset:45056
	v_add_f32_e32 v0, v66, v67
	v_add_f32_e32 v203, v68, v69
	v_add_f32_e32 v0, v0, v70
	v_mfma_f32_32x32x16_bf16 v[34:49], v[140:143], v[192:195], v[34:49]
	ds_read_b64_tr_b16 v[250:251], v120 offset:45056
	ds_read_b64_tr_b16 v[252:253], v121 offset:45056
	v_add_f32_e32 v203, v203, v71
	v_add_f32_e32 v0, v0, v72
	v_add_f32_e32 v203, v203, v73
	s_waitcnt lgkmcnt(8)
	v_mfma_f32_32x32x16_bf16 v[18:33], v[204:207], v[192:195], v[18:33]
	v_add_f32_e32 v0, v0, v203
	v_add_f32_e32 v167, v167, v0
	v_add_f32_e32 v0, v74, v75
	v_mfma_f32_32x32x16_bf16 v[2:17], v[208:211], v[192:195], v[2:17]
	v_add_f32_e32 v203, v76, v77
	v_add_f32_e32 v0, v0, v78
	v_add_f32_e32 v203, v203, v79
	s_waitcnt lgkmcnt(4)
	v_mfma_f32_32x32x16_bf16 v[50:65], v[238:241], v[196:199], v[50:65]
	v_add_f32_e32 v0, v0, v80
	v_add_f32_e32 v203, v203, v81
	v_add_f32_e32 v0, v0, v203
	v_mfma_f32_32x32x16_bf16 v[34:49], v[242:245], v[196:199], v[34:49]
	v_add_f32_e32 v167, v167, v0
	s_waitcnt lgkmcnt(0)
	v_mfma_f32_32x32x16_bf16 v[18:33], v[246:249], v[196:199], v[18:33]
	v_mfma_f32_32x32x16_bf16 v[2:17], v[250:253], v[196:199], v[2:17]
	ds_read_b128 v[136:139], v126 offset:16384
	ds_read_b128 v[140:143], v126 offset:24576
	ds_read_b128 v[204:207], v127 offset:16384
	ds_read_b128 v[208:211], v127 offset:24576
	ds_read_b128 v[238:241], v128 offset:16384
	ds_read_b128 v[242:245], v128 offset:24576
	ds_read_b128 v[246:249], v129 offset:16384
	ds_read_b128 v[250:253], v129 offset:24576
	s_waitcnt vmcnt(6)
	s_add_i32 s71, s71, 64
	s_barrier
; #define LAS __attribute__((address_space(3)))
; __device__ __forceinline__ void attn_block(LAS unsigned char* lds, const bf16_t* P, bf16_t* mix, int b, int h, int qb, float lam, float outscale, const float* subln) {
;     ...
;         if (kt + 1 < ntiles) {
;             const size_t ro = (size_t)(64 * (kt + 1)) * INC;
;             kr0 = *(const u32x4*)(kg + ro + (size_t)srow * INC); kr1 = *(const u32x4*)(kg + ro + (size_t)(srow + 32) * INC);
;             vr0 = *(const u32x4*)(vg + ro + (size_t)srow * INC); vr1 = *(const u32x4*)(vg + ro + (size_t)(srow + 32) * INC);
;         }
;         const int kb = 64 * kt;
;         if (kb <= qw0 + 31) {
;             LAS const unsigned char* Kb = lds + ATT_K0 + buf * 16384;
;             LAS const unsigned char* Vb = lds + ATT_V0 + buf * 16384;
;             f32x16 s0, s1;
; #pragma unroll
;             for (int j = 0; j < 16; ++j) { s0[j] = 0.f; s1[j] = 0.f; }
;             bf16x8 ka[4][2];
; #pragma unroll
;             for (int ks = 0; ks < 4; ++ks) { ka[ks][0] = *(const LAS bf16x8*)(Kb + kbase[ks]); ka[ks][1] = *(const LAS bf16x8*)(Kb + kbase[ks] + 8192); }
;             __builtin_amdgcn_sched_barrier(0);
; #pragma unroll
;             for (int ks = 0; ks < 4; ++ks) {
;                 s0 = __builtin_amdgcn_mfma_f32_32x32x16_bf16(ka[ks][0], qf[ks], s0, 0, 0, 0);
;                 s1 = __builtin_amdgcn_mfma_f32_32x32x16_bf16(ka[ks][1], qf[ks], s1, 0, 0, 0);
;             }
;             if (kb + 63 > qw0) {
; #pragma unroll
;                 for (int j = 0; j < 16; ++j) { const int key = kb + crow(j, hi); if (key > qrow) s0[j] = -INFINITY; if (key + 32 > qrow) s1[j] = -INFINITY; }
;             }
;             float mxa = max3f(s0[0], s1[0], s0[1]), mxb = max3f(s1[1], s0[2], s1[2]), mxc = max3f(s0[3], s1[3], s0[4]), mxd = max3f(s1[4], s0[5], s1[5]);
;             mxa = max3f(mxa, s0[6], s1[6]); mxb = max3f(mxb, s0[7], s1[7]); mxc = max3f(mxc, s0[8], s1[8]); mxd = max3f(mxd, s0[9], s1[9]);
;             mxa = max3f(mxa, s0[10], s1[10]); mxb = max3f(mxb, s0[11], s1[11]); mxc = max3f(mxc, s0[12], s1[12]); mxd = max3f(mxd, s0[13], s1[13]);
;             mxa = max3f(mxa, s0[14], s1[14]); mxb = max3f(mxb, s0[15], s1[15]);
;             float mx = max3f(mxa, mxb, max3f(mxc, mxd, mxd));
;             { auto rr = __builtin_amdgcn_permlane32_swap(__builtin_bit_cast(unsigned, mx), __builtin_bit_cast(unsigned, mx), false, false);
	s_add_i32 m0, s73, 0x10000
	s_nop 0
	global_load_lds_dwordx4 v[134:135], off
	s_add_i32 m0, s73, 0x12000
	s_nop 0
	global_load_lds_dwordx4 v[200:201], off
	s_waitcnt lgkmcnt(6)
	v_mfma_f32_32x32x16_bf16 v[82:97], v[136:139], v[110:113], v[222:237]
	v_mfma_f32_32x32x16_bf16 v[66:81], v[140:143], v[110:113], v[222:237]
	s_waitcnt lgkmcnt(4)
	v_mfma_f32_32x32x16_bf16 v[82:97], v[204:207], v[106:109], v[82:97]
	v_mfma_f32_32x32x16_bf16 v[66:81], v[208:211], v[106:109], v[66:81]
	s_waitcnt lgkmcnt(2)
	v_mfma_f32_32x32x16_bf16 v[82:97], v[238:241], v[102:105], v[82:97]
	v_mfma_f32_32x32x16_bf16 v[66:81], v[242:245], v[102:105], v[66:81]
	s_waitcnt lgkmcnt(0)
	v_mfma_f32_32x32x16_bf16 v[82:97], v[246:249], v[98:101], v[82:97]
	v_mfma_f32_32x32x16_bf16 v[66:81], v[250:253], v[98:101], v[66:81]
	ds_read_b64_tr_b16 v[136:137], v114 offset:49152
	ds_read_b64_tr_b16 v[138:139], v115 offset:49152
	ds_read_b64_tr_b16 v[140:141], v116 offset:49152
	ds_read_b64_tr_b16 v[142:143], v117 offset:49152
	ds_read_b64_tr_b16 v[204:205], v118 offset:49152
	ds_read_b64_tr_b16 v[206:207], v119 offset:49152
	ds_read_b64_tr_b16 v[208:209], v120 offset:49152
	ds_read_b64_tr_b16 v[210:211], v121 offset:49152
	ds_read_b64_tr_b16 v[238:239], v114 offset:53248
	ds_read_b64_tr_b16 v[240:241], v115 offset:53248
	ds_read_b64_tr_b16 v[242:243], v116 offset:53248
	ds_read_b64_tr_b16 v[244:245], v117 offset:53248
	v_max3_f32 v122, v82, v66, v83
	v_max3_f32 v123, v67, v84, v68
	v_max3_f32 v124, v85, v69, v86
	v_max3_f32 v125, v70, v87, v71
	v_max3_f32 v122, v122, v88, v72
	v_max3_f32 v123, v123, v89, v73
	v_max3_f32 v124, v124, v90, v74
	v_max3_f32 v125, v125, v91, v75
	v_max3_f32 v122, v122, v92, v76
	v_max3_f32 v123, v123, v93, v77
	v_max3_f32 v124, v124, v94, v78
	v_max3_f32 v125, v125, v95, v79
	v_max3_f32 v122, v122, v96, v80
	v_max3_f32 v123, v123, v97, v81
	v_max3_f32 v122, v122, v123, v124
	v_max_f32_e32 v122, v122, v125
	v_mov_b32_e32 v203, v122
	s_nop 1
	v_permlane32_swap_b32_e32 v122, v203
	s_nop 1
	v_max_f32_e32 v122, v122, v203
	s_mov_b32 s70, 0
	v_cmp_lt_f32_e32 vcc, 0x41000000, v122
	s_cmp_eq_u32 s71, 0
	s_cbranch_scc1 .Lat1_u3_first
	s_cbranch_vccz .Lat1_u3_norescale
	s_branch .Lat1_u3_rescale

; #define LAS __attribute__((address_space(3)))
; __device__ __forceinline__ unsigned pk2(float lo, float hi) { f32x2 v = {lo, hi}; bf16x2_t b = __builtin_convertvector(v, bf16x2_t); return __builtin_bit_cast(unsigned, b); }
; __device__ __forceinline__ s16x4 vtr(LAS const unsigned char* p) { return __builtin_bit_cast(s16x4, __builtin_amdgcn_ds_read_tr16_b64_v4i16((LAS v4i16_t*)p)); }
; __device__ __forceinline__ void attn_block(LAS unsigned char* lds, const bf16_t* P, bf16_t* mix, int b, int h, int qb, float lam, float outscale, const float* subln) {
;     ...
;             for (int j = 0; j < 16; ++j) { s0[j] = __builtin_amdgcn_exp2f(s0[j] - mrun); s1[j] = __builtin_amdgcn_exp2f(s1[j] - mrun); }
;             float ps0 = 0.f, ps1 = 0.f, ps2 = 0.f, ps3 = 0.f;
; #pragma unroll
;             for (int j = 0; j < 16; j += 2) { ps0 += s0[j]; ps1 += s1[j]; ps2 += s0[j + 1]; ps3 += s1[j + 1]; }
;             lrun += (ps0 + ps1) + (ps2 + ps3);
;             bf16x8 pb[4];
; #pragma unroll
;             for (int s2 = 0; s2 < 2; ++s2) {
;                 u32x4 w0, w1;
;                 w0.x = pk2(s0[8 * s2 + 0], s0[8 * s2 + 1]); w0.y = pk2(s0[8 * s2 + 2], s0[8 * s2 + 3]); w0.z = pk2(s0[8 * s2 + 4], s0[8 * s2 + 5]); w0.w = pk2(s0[8 * s2 + 6], s0[8 * s2 + 7]);
;                 w1.x = pk2(s1[8 * s2 + 0], s1[8 * s2 + 1]); w1.y = pk2(s1[8 * s2 + 2], s1[8 * s2 + 3]); w1.z = pk2(s1[8 * s2 + 4], s1[8 * s2 + 5]); w1.w = pk2(s1[8 * s2 + 6], s1[8 * s2 + 7]);
;                 pb[s2] = __builtin_bit_cast(bf16x8, w0); pb[2 + s2] = __builtin_bit_cast(bf16x8, w1);
;             }
; #pragma unroll
;             for (int s = 0; s < 4; ++s) {
; #pragma unroll
;                 for (int c = 0; c < 4; ++c) {
;                     const s16x4 v0 = vtr(Vb + vbase[c][0] + 4096 * s);
;                     const s16x4 v1 = vtr(Vb + vbase[c][1] + 4096 * s);
;                     o[c] = __builtin_amdgcn_mfma_f32_32x32x16_bf16(cat8(v0, v1), pb[s], o[c], 0, 0, 0);
;                 }
;             }
;         }
;         if (kt + 1 < ntiles) {
;             const int nb = (kt + 1) & 1;
;             *(LAS u32x4*)(lds + ATT_K0 + nb * 16384 + so0) = kr0; *(LAS u32x4*)(lds + ATT_K0 + nb * 16384 + so1) = kr1;
;             *(LAS u32x4*)(lds + ATT_V0 + nb * 16384 + so0) = vr0; *(LAS u32x4*)(lds + ATT_V0 + nb * 16384 + so1) = vr1;
;         }
;     }
.Lat1_u3_norescale:
	v_exp_f32_e32 v82, v82
	v_exp_f32_e32 v83, v83
	v_exp_f32_e32 v84, v84
	v_exp_f32_e32 v85, v85
	v_exp_f32_e32 v86, v86
	v_exp_f32_e32 v87, v87
	v_exp_f32_e32 v88, v88
	v_exp_f32_e32 v89, v89
	v_exp_f32_e32 v90, v90
	v_exp_f32_e32 v91, v91
	v_exp_f32_e32 v92, v92
	v_exp_f32_e32 v93, v93
	v_exp_f32_e32 v94, v94
	v_exp_f32_e32 v95, v95
	v_exp_f32_e32 v96, v96
	v_exp_f32_e32 v97, v97
	v_cvt_pk_bf16_f32 v184, v82, v83
	v_cvt_pk_bf16_f32 v185, v84, v85
	v_cvt_pk_bf16_f32 v186, v86, v87
	v_cvt_pk_bf16_f32 v187, v88, v89
	v_cvt_pk_bf16_f32 v188, v90, v91
	v_cvt_pk_bf16_f32 v189, v92, v93
	v_cvt_pk_bf16_f32 v190, v94, v95
	v_cvt_pk_bf16_f32 v191, v96, v97
	v_add_f32_e32 v122, v82, v83
	v_add_f32_e32 v123, v84, v85
	v_add_f32_e32 v122, v122, v86
	v_add_f32_e32 v123, v123, v87
	v_add_f32_e32 v122, v122, v88
	v_add_f32_e32 v123, v123, v89
	v_add_f32_e32 v122, v122, v123
	v_add_f32_e32 v167, v167, v122
	v_add_f32_e32 v124, v90, v91
	v_add_f32_e32 v125, v92, v93
	v_add_f32_e32 v124, v124, v94
	v_add_f32_e32 v125, v125, v95
	v_add_f32_e32 v124, v124, v96
	v_add_f32_e32 v125, v125, v97
	v_add_f32_e32 v124, v124, v125
	v_add_f32_e32 v167, v167, v124
	s_add_i32 m0, s73, 0x17800
	s_nop 0
	global_load_lds_dwordx4 v[134:135], off offset:2048
	s_add_i32 m0, s73, 0x19800
	s_nop 0
	global_load_lds_dwordx4 v[200:201], off offset:2048
	v_lshl_add_u64 v[134:135], v[134:135], 0, s[40:41]
	v_lshl_add_u64 v[200:201], v[200:201], 0, s[40:41]
	s_waitcnt lgkmcnt(8)
	v_mfma_f32_32x32x16_bf16 v[50:65], v[136:139], v[184:187], v[50:65]
	ds_read_b64_tr_b16 v[246:247], v118 offset:53248
	ds_read_b64_tr_b16 v[248:249], v119 offset:53248
	v_exp_f32_e32 v66, v66
	v_exp_f32_e32 v67, v67
	v_exp_f32_e32 v68, v68
	v_mfma_f32_32x32x16_bf16 v[34:49], v[140:143], v[184:187], v[34:49]
	ds_read_b64_tr_b16 v[250:251], v120 offset:53248
	ds_read_b64_tr_b16 v[252:253], v121 offset:53248
	v_exp_f32_e32 v69, v69
	v_exp_f32_e32 v70, v70
	v_exp_f32_e32 v71, v71
	s_waitcnt lgkmcnt(8)
	v_mfma_f32_32x32x16_bf16 v[18:33], v[204:207], v[184:187], v[18:33]
	ds_read_b64_tr_b16 v[136:137], v114 offset:57344
	ds_read_b64_tr_b16 v[138:139], v115 offset:57344
	v_exp_f32_e32 v72, v72
	v_exp_f32_e32 v73, v73
	v_cvt_pk_bf16_f32 v192, v66, v67
	v_mfma_f32_32x32x16_bf16 v[2:17], v[208:211], v[184:187], v[2:17]
	ds_read_b64_tr_b16 v[140:141], v116 offset:57344
	ds_read_b64_tr_b16 v[142:143], v117 offset:57344
	v_cvt_pk_bf16_f32 v193, v68, v69
	v_cvt_pk_bf16_f32 v194, v70, v71
	v_cvt_pk_bf16_f32 v195, v72, v73
	s_waitcnt lgkmcnt(8)
	v_mfma_f32_32x32x16_bf16 v[50:65], v[238:241], v[188:191], v[50:65]
	ds_read_b64_tr_b16 v[204:205], v118 offset:57344
	ds_read_b64_tr_b16 v[206:207], v119 offset:57344
	v_exp_f32_e32 v74, v74
	v_exp_f32_e32 v75, v75
	v_exp_f32_e32 v76, v76
	v_mfma_f32_32x32x16_bf16 v[34:49], v[242:245], v[188:191], v[34:49]
	ds_read_b64_tr_b16 v[208:209], v120 offset:57344
	ds_read_b64_tr_b16 v[210:211], v121 offset:57344
	v_exp_f32_e32 v77, v77
	v_exp_f32_e32 v78, v78
	v_exp_f32_e32 v79, v79
	s_waitcnt lgkmcnt(8)
	v_mfma_f32_32x32x16_bf16 v[18:33], v[246:249], v[188:191], v[18:33]
	ds_read_b64_tr_b16 v[238:239], v114 offset:61440
	ds_read_b64_tr_b16 v[240:241], v115 offset:61440
	v_exp_f32_e32 v80, v80
	v_exp_f32_e32 v81, v81
	v_cvt_pk_bf16_f32 v196, v74, v75
	v_mfma_f32_32x32x16_bf16 v[2:17], v[250:253], v[188:191], v[2:17]
	ds_read_b64_tr_b16 v[242:243], v116 offset:61440
	ds_read_b64_tr_b16 v[244:245], v117 offset:61440
	v_cvt_pk_bf16_f32 v197, v76, v77
	v_cvt_pk_bf16_f32 v198, v78, v79
	v_cvt_pk_bf16_f32 v199, v80, v81
	s_waitcnt lgkmcnt(8)
	v_mfma_f32_32x32x16_bf16 v[50:65], v[136:139], v[192:195], v[50:65]
	ds_read_b64_tr_b16 v[246:247], v118 offset:61440
	ds_read_b64_tr_b16 v[248:249], v119 offset:61440
	v_add_f32_e32 v0, v66, v67
	v_add_f32_e32 v203, v68, v69
	v_add_f32_e32 v0, v0, v70
	v_mfma_f32_32x32x16_bf16 v[34:49], v[140:143], v[192:195], v[34:49]
	ds_read_b64_tr_b16 v[250:251], v120 offset:61440
	ds_read_b64_tr_b16 v[252:253], v121 offset:61440
	v_add_f32_e32 v203, v203, v71
	v_add_f32_e32 v0, v0, v72
	v_add_f32_e32 v203, v203, v73
	s_waitcnt lgkmcnt(8)
	v_mfma_f32_32x32x16_bf16 v[18:33], v[204:207], v[192:195], v[18:33]
	v_add_f32_e32 v0, v0, v203
	v_add_f32_e32 v167, v167, v0
	v_add_f32_e32 v0, v74, v75
	v_mfma_f32_32x32x16_bf16 v[2:17], v[208:211], v[192:195], v[2:17]
	v_add_f32_e32 v203, v76, v77
	v_add_f32_e32 v0, v0, v78
	v_add_f32_e32 v203, v203, v79
	s_waitcnt lgkmcnt(4)
	v_mfma_f32_32x32x16_bf16 v[50:65], v[238:241], v[196:199], v[50:65]
	v_add_f32_e32 v0, v0, v80
	v_add_f32_e32 v203, v203, v81
	v_add_f32_e32 v0, v0, v203
	v_mfma_f32_32x32x16_bf16 v[34:49], v[242:245], v[196:199], v[34:49]
	v_add_f32_e32 v167, v167, v0
	s_waitcnt lgkmcnt(0)
	v_mfma_f32_32x32x16_bf16 v[18:33], v[246:249], v[196:199], v[18:33]
	v_mfma_f32_32x32x16_bf16 v[2:17], v[250:253], v[196:199], v[2:17]
	ds_read_b128 v[136:139], v180 offset:0
	ds_read_b128 v[140:143], v180 offset:8192
	ds_read_b128 v[204:207], v181 offset:0
	ds_read_b128 v[208:211], v181 offset:8192
	ds_read_b128 v[238:241], v178 offset:0
	ds_read_b128 v[242:245], v178 offset:8192
	ds_read_b128 v[246:249], v177 offset:0
	ds_read_b128 v[250:253], v177 offset:8192
	s_waitcnt vmcnt(6)
	s_add_i32 s71, s71, 64
	s_add_i32 s72, s71, 384
	s_cmp_le_u32 s72, s36
	s_barrier
	s_cbranch_scc1 .Lat1_U_top

; #define LAS __attribute__((address_space(3)))
; __device__ __forceinline__ void attn_block(LAS unsigned char* lds, const bf16_t* P, bf16_t* mix, int b, int h, int qb, float lam, float outscale, const float* subln) {
;     ...
;     for (int kt = 0; kt < ntiles; ++kt) {
;         __syncthreads();
;         const int buf = kt & 1;
;         if (kt + 1 < ntiles) {
;             const size_t ro = (size_t)(64 * (kt + 1)) * INC;
;             kr0 = *(const u32x4*)(kg + ro + (size_t)srow * INC); kr1 = *(const u32x4*)(kg + ro + (size_t)(srow + 32) * INC);
;             vr0 = *(const u32x4*)(vg + ro + (size_t)srow * INC); vr1 = *(const u32x4*)(vg + ro + (size_t)(srow + 32) * INC);
;         }
;         const int kb = 64 * kt;
;         if (kb <= qw0 + 31) {
;             LAS const unsigned char* Kb = lds + ATT_K0 + buf * 16384;
;             LAS const unsigned char* Vb = lds + ATT_V0 + buf * 16384;
;             f32x16 s0, s1;
; #pragma unroll
;             for (int j = 0; j < 16; ++j) { s0[j] = 0.f; s1[j] = 0.f; }
;             bf16x8 ka[4][2];
; #pragma unroll
;             for (int ks = 0; ks < 4; ++ks) { ka[ks][0] = *(const LAS bf16x8*)(Kb + kbase[ks]); ka[ks][1] = *(const LAS bf16x8*)(Kb + kbase[ks] + 8192); }
;             __builtin_amdgcn_sched_barrier(0);
; #pragma unroll
;             for (int ks = 0; ks < 4; ++ks) {
;                 s0 = __builtin_amdgcn_mfma_f32_32x32x16_bf16(ka[ks][0], qf[ks], s0, 0, 0, 0);
;                 s1 = __builtin_amdgcn_mfma_f32_32x32x16_bf16(ka[ks][1], qf[ks], s1, 0, 0, 0);
;             }
;             if (kb + 63 > qw0) {
; #pragma unroll
;                 for (int j = 0; j < 16; ++j) { const int key = kb + crow(j, hi); if (key > qrow) s0[j] = -INFINITY; if (key + 32 > qrow) s1[j] = -INFINITY; }
;             }
;             float mxa = max3f(s0[0], s1[0], s0[1]), mxb = max3f(s1[1], s0[2], s1[2]), mxc = max3f(s0[3], s1[3], s0[4]), mxd = max3f(s1[4], s0[5], s1[5]);
;             mxa = max3f(mxa, s0[6], s1[6]); mxb = max3f(mxb, s0[7], s1[7]); mxc = max3f(mxc, s0[8], s1[8]); mxd = max3f(mxd, s0[9], s1[9]);
;             mxa = max3f(mxa, s0[10], s1[10]); mxb = max3f(mxb, s0[11], s1[11]); mxc = max3f(mxc, s0[12], s1[12]); mxd = max3f(mxd, s0[13], s1[13]);
;             mxa = max3f(mxa, s0[14], s1[14]); mxb = max3f(mxb, s0[15], s1[15]);
;             float mx = max3f(mxa, mxb, max3f(mxc, mxd, mxd));
.Lat1_S_top:
	s_add_i32 s73, s71, 192
	s_lshl_b32 s70, s73, 8
	s_lshl_b32 s73, s73, 9
	s_and_b32 s70, s70, 0x4000
	s_and_b32 s73, s73, 0x10000
	s_or_b32 s73, s73, s70
	s_lshl_b32 s70, s42, 4
	s_and_b32 s70, s70, 0x1c00
	s_add_i32 s73, s73, s70
	s_add_i32 m0, s73, 0x0
	s_nop 0
	global_load_lds_dwordx4 v[134:135], off
	s_add_i32 m0, s73, 0x2000
	s_nop 0
	global_load_lds_dwordx4 v[200:201], off
	s_lshl_b32 s70, s71, 8
	s_lshl_b32 s72, s71, 9
	s_and_b32 s70, s70, 0x4000
	s_and_b32 s72, s72, 0x10000
	s_or_b32 s72, s72, s70
	s_waitcnt lgkmcnt(6)
	v_mfma_f32_32x32x16_bf16 v[82:97], v[136:139], v[110:113], v[222:237]
	v_mfma_f32_32x32x16_bf16 v[66:81], v[140:143], v[110:113], v[222:237]
	s_waitcnt lgkmcnt(4)
	v_mfma_f32_32x32x16_bf16 v[82:97], v[204:207], v[106:109], v[82:97]
	v_mfma_f32_32x32x16_bf16 v[66:81], v[208:211], v[106:109], v[66:81]
	s_waitcnt lgkmcnt(2)
	v_mfma_f32_32x32x16_bf16 v[82:97], v[238:241], v[102:105], v[82:97]
	v_mfma_f32_32x32x16_bf16 v[66:81], v[242:245], v[102:105], v[66:81]
	s_waitcnt lgkmcnt(0)
	v_mfma_f32_32x32x16_bf16 v[82:97], v[246:249], v[98:101], v[82:97]
	v_mfma_f32_32x32x16_bf16 v[66:81], v[250:253], v[98:101], v[66:81]
	v_add_u32_e32 v114, s72, v173
	v_add_u32_e32 v115, s72, v174
	v_add_u32_e32 v116, s72, v170
	v_add_u32_e32 v117, s72, v172
	v_add_u32_e32 v118, s72, v168
	v_add_u32_e32 v119, s72, v171
	v_add_u32_e32 v120, s72, v145
	v_add_u32_e32 v121, s72, v169
	s_nop 3
	v_max3_f32 v122, v82, v66, v83
	v_max3_f32 v123, v67, v84, v68
	v_max3_f32 v124, v85, v69, v86
	v_max3_f32 v125, v70, v87, v71
	v_max3_f32 v122, v122, v88, v72
	v_max3_f32 v123, v123, v89, v73
	v_max3_f32 v124, v124, v90, v74
	v_max3_f32 v125, v125, v91, v75
	v_max3_f32 v122, v122, v92, v76
	v_max3_f32 v123, v123, v93, v77
	v_max3_f32 v124, v124, v94, v78
	v_max3_f32 v125, v125, v95, v79
	v_max3_f32 v122, v122, v96, v80
	v_max3_f32 v123, v123, v97, v81
	v_max3_f32 v122, v122, v123, v124
	v_max_f32_e32 v122, v122, v125
	v_mov_b32_e32 v203, v122
	s_nop 1
	v_permlane32_swap_b32_e32 v122, v203
	s_nop 1
	v_max_f32_e32 v122, v122, v203
	s_mov_b32 s70, 0
	v_cmp_lt_f32_e32 vcc, 0x41000000, v122
	s_cmp_eq_u32 s71, 0
	s_cbranch_scc1 .Lat1_sA_first
	s_cbranch_vccz .Lat1_sA_norescale
	s_branch .Lat1_sA_rescale

; #define LAS __attribute__((address_space(3)))
; __device__ __forceinline__ unsigned pk2(float lo, float hi) { f32x2 v = {lo, hi}; bf16x2_t b = __builtin_convertvector(v, bf16x2_t); return __builtin_bit_cast(unsigned, b); }
; __device__ __forceinline__ s16x4 vtr(LAS const unsigned char* p) { return __builtin_bit_cast(s16x4, __builtin_amdgcn_ds_read_tr16_b64_v4i16((LAS v4i16_t*)p)); }
; __device__ __forceinline__ void attn_block(LAS unsigned char* lds, const bf16_t* P, bf16_t* mix, int b, int h, int qb, float lam, float outscale, const float* subln) {
;     ...
;             for (int j = 0; j < 16; ++j) { s0[j] = __builtin_amdgcn_exp2f(s0[j] - mrun); s1[j] = __builtin_amdgcn_exp2f(s1[j] - mrun); }
;             float ps0 = 0.f, ps1 = 0.f, ps2 = 0.f, ps3 = 0.f;
; #pragma unroll
;             for (int j = 0; j < 16; j += 2) { ps0 += s0[j]; ps1 += s1[j]; ps2 += s0[j + 1]; ps3 += s1[j + 1]; }
;             lrun += (ps0 + ps1) + (ps2 + ps3);
;             bf16x8 pb[4];
; #pragma unroll
;             for (int s2 = 0; s2 < 2; ++s2) {
;                 u32x4 w0, w1;
;                 w0.x = pk2(s0[8 * s2 + 0], s0[8 * s2 + 1]); w0.y = pk2(s0[8 * s2 + 2], s0[8 * s2 + 3]); w0.z = pk2(s0[8 * s2 + 4], s0[8 * s2 + 5]); w0.w = pk2(s0[8 * s2 + 6], s0[8 * s2 + 7]);
;                 w1.x = pk2(s1[8 * s2 + 0], s1[8 * s2 + 1]); w1.y = pk2(s1[8 * s2 + 2], s1[8 * s2 + 3]); w1.z = pk2(s1[8 * s2 + 4], s1[8 * s2 + 5]); w1.w = pk2(s1[8 * s2 + 6], s1[8 * s2 + 7]);
;                 pb[s2] = __builtin_bit_cast(bf16x8, w0); pb[2 + s2] = __builtin_bit_cast(bf16x8, w1);
;             }
; #pragma unroll
;             for (int s = 0; s < 4; ++s) {
; #pragma unroll
;                 for (int c = 0; c < 4; ++c) {
;                     const s16x4 v0 = vtr(Vb + vbase[c][0] + 4096 * s);
;                     const s16x4 v1 = vtr(Vb + vbase[c][1] + 4096 * s);
;                     o[c] = __builtin_amdgcn_mfma_f32_32x32x16_bf16(cat8(v0, v1), pb[s], o[c], 0, 0, 0);
;                 }
;             }
;         }
;         if (kt + 1 < ntiles) {
;             const int nb = (kt + 1) & 1;
;             *(LAS u32x4*)(lds + ATT_K0 + nb * 16384 + so0) = kr0; *(LAS u32x4*)(lds + ATT_K0 + nb * 16384 + so1) = kr1;
;             *(LAS u32x4*)(lds + ATT_V0 + nb * 16384 + so0) = vr0; *(LAS u32x4*)(lds + ATT_V0 + nb * 16384 + so1) = vr1;
;         }
.Lat1_sA_norescale:
	ds_read_b64_tr_b16 v[136:137], v114 offset:32768
	ds_read_b64_tr_b16 v[138:139], v115 offset:32768
	ds_read_b64_tr_b16 v[140:141], v116 offset:32768
	ds_read_b64_tr_b16 v[142:143], v117 offset:32768
	ds_read_b64_tr_b16 v[204:205], v118 offset:32768
	ds_read_b64_tr_b16 v[206:207], v119 offset:32768
	ds_read_b64_tr_b16 v[208:209], v120 offset:32768
	ds_read_b64_tr_b16 v[210:211], v121 offset:32768
	ds_read_b64_tr_b16 v[238:239], v114 offset:36864
	ds_read_b64_tr_b16 v[240:241], v115 offset:36864
	ds_read_b64_tr_b16 v[242:243], v116 offset:36864
	ds_read_b64_tr_b16 v[244:245], v117 offset:36864
	v_exp_f32_e32 v82, v82
	v_exp_f32_e32 v83, v83
	v_exp_f32_e32 v84, v84
	v_exp_f32_e32 v85, v85
	v_exp_f32_e32 v86, v86
	v_exp_f32_e32 v87, v87
	v_exp_f32_e32 v88, v88
	v_exp_f32_e32 v89, v89
	v_exp_f32_e32 v90, v90
	v_exp_f32_e32 v91, v91
	v_exp_f32_e32 v92, v92
	v_exp_f32_e32 v93, v93
	v_exp_f32_e32 v94, v94
	v_exp_f32_e32 v95, v95
	v_exp_f32_e32 v96, v96
	v_exp_f32_e32 v97, v97
	v_cvt_pk_bf16_f32 v184, v82, v83
	v_cvt_pk_bf16_f32 v185, v84, v85
	v_cvt_pk_bf16_f32 v186, v86, v87
	v_cvt_pk_bf16_f32 v187, v88, v89
	v_cvt_pk_bf16_f32 v188, v90, v91
	v_cvt_pk_bf16_f32 v189, v92, v93
	v_cvt_pk_bf16_f32 v190, v94, v95
	v_cvt_pk_bf16_f32 v191, v96, v97
	v_add_f32_e32 v122, v82, v83
	v_add_f32_e32 v123, v84, v85
	v_add_f32_e32 v122, v122, v86
	v_add_f32_e32 v123, v123, v87
	v_add_f32_e32 v122, v122, v88
	v_add_f32_e32 v123, v123, v89
	v_add_f32_e32 v122, v122, v123
	v_add_f32_e32 v167, v167, v122
	v_add_f32_e32 v124, v90, v91
	v_add_f32_e32 v125, v92, v93
	v_add_f32_e32 v124, v124, v94
	v_add_f32_e32 v125, v125, v95
	v_add_f32_e32 v124, v124, v96
	v_add_f32_e32 v125, v125, v97
	v_add_f32_e32 v124, v124, v125
	v_add_f32_e32 v167, v167, v124
	s_add_i32 m0, s73, 0x7800
	s_nop 0
	global_load_lds_dwordx4 v[134:135], off offset:2048
	s_add_i32 m0, s73, 0x9800
	s_nop 0
	global_load_lds_dwordx4 v[200:201], off offset:2048
	v_lshl_add_u64 v[134:135], v[134:135], 0, s[40:41]
	v_lshl_add_u64 v[200:201], v[200:201], 0, s[40:41]
	s_waitcnt lgkmcnt(8)
	v_mfma_f32_32x32x16_bf16 v[50:65], v[136:139], v[184:187], v[50:65]
	ds_read_b64_tr_b16 v[246:247], v118 offset:36864
	ds_read_b64_tr_b16 v[248:249], v119 offset:36864
	v_exp_f32_e32 v66, v66
	v_exp_f32_e32 v67, v67
	v_exp_f32_e32 v68, v68
	v_mfma_f32_32x32x16_bf16 v[34:49], v[140:143], v[184:187], v[34:49]
	ds_read_b64_tr_b16 v[250:251], v120 offset:36864
	ds_read_b64_tr_b16 v[252:253], v121 offset:36864
	v_exp_f32_e32 v69, v69
	v_exp_f32_e32 v70, v70
	v_exp_f32_e32 v71, v71
	s_waitcnt lgkmcnt(8)
	v_mfma_f32_32x32x16_bf16 v[18:33], v[204:207], v[184:187], v[18:33]
	ds_read_b64_tr_b16 v[136:137], v114 offset:40960
	ds_read_b64_tr_b16 v[138:139], v115 offset:40960
	v_exp_f32_e32 v72, v72
	v_exp_f32_e32 v73, v73
	v_cvt_pk_bf16_f32 v192, v66, v67
	v_mfma_f32_32x32x16_bf16 v[2:17], v[208:211], v[184:187], v[2:17]
	ds_read_b64_tr_b16 v[140:141], v116 offset:40960
	ds_read_b64_tr_b16 v[142:143], v117 offset:40960
	v_cvt_pk_bf16_f32 v193, v68, v69
	v_cvt_pk_bf16_f32 v194, v70, v71
	v_cvt_pk_bf16_f32 v195, v72, v73
	s_waitcnt lgkmcnt(8)
	v_mfma_f32_32x32x16_bf16 v[50:65], v[238:241], v[188:191], v[50:65]
	ds_read_b64_tr_b16 v[204:205], v118 offset:40960
	ds_read_b64_tr_b16 v[206:207], v119 offset:40960
	v_exp_f32_e32 v74, v74
	v_exp_f32_e32 v75, v75
	v_exp_f32_e32 v76, v76
	v_mfma_f32_32x32x16_bf16 v[34:49], v[242:245], v[188:191], v[34:49]
	ds_read_b64_tr_b16 v[208:209], v120 offset:40960
	ds_read_b64_tr_b16 v[210:211], v121 offset:40960
	v_exp_f32_e32 v77, v77
	v_exp_f32_e32 v78, v78
	v_exp_f32_e32 v79, v79
	s_waitcnt lgkmcnt(8)
	v_mfma_f32_32x32x16_bf16 v[18:33], v[246:249], v[188:191], v[18:33]
	ds_read_b64_tr_b16 v[238:239], v114 offset:45056
	ds_read_b64_tr_b16 v[240:241], v115 offset:45056
	v_exp_f32_e32 v80, v80
	v_exp_f32_e32 v81, v81
	v_cvt_pk_bf16_f32 v196, v74, v75
	v_mfma_f32_32x32x16_bf16 v[2:17], v[250:253], v[188:191], v[2:17]
	ds_read_b64_tr_b16 v[242:243], v116 offset:45056
	ds_read_b64_tr_b16 v[244:245], v117 offset:45056
	v_cvt_pk_bf16_f32 v197, v76, v77
	v_cvt_pk_bf16_f32 v198, v78, v79
	v_cvt_pk_bf16_f32 v199, v80, v81
	s_waitcnt lgkmcnt(8)
	v_mfma_f32_32x32x16_bf16 v[50:65], v[136:139], v[192:195], v[50:65]
	ds_read_b64_tr_b16 v[246:247], v118 offset:45056
	ds_read_b64_tr_b16 v[248:249], v119 offset:45056
	v_add_f32_e32 v0, v66, v67
	v_add_f32_e32 v203, v68, v69
	v_add_f32_e32 v0, v0, v70
	v_mfma_f32_32x32x16_bf16 v[34:49], v[140:143], v[192:195], v[34:49]
	ds_read_b64_tr_b16 v[250:251], v120 offset:45056
	ds_read_b64_tr_b16 v[252:253], v121 offset:45056
	v_add_f32_e32 v203, v203, v71
	v_add_f32_e32 v0, v0, v72
	v_add_f32_e32 v203, v203, v73
	s_waitcnt lgkmcnt(8)
	v_mfma_f32_32x32x16_bf16 v[18:33], v[204:207], v[192:195], v[18:33]
	v_add_f32_e32 v0, v0, v203
	v_add_f32_e32 v167, v167, v0
	v_add_f32_e32 v0, v74, v75
	v_mfma_f32_32x32x16_bf16 v[2:17], v[208:211], v[192:195], v[2:17]
	v_add_f32_e32 v203, v76, v77
	v_add_f32_e32 v0, v0, v78
	v_add_f32_e32 v203, v203, v79
	s_waitcnt lgkmcnt(4)
	v_mfma_f32_32x32x16_bf16 v[50:65], v[238:241], v[196:199], v[50:65]
	v_add_f32_e32 v0, v0, v80
	v_add_f32_e32 v203, v203, v81
	v_add_f32_e32 v0, v0, v203
	v_mfma_f32_32x32x16_bf16 v[34:49], v[242:245], v[196:199], v[34:49]
	v_add_f32_e32 v167, v167, v0
	s_waitcnt lgkmcnt(0)
	v_mfma_f32_32x32x16_bf16 v[18:33], v[246:249], v[196:199], v[18:33]
	v_mfma_f32_32x32x16_bf16 v[2:17], v[250:253], v[196:199], v[2:17]
	s_add_i32 s73, s71, 64
	s_lshl_b32 s70, s73, 8
	s_lshl_b32 s73, s73, 9
	s_and_b32 s70, s70, 0x4000
	s_and_b32 s73, s73, 0x10000
	s_or_b32 s73, s73, s70
	v_add_u32_e32 v0, s73, v180
	ds_read_b128 v[136:139], v0
	ds_read_b128 v[140:143], v0 offset:8192
	v_add_u32_e32 v0, s73, v181
	ds_read_b128 v[204:207], v0
	ds_read_b128 v[208:211], v0 offset:8192
	v_add_u32_e32 v0, s73, v178
	ds_read_b128 v[238:241], v0
	ds_read_b128 v[242:245], v0 offset:8192
	v_add_u32_e32 v0, s73, v177
	ds_read_b128 v[246:249], v0
	ds_read_b128 v[250:253], v0 offset:8192

; #define LAS __attribute__((address_space(3)))
; __device__ __forceinline__ void attn_block(LAS unsigned char* lds, const bf16_t* P, bf16_t* mix, int b, int h, int qb, float lam, float outscale, const float* subln) {
;     ...
;     for (int kt = 0; kt < ntiles; ++kt) {
;         __syncthreads();
;         const int buf = kt & 1;
;         if (kt + 1 < ntiles) {
;             const size_t ro = (size_t)(64 * (kt + 1)) * INC;
;             kr0 = *(const u32x4*)(kg + ro + (size_t)srow * INC); kr1 = *(const u32x4*)(kg + ro + (size_t)(srow + 32) * INC);
;             vr0 = *(const u32x4*)(vg + ro + (size_t)srow * INC); vr1 = *(const u32x4*)(vg + ro + (size_t)(srow + 32) * INC);
;         }
;         const int kb = 64 * kt;
;         if (kb <= qw0 + 31) {
;             LAS const unsigned char* Kb = lds + ATT_K0 + buf * 16384;
;             LAS const unsigned char* Vb = lds + ATT_V0 + buf * 16384;
;             f32x16 s0, s1;
; #pragma unroll
;             for (int j = 0; j < 16; ++j) { s0[j] = 0.f; s1[j] = 0.f; }
;             bf16x8 ka[4][2];
; #pragma unroll
;             for (int ks = 0; ks < 4; ++ks) { ka[ks][0] = *(const LAS bf16x8*)(Kb + kbase[ks]); ka[ks][1] = *(const LAS bf16x8*)(Kb + kbase[ks] + 8192); }
;             __builtin_amdgcn_sched_barrier(0);
; #pragma unroll
;             for (int ks = 0; ks < 4; ++ks) {
;                 s0 = __builtin_amdgcn_mfma_f32_32x32x16_bf16(ka[ks][0], qf[ks], s0, 0, 0, 0);
;                 s1 = __builtin_amdgcn_mfma_f32_32x32x16_bf16(ka[ks][1], qf[ks], s1, 0, 0, 0);
;             }
;             if (kb + 63 > qw0) {
; #pragma unroll
;                 for (int j = 0; j < 16; ++j) { const int key = kb + crow(j, hi); if (key > qrow) s0[j] = -INFINITY; if (key + 32 > qrow) s1[j] = -INFINITY; }
;             }
;             float mxa = max3f(s0[0], s1[0], s0[1]), mxb = max3f(s1[1], s0[2], s1[2]), mxc = max3f(s0[3], s1[3], s0[4]), mxd = max3f(s1[4], s0[5], s1[5]);
;             mxa = max3f(mxa, s0[6], s1[6]); mxb = max3f(mxb, s0[7], s1[7]); mxc = max3f(mxc, s0[8], s1[8]); mxd = max3f(mxd, s0[9], s1[9]);
;             mxa = max3f(mxa, s0[10], s1[10]); mxb = max3f(mxb, s0[11], s1[11]); mxc = max3f(mxc, s0[12], s1[12]); mxd = max3f(mxd, s0[13], s1[13]);
;             mxa = max3f(mxa, s0[14], s1[14]); mxb = max3f(mxb, s0[15], s1[15]);
;             float mx = max3f(mxa, mxb, max3f(mxc, mxd, mxd));
.Lat1_T_top:
	s_add_i32 s73, s71, 192
	s_cmp_le_u32 s73, s36
	s_cbranch_scc0 .Lat1_tA_noload
	s_add_i32 s73, s71, 192
	s_lshl_b32 s70, s73, 8
	s_lshl_b32 s73, s73, 9
	s_and_b32 s70, s70, 0x4000
	s_and_b32 s73, s73, 0x10000
	s_or_b32 s73, s73, s70
	s_lshl_b32 s70, s42, 4
	s_and_b32 s70, s70, 0x1c00
	s_add_i32 s73, s73, s70
	s_add_i32 m0, s73, 0x0
	s_nop 0
	global_load_lds_dwordx4 v[134:135], off
	s_add_i32 m0, s73, 0x2000
	s_nop 0
	global_load_lds_dwordx4 v[200:201], off
.Lat1_tA_noload:
	s_lshl_b32 s70, s71, 8
	s_lshl_b32 s72, s71, 9
	s_and_b32 s70, s70, 0x4000
	s_and_b32 s72, s72, 0x10000
	s_or_b32 s72, s72, s70
	s_cmp_gt_u32 s71, s69
	s_cbranch_scc1 .Lat1_tB_skip
	s_waitcnt lgkmcnt(6)
	v_mfma_f32_32x32x16_bf16 v[82:97], v[136:139], v[110:113], v[222:237]
	v_mfma_f32_32x32x16_bf16 v[66:81], v[140:143], v[110:113], v[222:237]
	s_waitcnt lgkmcnt(4)
	v_mfma_f32_32x32x16_bf16 v[82:97], v[204:207], v[106:109], v[82:97]
	v_mfma_f32_32x32x16_bf16 v[66:81], v[208:211], v[106:109], v[66:81]
	s_waitcnt lgkmcnt(2)
	v_mfma_f32_32x32x16_bf16 v[82:97], v[238:241], v[102:105], v[82:97]
	v_mfma_f32_32x32x16_bf16 v[66:81], v[242:245], v[102:105], v[66:81]
	s_waitcnt lgkmcnt(0)
	v_mfma_f32_32x32x16_bf16 v[82:97], v[246:249], v[98:101], v[82:97]
	v_mfma_f32_32x32x16_bf16 v[66:81], v[250:253], v[98:101], v[66:81]
	v_add_u32_e32 v114, s72, v173
	v_add_u32_e32 v115, s72, v174
	v_add_u32_e32 v116, s72, v170
	v_add_u32_e32 v117, s72, v172
	v_add_u32_e32 v118, s72, v168
	v_add_u32_e32 v119, s72, v171
	v_add_u32_e32 v120, s72, v145
	v_add_u32_e32 v121, s72, v169
	s_nop 3
	s_add_i32 s73, s71, 63
	s_cmp_gt_u32 s73, s61
	s_cbranch_scc0 .Lat1_tA_nomask
	v_add_u32_e32 v0, s71, v164
	v_sub_u32_e32 v0, v176, v0
	v_cmp_le_i32_e32 vcc, 0, v0
	s_nop 1
	v_cndmask_b32_e32 v82, v218, v82, vcc
	v_cmp_le_i32_e32 vcc, 1, v0
	s_nop 1
	v_cndmask_b32_e32 v83, v218, v83, vcc
	v_cmp_le_i32_e32 vcc, 2, v0
	s_nop 1
	v_cndmask_b32_e32 v84, v218, v84, vcc
	v_cmp_le_i32_e32 vcc, 3, v0
	s_nop 1
	v_cndmask_b32_e32 v85, v218, v85, vcc
	v_cmp_le_i32_e32 vcc, 8, v0
	s_nop 1
	v_cndmask_b32_e32 v86, v218, v86, vcc
	v_cmp_le_i32_e32 vcc, 9, v0
	s_nop 1
	v_cndmask_b32_e32 v87, v218, v87, vcc
	v_cmp_le_i32_e32 vcc, 10, v0
	s_nop 1
	v_cndmask_b32_e32 v88, v218, v88, vcc
	v_cmp_le_i32_e32 vcc, 11, v0
	s_nop 1
	v_cndmask_b32_e32 v89, v218, v89, vcc
	v_cmp_le_i32_e32 vcc, 16, v0
	s_nop 1
	v_cndmask_b32_e32 v90, v218, v90, vcc
	v_cmp_le_i32_e32 vcc, 17, v0
	s_nop 1
	v_cndmask_b32_e32 v91, v218, v91, vcc
	v_cmp_le_i32_e32 vcc, 18, v0
	s_nop 1
	v_cndmask_b32_e32 v92, v218, v92, vcc
	v_cmp_le_i32_e32 vcc, 19, v0
	s_nop 1
	v_cndmask_b32_e32 v93, v218, v93, vcc
	v_cmp_le_i32_e32 vcc, 24, v0
	s_nop 1
	v_cndmask_b32_e32 v94, v218, v94, vcc
	v_cmp_le_i32_e32 vcc, 25, v0
	s_nop 1
	v_cndmask_b32_e32 v95, v218, v95, vcc
	v_cmp_le_i32_e32 vcc, 26, v0
	s_nop 1
	v_cndmask_b32_e32 v96, v218, v96, vcc
	v_cmp_le_i32_e32 vcc, 27, v0
	s_nop 1
	v_cndmask_b32_e32 v97, v218, v97, vcc
	v_cmp_le_i32_e32 vcc, 32, v0
	s_nop 1
	v_cndmask_b32_e32 v66, v218, v66, vcc
	v_cmp_le_i32_e32 vcc, 33, v0
	s_nop 1
	v_cndmask_b32_e32 v67, v218, v67, vcc
	v_cmp_le_i32_e32 vcc, 34, v0
	s_nop 1
	v_cndmask_b32_e32 v68, v218, v68, vcc
	v_cmp_le_i32_e32 vcc, 35, v0
	s_nop 1
	v_cndmask_b32_e32 v69, v218, v69, vcc
	v_cmp_le_i32_e32 vcc, 40, v0
	s_nop 1
	v_cndmask_b32_e32 v70, v218, v70, vcc
	v_cmp_le_i32_e32 vcc, 41, v0
	s_nop 1
	v_cndmask_b32_e32 v71, v218, v71, vcc
	v_cmp_le_i32_e32 vcc, 42, v0
	s_nop 1
	v_cndmask_b32_e32 v72, v218, v72, vcc
	v_cmp_le_i32_e32 vcc, 43, v0
	s_nop 1
	v_cndmask_b32_e32 v73, v218, v73, vcc
	v_cmp_le_i32_e32 vcc, 48, v0
	s_nop 1
	v_cndmask_b32_e32 v74, v218, v74, vcc
	v_cmp_le_i32_e32 vcc, 49, v0
	s_nop 1
	v_cndmask_b32_e32 v75, v218, v75, vcc
	v_cmp_le_i32_e32 vcc, 50, v0
	s_nop 1
	v_cndmask_b32_e32 v76, v218, v76, vcc
	v_cmp_le_i32_e32 vcc, 51, v0
	s_nop 1
	v_cndmask_b32_e32 v77, v218, v77, vcc
	v_cmp_le_i32_e32 vcc, 56, v0
	s_nop 1
	v_cndmask_b32_e32 v78, v218, v78, vcc
	v_cmp_le_i32_e32 vcc, 57, v0
	s_nop 1
	v_cndmask_b32_e32 v79, v218, v79, vcc
	v_cmp_le_i32_e32 vcc, 58, v0
	s_nop 1
	v_cndmask_b32_e32 v80, v218, v80, vcc
	v_cmp_le_i32_e32 vcc, 59, v0
	s_nop 1
	v_cndmask_b32_e32 v81, v218, v81, vcc
.Lat1_tA_nomask:
	v_max3_f32 v122, v82, v66, v83
	v_max3_f32 v123, v67, v84, v68
	v_max3_f32 v124, v85, v69, v86
	v_max3_f32 v125, v70, v87, v71
	v_max3_f32 v122, v122, v88, v72
	v_max3_f32 v123, v123, v89, v73
	v_max3_f32 v124, v124, v90, v74
	v_max3_f32 v125, v125, v91, v75
	v_max3_f32 v122, v122, v92, v76
	v_max3_f32 v123, v123, v93, v77
	v_max3_f32 v124, v124, v94, v78
	v_max3_f32 v125, v125, v95, v79
	v_max3_f32 v122, v122, v96, v80
	v_max3_f32 v123, v123, v97, v81
	v_max3_f32 v122, v122, v123, v124
	v_max_f32_e32 v122, v122, v125
	v_mov_b32_e32 v203, v122
	s_nop 1
	v_permlane32_swap_b32_e32 v122, v203
	s_nop 1
	v_max_f32_e32 v122, v122, v203
	s_mov_b32 s70, 0
	v_cmp_lt_f32_e32 vcc, 0x41000000, v122
	s_cmp_eq_u32 s71, 0
	s_cbranch_scc1 .Lat1_tA_first
	s_cbranch_vccz .Lat1_tA_norescale
	s_branch .Lat1_tA_rescale

; #define LAS __attribute__((address_space(3)))
; __device__ __forceinline__ s16x4 vtr(LAS const unsigned char* p) { return __builtin_bit_cast(s16x4, __builtin_amdgcn_ds_read_tr16_b64_v4i16((LAS v4i16_t*)p)); }
; __device__ __forceinline__ bf16x8 cat8(s16x4 a, s16x4 b) { return (bf16x8){a[0], a[1], a[2], a[3], b[0], b[1], b[2], b[3]}; }
; __device__ __forceinline__ void attn_block(LAS unsigned char* lds, const bf16_t* P, bf16_t* mix, int b, int h, int qb, float lam, float outscale, const float* subln) {
;     ...
; #pragma unroll
;             for (int s = 0; s < 4; ++s) {
; #pragma unroll
;                 for (int c = 0; c < 4; ++c) {
;                     const s16x4 v0 = vtr(Vb + vbase[c][0] + 4096 * s);
;                     const s16x4 v1 = vtr(Vb + vbase[c][1] + 4096 * s);
;                     o[c] = __builtin_amdgcn_mfma_f32_32x32x16_bf16(cat8(v0, v1), pb[s], o[c], 0, 0, 0);
;                 }
;             }
;         }
;         if (kt + 1 < ntiles) {
;             const int nb = (kt + 1) & 1;
;             *(LAS u32x4*)(lds + ATT_K0 + nb * 16384 + so0) = kr0; *(LAS u32x4*)(lds + ATT_K0 + nb * 16384 + so1) = kr1;
;             *(LAS u32x4*)(lds + ATT_V0 + nb * 16384 + so0) = vr0; *(LAS u32x4*)(lds + ATT_V0 + nb * 16384 + so1) = vr1;
;         }
.Lat1_tB_noload:
	s_cmp_gt_u32 s71, s69
	s_cbranch_scc1 .Lat1_tB_end
	s_waitcnt lgkmcnt(8)
	v_mfma_f32_32x32x16_bf16 v[50:65], v[136:139], v[184:187], v[50:65]
	ds_read_b64_tr_b16 v[246:247], v118 offset:36864
	ds_read_b64_tr_b16 v[248:249], v119 offset:36864
	v_exp_f32_e32 v66, v66
	v_exp_f32_e32 v67, v67
	v_exp_f32_e32 v68, v68
	v_mfma_f32_32x32x16_bf16 v[34:49], v[140:143], v[184:187], v[34:49]
	ds_read_b64_tr_b16 v[250:251], v120 offset:36864
	ds_read_b64_tr_b16 v[252:253], v121 offset:36864
	v_exp_f32_e32 v69, v69
	v_exp_f32_e32 v70, v70
	v_exp_f32_e32 v71, v71
	s_waitcnt lgkmcnt(8)
	v_mfma_f32_32x32x16_bf16 v[18:33], v[204:207], v[184:187], v[18:33]
	ds_read_b64_tr_b16 v[136:137], v114 offset:40960
	ds_read_b64_tr_b16 v[138:139], v115 offset:40960
	v_exp_f32_e32 v72, v72
	v_exp_f32_e32 v73, v73
	v_cvt_pk_bf16_f32 v192, v66, v67
	v_mfma_f32_32x32x16_bf16 v[2:17], v[208:211], v[184:187], v[2:17]
	ds_read_b64_tr_b16 v[140:141], v116 offset:40960
	ds_read_b64_tr_b16 v[142:143], v117 offset:40960
	v_cvt_pk_bf16_f32 v193, v68, v69
	v_cvt_pk_bf16_f32 v194, v70, v71
	v_cvt_pk_bf16_f32 v195, v72, v73
	s_waitcnt lgkmcnt(8)
	v_mfma_f32_32x32x16_bf16 v[50:65], v[238:241], v[188:191], v[50:65]
	ds_read_b64_tr_b16 v[204:205], v118 offset:40960
	ds_read_b64_tr_b16 v[206:207], v119 offset:40960
	v_exp_f32_e32 v74, v74
	v_exp_f32_e32 v75, v75
	v_exp_f32_e32 v76, v76
	v_mfma_f32_32x32x16_bf16 v[34:49], v[242:245], v[188:191], v[34:49]
	ds_read_b64_tr_b16 v[208:209], v120 offset:40960
	ds_read_b64_tr_b16 v[210:211], v121 offset:40960
	v_exp_f32_e32 v77, v77
	v_exp_f32_e32 v78, v78
	v_exp_f32_e32 v79, v79
	s_waitcnt lgkmcnt(8)
	v_mfma_f32_32x32x16_bf16 v[18:33], v[246:249], v[188:191], v[18:33]
	ds_read_b64_tr_b16 v[238:239], v114 offset:45056
	ds_read_b64_tr_b16 v[240:241], v115 offset:45056
	v_exp_f32_e32 v80, v80
	v_exp_f32_e32 v81, v81
	v_cvt_pk_bf16_f32 v196, v74, v75
	v_mfma_f32_32x32x16_bf16 v[2:17], v[250:253], v[188:191], v[2:17]
	ds_read_b64_tr_b16 v[242:243], v116 offset:45056
	ds_read_b64_tr_b16 v[244:245], v117 offset:45056
	v_cvt_pk_bf16_f32 v197, v76, v77
	v_cvt_pk_bf16_f32 v198, v78, v79
	v_cvt_pk_bf16_f32 v199, v80, v81
	s_waitcnt lgkmcnt(8)
	v_mfma_f32_32x32x16_bf16 v[50:65], v[136:139], v[192:195], v[50:65]
	ds_read_b64_tr_b16 v[246:247], v118 offset:45056
	ds_read_b64_tr_b16 v[248:249], v119 offset:45056
	v_add_f32_e32 v0, v66, v67
	v_add_f32_e32 v203, v68, v69
	v_add_f32_e32 v0, v0, v70
	v_mfma_f32_32x32x16_bf16 v[34:49], v[140:143], v[192:195], v[34:49]
	ds_read_b64_tr_b16 v[250:251], v120 offset:45056
	ds_read_b64_tr_b16 v[252:253], v121 offset:45056
	v_add_f32_e32 v203, v203, v71
	v_add_f32_e32 v0, v0, v72
	v_add_f32_e32 v203, v203, v73
	s_waitcnt lgkmcnt(8)
	v_mfma_f32_32x32x16_bf16 v[18:33], v[204:207], v[192:195], v[18:33]
	v_add_f32_e32 v0, v0, v203
	v_add_f32_e32 v167, v167, v0
	v_add_f32_e32 v0, v74, v75
	v_mfma_f32_32x32x16_bf16 v[2:17], v[208:211], v[192:195], v[2:17]
	v_add_f32_e32 v203, v76, v77
	v_add_f32_e32 v0, v0, v78
	v_add_f32_e32 v203, v203, v79
	s_waitcnt lgkmcnt(4)
	v_mfma_f32_32x32x16_bf16 v[50:65], v[238:241], v[196:199], v[50:65]
	v_add_f32_e32 v0, v0, v80
	v_add_f32_e32 v203, v203, v81
	v_add_f32_e32 v0, v0, v203
	v_mfma_f32_32x32x16_bf16 v[34:49], v[242:245], v[196:199], v[34:49]
	v_add_f32_e32 v167, v167, v0
	s_waitcnt lgkmcnt(0)
	v_mfma_f32_32x32x16_bf16 v[18:33], v[246:249], v[196:199], v[18:33]
	v_mfma_f32_32x32x16_bf16 v[2:17], v[250:253], v[196:199], v[2:17]
	s_add_i32 s73, s71, 64
	s_cmp_gt_u32 s73, s36
	s_cbranch_scc1 .Lat1_tB_end
	s_cmp_gt_u32 s73, s69
	s_cbranch_scc1 .Lat1_tB_end
	s_add_i32 s73, s71, 64
	s_lshl_b32 s70, s73, 8
	s_lshl_b32 s73, s73, 9
	s_and_b32 s70, s70, 0x4000
	s_and_b32 s73, s73, 0x10000
	s_or_b32 s73, s73, s70
	v_add_u32_e32 v0, s73, v180
	ds_read_b128 v[136:139], v0
	ds_read_b128 v[140:143], v0 offset:8192
	v_add_u32_e32 v0, s73, v181
	ds_read_b128 v[204:207], v0
	ds_read_b128 v[208:211], v0 offset:8192
	v_add_u32_e32 v0, s73, v178
	ds_read_b128 v[238:241], v0
	ds_read_b128 v[242:245], v0 offset:8192
	v_add_u32_e32 v0, s73, v177
	ds_read_b128 v[246:249], v0
	ds_read_b128 v[250:253], v0 offset:8192

; #define LAS __attribute__((address_space(3)))
; __device__ __forceinline__ void attn_block(LAS unsigned char* lds, const bf16_t* P, bf16_t* mix, int b, int h, int qb, float lam, float outscale, const float* subln) {
;     ...
;     const int tid = tid_, lane = tid & 63, wave = __builtin_amdgcn_readfirstlane(tid >> 6), r32 = lane & 31, hi = lane >> 5;
;     const int comp = wave >> 2, wq = wave & 3;
;     const int rb = b * SEQ, q0 = qb * 128, qw0 = q0 + wq * 32, qrow = qw0 + r32;
;     const float C1 = 0.125f * 1.4426950408889634f;
;     bf16x8 qf[4];
;     { const bf16_t* qp = P + (size_t)(rb + qrow) * INC + COL_AQ + h * 128 + comp * 64 + hi * 8;
; #pragma unroll
;       for (int ks = 0; ks < 4; ++ks) qf[ks] = *(const bf16x8*)(qp + 16 * ks); }
;     const int ntiles = 2 * qb + 2;
;     const int srow = tid >> 4, sch = tid & 15;
;     const bf16_t* kg = P + (size_t)rb * INC + COL_AK + h * 128 + sch * 8;
;     const bf16_t* vg = P + (size_t)rb * INC + COL_AV + h * 128 + sch * 8;
;     const unsigned so0 = off_b(srow, sch), so1 = off_b(srow + 32, sch);
;     u32x4 kr0, kr1, vr0, vr1;
;     kr0 = *(const u32x4*)(kg + (size_t)srow * INC); kr1 = *(const u32x4*)(kg + (size_t)(srow + 32) * INC);
;     vr0 = *(const u32x4*)(vg + (size_t)srow * INC); vr1 = *(const u32x4*)(vg + (size_t)(srow + 32) * INC);
;     *(LAS u32x4*)(lds + ATT_K0 + so0) = kr0; *(LAS u32x4*)(lds + ATT_K0 + so1) = kr1;
;     *(LAS u32x4*)(lds + ATT_V0 + so0) = vr0; *(LAS u32x4*)(lds + ATT_V0 + so1) = vr1;
;     float mrun = -INFINITY, lrun = 0.f;
;     f32x16 o[4];
; #pragma unroll
;     for (int c = 0; c < 4; ++c)
; #pragma unroll
;         for (int j = 0; j < 16; ++j) o[c][j] = 0.f;
;     const int blk = (lane >> 4) & 1, qq = (lane & 15) >> 2, pp = lane & 3;
;     unsigned kbase[4], vbase[4][2];
; #pragma unroll
;     for (int ks = 0; ks < 4; ++ks) kbase[ks] = off_b(r32, comp * 8 + 2 * ks + hi);
; #pragma unroll
;     for (int c = 0; c < 4; ++c)
; #pragma unroll
;         for (int t = 0; t < 2; ++t) vbase[c][t] = off_b(8 * t + 4 * hi + qq, 4 * c + 2 * blk + (pp >> 1)) + 8 * (pp & 1);
; __device__ __forceinline__ void attn_phase(LAS unsigned char* lds, const Params& p, int layer) {
;     ...
;         attn_block(lds, P, mix, b, h, 63 - pr, lam, 1.0f - lambda_init, subln);
.LBB0_116:
	v_mov_b32_e32 v20, v212
	s_barrier
	s_xor_b32 s36, s33, 63
	s_lshl_b32 s69, s36, 7
	v_readfirstlane_b32 s33, v20
	s_lshr_b32 s36, s33, 1
	s_and_b32 s43, s36, 0x60
	v_and_b32_e32 v166, 31, v20
	s_or_b32 s61, s43, s69
	v_readlane_b32 s52, v255, 12
	v_or_b32_e32 v177, s61, v166
	v_readlane_b32 s53, v255, 13
	v_or_b32_e32 v130, s2, v177
	s_movk_i32 s72, 0x3800
	v_mov_b64_e32 v[2:3], s[52:53]
	s_ashr_i32 s42, s33, 8
	v_mad_i64_i32 v[2:3], s[70:71], v130, s72, v[2:3]
	s_lshl_b32 s36, s38, 1
	s_lshl_b32 s70, s42, 6
	v_bfe_u32 v165, v20, 5, 1
	v_lshl_add_u64 v[2:3], v[2:3], 0, s[36:37]
	s_ashr_i32 s71, s70, 31
	v_lshl_add_u64 v[2:3], s[70:71], 1, v[2:3]
	v_lshlrev_b32_e32 v0, 4, v165
	v_and_b32_e32 v22, 15, v20
	v_lshl_add_u64 v[18:19], v[2:3], 0, v[0:1]
	v_ashrrev_i32_e32 v21, 4, v20
	v_lshlrev_b32_e32 v0, 4, v22
	v_lshl_add_u64 v[2:3], s[62:63], 0, v[0:1]
	v_add_u32_e32 v23, 32, v21
	v_mad_i64_i32 v[4:5], s[62:63], v21, s72, v[2:3]
	v_mad_i64_i32 v[6:7], s[62:63], v23, s72, v[2:3]
	global_load_dwordx4 v[2:5], v[4:5], off offset:2048
	s_nop 0
	global_load_dwordx4 v[6:9], v[6:7], off offset:2048
	v_lshl_add_u64 v[10:11], s[64:65], 0, v[0:1]
	v_mad_i64_i32 v[12:13], s[62:63], v21, s72, v[10:11]
	v_mad_i64_i32 v[14:15], s[62:63], v23, s72, v[10:11]
	global_load_dwordx4 v[10:13], v[12:13], off
	s_nop 0
	global_load_dwordx4 v[14:17], v[14:15], off
	s_nop 0
	global_load_dwordx4 v[110:113], v[18:19], off
	global_load_dwordx4 v[106:109], v[18:19], off offset:32
	global_load_dwordx4 v[102:105], v[18:19], off offset:64
	global_load_dwordx4 v[98:101], v[18:19], off offset:96
	v_lshlrev_b32_e32 v27, 2, v21
	v_bfe_u32 v28, v21, 2, 2
	v_and_b32_e32 v27, 12, v27
	v_lshlrev_b32_e32 v30, 8, v23
	v_lshlrev_b32_e32 v23, 2, v23
	v_lshlrev_b32_e32 v18, 2, v20
	v_bfe_u32 v19, v20, 2, 2
	v_lshlrev_b32_e32 v26, 8, v21
	s_lshl_b32 s2, s42, 3
	v_bitop3_b32 v27, v27, v22, v28 bitop3:0x36
	v_and_b32_e32 v23, 12, v23
	v_and_or_b32 v18, v18, 12, v19
	v_lshlrev_b32_e32 v164, 2, v165
	v_or_b32_e32 v34, s2, v165
	v_lshl_or_b32 v182, v27, 4, v26
	v_bitop3_b32 v22, v23, v22, v28 bitop3:0x36
	v_lshrrev_b32_e32 v24, 3, v20
	v_bfe_u32 v25, v20, 1, 1
	v_lshlrev_b32_e32 v29, 8, v166
	v_or_b32_e32 v33, 8, v164
	v_bitop3_b32 v35, s2, v18, v165 bitop3:0x36
	v_bitop3_b32 v23, v34, v18, 2 bitop3:0x36
	v_bitop3_b32 v26, v34, v18, 4 bitop3:0x36
	v_bitop3_b32 v18, v34, v18, 6 bitop3:0x36
	v_lshl_or_b32 v183, v22, 4, v30
	v_add_u32_e32 v22, 0, v182
	v_and_or_b32 v24, v24, 2, v25
	v_lshlrev_b32_e32 v25, 2, v19
	v_or_b32_e32 v31, v164, v19
	v_or_b32_e32 v19, v33, v19
	v_lshl_add_u32 v179, v18, 4, v29
	v_add_u32_e32 v18, 0, v183
	v_lshlrev_b32_e32 v20, 3, v20
	v_and_b32_e32 v20, 8, v20
	v_lshlrev_b32_e32 v31, 8, v31
	s_or_b32 s38, s61, 31
	s_or_b32 s2, s69, 64
	s_add_u32 s50, s39, s50
	s_addc_u32 s51, 0, s51
	v_bitop3_b32 v32, v25, v24, v165 bitop3:0x36
	v_lshlrev_b32_e32 v32, 4, v32
	v_lshl_add_u32 v178, v35, 4, v29
	v_or3_b32 v168, v32, v31, v20
	v_lshl_add_u32 v181, v23, 4, v29
	v_lshl_add_u32 v180, v26, 4, v29
	v_lshlrev_b32_e32 v132, 3, v165
	v_ashrrev_i32_e32 v131, 31, v130
	s_mov_b32 s39, 0
	v_mov_b32_e32 v176, 0xff800000
	s_waitcnt vmcnt(7)
	ds_write_b128 v22, v[2:5]
	s_waitcnt vmcnt(6)
	ds_write_b128 v18, v[6:9]
	s_waitcnt vmcnt(5)
	ds_write_b128 v22, v[10:13] offset:32768
	s_waitcnt vmcnt(4)
	ds_write_b128 v18, v[14:17] offset:32768
	v_lshrrev_b32_e32 v3, 2, v33
	v_lshlrev_b32_e32 v2, 8, v19
	v_bitop3_b32 v4, v3, v24, v25 bitop3:0x36
	v_lshl_add_u32 v4, v4, 4, v2
	v_or_b32_e32 v175, v4, v20
	v_or_b32_e32 v4, 4, v24
	v_bitop3_b32 v5, v25, v4, v165 bitop3:0x36
	v_bitop3_b32 v4, v3, v4, v25 bitop3:0x36
	v_lshl_add_u32 v4, v4, 4, v2
	v_lshlrev_b32_e32 v5, 4, v5
	v_or_b32_e32 v174, v4, v20
	v_or_b32_e32 v4, 8, v24
	v_or3_b32 v172, v5, v31, v20
	v_bitop3_b32 v5, v25, v4, v165 bitop3:0x36
	v_bitop3_b32 v4, v3, v4, v25 bitop3:0x36
	v_lshl_add_u32 v4, v4, 4, v2
	v_or_b32_e32 v173, v4, v20
	v_or_b32_e32 v4, 12, v24
	v_bitop3_b32 v3, v3, v4, v25 bitop3:0x36
	v_lshl_add_u32 v2, v3, 4, v2
	v_lshlrev_b32_e32 v5, 4, v5
	v_or_b32_e32 v171, v2, v20
	v_mov_b64_e32 v[2:3], s[50:51]
	v_or3_b32 v170, v5, v31, v20
	v_bitop3_b32 v5, v25, v4, v165 bitop3:0x36
	v_mad_i64_i32 v[2:3], s[50:51], v21, s72, v[2:3]
	v_lshlrev_b32_e32 v5, 4, v5
	v_lshl_add_u64 v[2:3], v[2:3], 0, v[0:1]
	v_mov_b32_e32 v14, v1
	v_mov_b32_e32 v15, v1
	v_or3_b32 v169, v5, v31, v20
	v_lshl_add_u64 v[134:135], s[48:49], 0, v[2:3]
	v_mov_b32_e32 v0, v1
	v_mov_b32_e32 v2, v1
	v_mov_b32_e32 v3, v1
	v_mov_b32_e32 v4, v1
	v_mov_b32_e32 v5, v1
	v_mov_b32_e32 v6, v1
	v_mov_b32_e32 v7, v1
	v_mov_b32_e32 v8, v1
	v_mov_b32_e32 v9, v1
	v_mov_b32_e32 v10, v1
	v_mov_b32_e32 v11, v1
	v_mov_b32_e32 v12, v1
	v_mov_b32_e32 v13, v1
	v_mov_b64_e32 v[64:65], v[14:15]
	v_mov_b64_e32 v[48:49], v[14:15]
	v_mov_b64_e32 v[32:33], v[14:15]
	v_mov_b64_e32 v[62:63], v[12:13]
	v_mov_b64_e32 v[60:61], v[10:11]
	v_mov_b64_e32 v[58:59], v[8:9]
	v_mov_b64_e32 v[56:57], v[6:7]
	v_mov_b64_e32 v[54:55], v[4:5]
	v_mov_b64_e32 v[52:53], v[2:3]
	v_mov_b64_e32 v[50:51], v[0:1]
	v_mov_b64_e32 v[46:47], v[12:13]
	v_mov_b64_e32 v[44:45], v[10:11]
	v_mov_b64_e32 v[42:43], v[8:9]
	v_mov_b64_e32 v[40:41], v[6:7]
	v_mov_b64_e32 v[38:39], v[4:5]
	v_mov_b64_e32 v[36:37], v[2:3]
	v_mov_b64_e32 v[34:35], v[0:1]
	v_mov_b64_e32 v[30:31], v[12:13]
	v_mov_b64_e32 v[28:29], v[10:11]
	v_mov_b64_e32 v[26:27], v[8:9]
	v_mov_b64_e32 v[24:25], v[6:7]
	v_mov_b64_e32 v[22:23], v[4:5]
	v_mov_b64_e32 v[20:21], v[2:3]
	v_mov_b64_e32 v[18:19], v[0:1]
	v_mov_b64_e32 v[16:17], v[14:15]
	v_mov_b32_e32 v167, 0
	s_mov_b32 s50, 0
	v_mov_b64_e32 v[14:15], v[12:13]
	v_mov_b64_e32 v[12:13], v[10:11]
	v_mov_b64_e32 v[10:11], v[8:9]
	v_mov_b64_e32 v[8:9], v[6:7]
	v_mov_b64_e32 v[6:7], v[4:5]
	v_mov_b64_e32 v[4:5], v[2:3]
	v_mov_b64_e32 v[2:3], v[0:1]
	s_waitcnt vmcnt(0)
	v_lshrrev_b32_e32 v0, 4, v212
	v_and_b32_e32 v203, 3, v0
	v_lshlrev_b32_e32 v203, 2, v203
	v_bfe_u32 v0, v0, 2, 2
	v_or_b32_e32 v0, v203, v0
	v_lshlrev_b32_e32 v0, 4, v0
	v_xor_b32_e32 v134, v134, v0
	s_nop 0
	v_add_co_u32_e32 v200, vcc, 0x70000, v134
	s_nop 1
	v_addc_co_u32_e32 v201, vcc, 0, v135, vcc
	s_nop 0
	s_movk_i32 s62, 0x4000
	s_lshl_b32 s39, s33, 4
	s_and_b32 s39, s39, 0x1c00
	s_add_i32 s62, s62, s39
	s_add_i32 m0, s62, 0x0
	s_nop 0
	global_load_lds_dwordx4 v[134:135], off
	s_add_i32 m0, s62, 0x2000
	s_nop 0
	global_load_lds_dwordx4 v[200:201], off
	s_add_i32 m0, s62, 0x7800
	s_nop 0
	global_load_lds_dwordx4 v[134:135], off offset:2048
	s_add_i32 m0, s62, 0x9800
	s_nop 0
	global_load_lds_dwordx4 v[200:201], off offset:2048
	v_lshl_add_u64 v[134:135], v[134:135], 0, s[40:41]
	v_lshl_add_u64 v[200:201], v[200:201], 0, s[40:41]
	s_cmpk_lt_u32 s2, 0x80
	s_cbranch_scc1 .Lat2_pre_t2
; __device__ __forceinline__ void attn_block(LAS unsigned char* lds, const bf16_t* P, bf16_t* mix, int b, int h, int qb, float lam, float outscale, const float* subln) {
;     ...
;     for (int kt = 0; kt < ntiles; ++kt) {
;         __syncthreads();
;         const int buf = kt & 1;
;         if (kt + 1 < ntiles) {
;             const size_t ro = (size_t)(64 * (kt + 1)) * INC;
;             kr0 = *(const u32x4*)(kg + ro + (size_t)srow * INC); kr1 = *(const u32x4*)(kg + ro + (size_t)(srow + 32) * INC);
;             vr0 = *(const u32x4*)(vg + ro + (size_t)srow * INC); vr1 = *(const u32x4*)(vg + ro + (size_t)(srow + 32) * INC);
;         }
	s_mov_b32 s62, 0x10000
	s_lshl_b32 s39, s33, 4
	s_and_b32 s39, s39, 0x1c00
	s_add_i32 s62, s62, s39
	s_add_i32 m0, s62, 0x0
	s_nop 0
	global_load_lds_dwordx4 v[134:135], off
	s_add_i32 m0, s62, 0x2000
	s_nop 0
	global_load_lds_dwordx4 v[200:201], off
	s_add_i32 m0, s62, 0x7800
	s_nop 0
	global_load_lds_dwordx4 v[134:135], off offset:2048
	s_add_i32 m0, s62, 0x9800
	s_nop 0
	global_load_lds_dwordx4 v[200:201], off offset:2048
	v_lshl_add_u64 v[134:135], v[134:135], 0, s[40:41]
	v_lshl_add_u64 v[200:201], v[200:201], 0, s[40:41]
	v_mov_b32_e32 v222, 0
	v_mov_b32_e32 v223, 0
	v_mov_b32_e32 v224, 0
	v_mov_b32_e32 v225, 0
	v_mov_b32_e32 v226, 0
	v_mov_b32_e32 v227, 0
	v_mov_b32_e32 v228, 0
	v_mov_b32_e32 v229, 0
	v_mov_b32_e32 v230, 0
	v_mov_b32_e32 v231, 0
	v_mov_b32_e32 v232, 0
	v_mov_b32_e32 v233, 0
	v_mov_b32_e32 v234, 0
	v_mov_b32_e32 v235, 0
	v_mov_b32_e32 v236, 0
	v_mov_b32_e32 v237, 0
	s_waitcnt vmcnt(6)
	s_branch .Lat2_pre_done

; #define LAS __attribute__((address_space(3)))
; __device__ __forceinline__ void attn_block(LAS unsigned char* lds, const bf16_t* P, bf16_t* mix, int b, int h, int qb, float lam, float outscale, const float* subln) {
;     ...
;     for (int kt = 0; kt < ntiles; ++kt) {
;         __syncthreads();
;         const int buf = kt & 1;
;         if (kt + 1 < ntiles) {
;             const size_t ro = (size_t)(64 * (kt + 1)) * INC;
;             kr0 = *(const u32x4*)(kg + ro + (size_t)srow * INC); kr1 = *(const u32x4*)(kg + ro + (size_t)(srow + 32) * INC);
;             vr0 = *(const u32x4*)(vg + ro + (size_t)srow * INC); vr1 = *(const u32x4*)(vg + ro + (size_t)(srow + 32) * INC);
;         }
;         const int kb = 64 * kt;
;         if (kb <= qw0 + 31) {
;             LAS const unsigned char* Kb = lds + ATT_K0 + buf * 16384;
;             LAS const unsigned char* Vb = lds + ATT_V0 + buf * 16384;
;             f32x16 s0, s1;
; #pragma unroll
;             for (int j = 0; j < 16; ++j) { s0[j] = 0.f; s1[j] = 0.f; }
;             bf16x8 ka[4][2];
; #pragma unroll
;             for (int ks = 0; ks < 4; ++ks) { ka[ks][0] = *(const LAS bf16x8*)(Kb + kbase[ks]); ka[ks][1] = *(const LAS bf16x8*)(Kb + kbase[ks] + 8192); }
;             __builtin_amdgcn_sched_barrier(0);
; #pragma unroll
;             for (int ks = 0; ks < 4; ++ks) {
;                 s0 = __builtin_amdgcn_mfma_f32_32x32x16_bf16(ka[ks][0], qf[ks], s0, 0, 0, 0);
;                 s1 = __builtin_amdgcn_mfma_f32_32x32x16_bf16(ka[ks][1], qf[ks], s1, 0, 0, 0);
;             }
;             if (kb + 63 > qw0) {
; #pragma unroll
;                 for (int j = 0; j < 16; ++j) { const int key = kb + crow(j, hi); if (key > qrow) s0[j] = -INFINITY; if (key + 32 > qrow) s1[j] = -INFINITY; }
;             }
;             float mxa = max3f(s0[0], s1[0], s0[1]), mxb = max3f(s1[1], s0[2], s1[2]), mxc = max3f(s0[3], s1[3], s0[4]), mxd = max3f(s1[4], s0[5], s1[5]);
;             mxa = max3f(mxa, s0[6], s1[6]); mxb = max3f(mxb, s0[7], s1[7]); mxc = max3f(mxc, s0[8], s1[8]); mxd = max3f(mxd, s0[9], s1[9]);
;             mxa = max3f(mxa, s0[10], s1[10]); mxb = max3f(mxb, s0[11], s1[11]); mxc = max3f(mxc, s0[12], s1[12]); mxd = max3f(mxd, s0[13], s1[13]);
;             mxa = max3f(mxa, s0[14], s1[14]); mxb = max3f(mxb, s0[15], s1[15]);
;             float mx = max3f(mxa, mxb, max3f(mxc, mxd, mxd));
.Lat2_pre_done:
	s_waitcnt lgkmcnt(0)
	s_barrier
	ds_read_b128 v[136:139], v178
	ds_read_b128 v[140:143], v178 offset:8192
	ds_read_b128 v[204:207], v181
	ds_read_b128 v[208:211], v181 offset:8192
	ds_read_b128 v[238:241], v180
	ds_read_b128 v[242:245], v180 offset:8192
	ds_read_b128 v[246:249], v179
	ds_read_b128 v[250:253], v179 offset:8192
	s_add_i32 s62, s50, 384
	s_cmp_le_u32 s62, s2
	s_cbranch_scc0 .Lat2_U_none
	v_add_u32_e32 v114, 0x10000, v168
	v_add_u32_e32 v115, 0x10000, v175
	v_add_u32_e32 v116, 0x10000, v172
	v_add_u32_e32 v117, 0x10000, v174
	v_add_u32_e32 v118, 0x10000, v170
	v_add_u32_e32 v119, 0x10000, v173
	v_add_u32_e32 v120, 0x10000, v169
	v_add_u32_e32 v121, 0x10000, v171
	v_add_u32_e32 v126, 0x10000, v178
	v_add_u32_e32 v127, 0x10000, v181
	v_add_u32_e32 v128, 0x10000, v180
	v_add_u32_e32 v129, 0x10000, v179
	s_lshl_b32 s39, s33, 4
	s_and_b32 s39, s39, 0x1c00
	s_mov_b32 s62, s39
.Lat2_U_top:
	s_add_i32 m0, s62, 0x14000
	s_nop 0
	global_load_lds_dwordx4 v[134:135], off
	s_add_i32 m0, s62, 0x16000
	s_nop 0
	global_load_lds_dwordx4 v[200:201], off
	s_waitcnt lgkmcnt(6)
	v_mfma_f32_32x32x16_bf16 v[82:97], v[136:139], v[110:113], v[222:237]
	v_mfma_f32_32x32x16_bf16 v[66:81], v[140:143], v[110:113], v[222:237]
	s_waitcnt lgkmcnt(4)
	v_mfma_f32_32x32x16_bf16 v[82:97], v[204:207], v[106:109], v[82:97]
	v_mfma_f32_32x32x16_bf16 v[66:81], v[208:211], v[106:109], v[66:81]
	s_waitcnt lgkmcnt(2)
	v_mfma_f32_32x32x16_bf16 v[82:97], v[238:241], v[102:105], v[82:97]
	v_mfma_f32_32x32x16_bf16 v[66:81], v[242:245], v[102:105], v[66:81]
	s_waitcnt lgkmcnt(0)
	v_mfma_f32_32x32x16_bf16 v[82:97], v[246:249], v[98:101], v[82:97]
	v_mfma_f32_32x32x16_bf16 v[66:81], v[250:253], v[98:101], v[66:81]
	ds_read_b64_tr_b16 v[136:137], v168 offset:32768
	ds_read_b64_tr_b16 v[138:139], v175 offset:32768
	ds_read_b64_tr_b16 v[140:141], v172 offset:32768
	ds_read_b64_tr_b16 v[142:143], v174 offset:32768
	ds_read_b64_tr_b16 v[204:205], v170 offset:32768
	ds_read_b64_tr_b16 v[206:207], v173 offset:32768
	ds_read_b64_tr_b16 v[208:209], v169 offset:32768
	ds_read_b64_tr_b16 v[210:211], v171 offset:32768
	ds_read_b64_tr_b16 v[238:239], v168 offset:36864
	ds_read_b64_tr_b16 v[240:241], v175 offset:36864
	ds_read_b64_tr_b16 v[242:243], v172 offset:36864
	ds_read_b64_tr_b16 v[244:245], v174 offset:36864
	v_max3_f32 v122, v82, v66, v83
	v_max3_f32 v123, v67, v84, v68
	v_max3_f32 v124, v85, v69, v86
	v_max3_f32 v125, v70, v87, v71
	v_max3_f32 v122, v122, v88, v72
	v_max3_f32 v123, v123, v89, v73
	v_max3_f32 v124, v124, v90, v74
	v_max3_f32 v125, v125, v91, v75
	v_max3_f32 v122, v122, v92, v76
	v_max3_f32 v123, v123, v93, v77
	v_max3_f32 v124, v124, v94, v78
	v_max3_f32 v125, v125, v95, v79
	v_max3_f32 v122, v122, v96, v80
	v_max3_f32 v123, v123, v97, v81
	v_max3_f32 v122, v122, v123, v124
	v_max_f32_e32 v122, v122, v125
	v_mov_b32_e32 v203, v122
	s_nop 1
	v_permlane32_swap_b32_e32 v122, v203
	s_nop 1
	v_max_f32_e32 v122, v122, v203
	s_mov_b32 s39, 0
	v_cmp_lt_f32_e32 vcc, 0x41000000, v122
	s_cmp_eq_u32 s50, 0
	s_cbranch_scc1 .Lat2_u0_first
	s_cbranch_vccz .Lat2_u0_norescale
	s_branch .Lat2_u0_rescale

; __device__ __forceinline__ unsigned pk2(float lo, float hi) { f32x2 v = {lo, hi}; bf16x2_t b = __builtin_convertvector(v, bf16x2_t); return __builtin_bit_cast(unsigned, b); }
; __device__ __forceinline__ s16x4 vtr(LAS const unsigned char* p) { return __builtin_bit_cast(s16x4, __builtin_amdgcn_ds_read_tr16_b64_v4i16((LAS v4i16_t*)p)); }
; __device__ __forceinline__ bf16x8 cat8(s16x4 a, s16x4 b) { return (bf16x8){a[0], a[1], a[2], a[3], b[0], b[1], b[2], b[3]}; }
; __device__ __forceinline__ void attn_block(LAS unsigned char* lds, const bf16_t* P, bf16_t* mix, int b, int h, int qb, float lam, float outscale, const float* subln) {
;     ...
;             if (__any(mx > mrun + 8.0f)) {
;                 const float mnew = fmaxf(mrun, mx); const float alpha = __builtin_amdgcn_exp2f(mrun - mnew); mrun = mnew; lrun *= alpha;
; #pragma unroll
;                 for (int c = 0; c < 4; ++c)
; #pragma unroll
;                     for (int j = 0; j < 16; ++j) o[c][j] *= alpha;
;             }
; #pragma unroll
;             for (int j = 0; j < 16; ++j) { s0[j] = __builtin_amdgcn_exp2f(s0[j] - mrun); s1[j] = __builtin_amdgcn_exp2f(s1[j] - mrun); }
;             float ps0 = 0.f, ps1 = 0.f, ps2 = 0.f, ps3 = 0.f;
; #pragma unroll
;             for (int j = 0; j < 16; j += 2) { ps0 += s0[j]; ps1 += s1[j]; ps2 += s0[j + 1]; ps3 += s1[j + 1]; }
;             lrun += (ps0 + ps1) + (ps2 + ps3);
;             bf16x8 pb[4];
; #pragma unroll
;             for (int s2 = 0; s2 < 2; ++s2) {
;                 u32x4 w0, w1;
;                 w0.x = pk2(s0[8 * s2 + 0], s0[8 * s2 + 1]); w0.y = pk2(s0[8 * s2 + 2], s0[8 * s2 + 3]); w0.z = pk2(s0[8 * s2 + 4], s0[8 * s2 + 5]); w0.w = pk2(s0[8 * s2 + 6], s0[8 * s2 + 7]);
;                 w1.x = pk2(s1[8 * s2 + 0], s1[8 * s2 + 1]); w1.y = pk2(s1[8 * s2 + 2], s1[8 * s2 + 3]); w1.z = pk2(s1[8 * s2 + 4], s1[8 * s2 + 5]); w1.w = pk2(s1[8 * s2 + 6], s1[8 * s2 + 7]);
;                 pb[s2] = __builtin_bit_cast(bf16x8, w0); pb[2 + s2] = __builtin_bit_cast(bf16x8, w1);
;             }
; #pragma unroll
;             for (int s = 0; s < 4; ++s) {
; #pragma unroll
;                 for (int c = 0; c < 4; ++c) {
;                     const s16x4 v0 = vtr(Vb + vbase[c][0] + 4096 * s);
;                     const s16x4 v1 = vtr(Vb + vbase[c][1] + 4096 * s);
;                     o[c] = __builtin_amdgcn_mfma_f32_32x32x16_bf16(cat8(v0, v1), pb[s], o[c], 0, 0, 0);
.Lat2_u0_rescale:
	v_max_f32_e32 v0, s39, v122
	v_sub_f32_e32 v203, 0, v0
	v_min_f32_e32 v203, 0x42fc0000, v203
	v_exp_f32_e32 v203, v203
	v_sub_f32_e32 v82, v82, v0
	v_sub_f32_e32 v83, v83, v0
	v_sub_f32_e32 v84, v84, v0
	v_sub_f32_e32 v85, v85, v0
	v_sub_f32_e32 v86, v86, v0
	v_sub_f32_e32 v87, v87, v0
	v_sub_f32_e32 v88, v88, v0
	v_sub_f32_e32 v89, v89, v0
	v_sub_f32_e32 v90, v90, v0
	v_sub_f32_e32 v91, v91, v0
	v_sub_f32_e32 v92, v92, v0
	v_sub_f32_e32 v93, v93, v0
	v_sub_f32_e32 v94, v94, v0
	v_sub_f32_e32 v95, v95, v0
	v_sub_f32_e32 v96, v96, v0
	v_sub_f32_e32 v97, v97, v0
	v_sub_f32_e32 v66, v66, v0
	v_sub_f32_e32 v67, v67, v0
	v_sub_f32_e32 v68, v68, v0
	v_sub_f32_e32 v69, v69, v0
	v_sub_f32_e32 v70, v70, v0
	v_sub_f32_e32 v71, v71, v0
	v_sub_f32_e32 v72, v72, v0
	v_sub_f32_e32 v73, v73, v0
	v_sub_f32_e32 v74, v74, v0
	v_sub_f32_e32 v75, v75, v0
	v_sub_f32_e32 v76, v76, v0
	v_sub_f32_e32 v77, v77, v0
	v_sub_f32_e32 v78, v78, v0
	v_sub_f32_e32 v79, v79, v0
	v_sub_f32_e32 v80, v80, v0
	v_sub_f32_e32 v81, v81, v0
	v_sub_f32_e32 v222, v222, v0
	v_mov_b32_e32 v223, v222
	v_mov_b32_e32 v224, v222
	v_mov_b32_e32 v225, v222
	v_mov_b32_e32 v226, v222
	v_mov_b32_e32 v227, v222
	v_mov_b32_e32 v228, v222
	v_mov_b32_e32 v229, v222
	v_mov_b32_e32 v230, v222
	v_mov_b32_e32 v231, v222
	v_mov_b32_e32 v232, v222
	v_mov_b32_e32 v233, v222
	v_mov_b32_e32 v234, v222
	v_mov_b32_e32 v235, v222
	v_mov_b32_e32 v236, v222
	v_mov_b32_e32 v237, v222
	v_mul_f32_e32 v50, v50, v203
	v_mul_f32_e32 v51, v51, v203
	v_mul_f32_e32 v52, v52, v203
	v_mul_f32_e32 v53, v53, v203
	v_mul_f32_e32 v54, v54, v203
	v_mul_f32_e32 v55, v55, v203
	v_mul_f32_e32 v56, v56, v203
	v_mul_f32_e32 v57, v57, v203
	v_mul_f32_e32 v58, v58, v203
	v_mul_f32_e32 v59, v59, v203
	v_mul_f32_e32 v60, v60, v203
	v_mul_f32_e32 v61, v61, v203
	v_mul_f32_e32 v62, v62, v203
	v_mul_f32_e32 v63, v63, v203
	v_mul_f32_e32 v64, v64, v203
	v_mul_f32_e32 v65, v65, v203
	v_mul_f32_e32 v34, v34, v203
	v_mul_f32_e32 v35, v35, v203
	v_mul_f32_e32 v36, v36, v203
	v_mul_f32_e32 v37, v37, v203
	v_mul_f32_e32 v38, v38, v203
	v_mul_f32_e32 v39, v39, v203
	v_mul_f32_e32 v40, v40, v203
	v_mul_f32_e32 v41, v41, v203
	v_mul_f32_e32 v42, v42, v203
	v_mul_f32_e32 v43, v43, v203
	v_mul_f32_e32 v44, v44, v203
	v_mul_f32_e32 v45, v45, v203
	v_mul_f32_e32 v46, v46, v203
	v_mul_f32_e32 v47, v47, v203
	v_mul_f32_e32 v48, v48, v203
	v_mul_f32_e32 v49, v49, v203
	v_mul_f32_e32 v18, v18, v203
	v_mul_f32_e32 v19, v19, v203
	v_mul_f32_e32 v20, v20, v203
	v_mul_f32_e32 v21, v21, v203
	v_mul_f32_e32 v22, v22, v203
	v_mul_f32_e32 v23, v23, v203
	v_mul_f32_e32 v24, v24, v203
	v_mul_f32_e32 v25, v25, v203
	v_mul_f32_e32 v26, v26, v203
	v_mul_f32_e32 v27, v27, v203
	v_mul_f32_e32 v28, v28, v203
	v_mul_f32_e32 v29, v29, v203
	v_mul_f32_e32 v30, v30, v203
	v_mul_f32_e32 v31, v31, v203
	v_mul_f32_e32 v32, v32, v203
	v_mul_f32_e32 v33, v33, v203
	v_mul_f32_e32 v2, v2, v203
	v_mul_f32_e32 v3, v3, v203
	v_mul_f32_e32 v4, v4, v203
	v_mul_f32_e32 v5, v5, v203
	v_mul_f32_e32 v6, v6, v203
	v_mul_f32_e32 v7, v7, v203
	v_mul_f32_e32 v8, v8, v203
	v_mul_f32_e32 v9, v9, v203
	v_mul_f32_e32 v10, v10, v203
	v_mul_f32_e32 v11, v11, v203
	v_mul_f32_e32 v12, v12, v203
	v_mul_f32_e32 v13, v13, v203
	v_mul_f32_e32 v14, v14, v203
	v_mul_f32_e32 v15, v15, v203
	v_mul_f32_e32 v16, v16, v203
	v_mul_f32_e32 v17, v17, v203
	v_mul_f32_e32 v167, v167, v203
.Lat2_u0_norescale:
	v_exp_f32_e32 v82, v82
	v_exp_f32_e32 v83, v83
	v_exp_f32_e32 v84, v84
	v_exp_f32_e32 v85, v85
	v_exp_f32_e32 v86, v86
	v_exp_f32_e32 v87, v87
	v_exp_f32_e32 v88, v88
	v_exp_f32_e32 v89, v89
	v_exp_f32_e32 v90, v90
	v_exp_f32_e32 v91, v91
	v_exp_f32_e32 v92, v92
	v_exp_f32_e32 v93, v93
	v_exp_f32_e32 v94, v94
	v_exp_f32_e32 v95, v95
	v_exp_f32_e32 v96, v96
	v_exp_f32_e32 v97, v97
	v_cvt_pk_bf16_f32 v184, v82, v83
	v_cvt_pk_bf16_f32 v185, v84, v85
	v_cvt_pk_bf16_f32 v186, v86, v87
	v_cvt_pk_bf16_f32 v187, v88, v89
	v_cvt_pk_bf16_f32 v188, v90, v91
	v_cvt_pk_bf16_f32 v189, v92, v93
	v_cvt_pk_bf16_f32 v190, v94, v95
	v_cvt_pk_bf16_f32 v191, v96, v97
	v_add_f32_e32 v122, v82, v83
	v_add_f32_e32 v123, v84, v85
	v_add_f32_e32 v122, v122, v86
	v_add_f32_e32 v123, v123, v87
	v_add_f32_e32 v122, v122, v88
	v_add_f32_e32 v123, v123, v89
	v_add_f32_e32 v122, v122, v123
	v_add_f32_e32 v167, v167, v122
	v_add_f32_e32 v124, v90, v91
	v_add_f32_e32 v125, v92, v93
	v_add_f32_e32 v124, v124, v94
	v_add_f32_e32 v125, v125, v95
	v_add_f32_e32 v124, v124, v96
	v_add_f32_e32 v125, v125, v97
	v_add_f32_e32 v124, v124, v125
	v_add_f32_e32 v167, v167, v124
	s_add_i32 m0, s62, 0x1b800
	s_nop 0
	global_load_lds_dwordx4 v[134:135], off offset:2048
	s_add_i32 m0, s62, 0x1d800
	s_nop 0
	global_load_lds_dwordx4 v[200:201], off offset:2048
	v_lshl_add_u64 v[134:135], v[134:135], 0, s[40:41]
	v_lshl_add_u64 v[200:201], v[200:201], 0, s[40:41]
	s_waitcnt lgkmcnt(8)
	v_mfma_f32_32x32x16_bf16 v[50:65], v[136:139], v[184:187], v[50:65]
	ds_read_b64_tr_b16 v[246:247], v170 offset:36864
	ds_read_b64_tr_b16 v[248:249], v173 offset:36864
	v_exp_f32_e32 v66, v66
	v_exp_f32_e32 v67, v67
	v_exp_f32_e32 v68, v68
	v_mfma_f32_32x32x16_bf16 v[34:49], v[140:143], v[184:187], v[34:49]
	ds_read_b64_tr_b16 v[250:251], v169 offset:36864
	ds_read_b64_tr_b16 v[252:253], v171 offset:36864
	v_exp_f32_e32 v69, v69
	v_exp_f32_e32 v70, v70
	v_exp_f32_e32 v71, v71
	s_waitcnt lgkmcnt(8)
; #define LAS __attribute__((address_space(3)))
; __device__ __forceinline__ void attn_block(LAS unsigned char* lds, const bf16_t* P, bf16_t* mix, int b, int h, int qb, float lam, float outscale, const float* subln) {
;     ...
;         if (kt + 1 < ntiles) {
;             const size_t ro = (size_t)(64 * (kt + 1)) * INC;
;             kr0 = *(const u32x4*)(kg + ro + (size_t)srow * INC); kr1 = *(const u32x4*)(kg + ro + (size_t)(srow + 32) * INC);
;             vr0 = *(const u32x4*)(vg + ro + (size_t)srow * INC); vr1 = *(const u32x4*)(vg + ro + (size_t)(srow + 32) * INC);
;         }
;         const int kb = 64 * kt;
;         if (kb <= qw0 + 31) {
;             LAS const unsigned char* Kb = lds + ATT_K0 + buf * 16384;
;             LAS const unsigned char* Vb = lds + ATT_V0 + buf * 16384;
;             f32x16 s0, s1;
; #pragma unroll
;             for (int j = 0; j < 16; ++j) { s0[j] = 0.f; s1[j] = 0.f; }
;             bf16x8 ka[4][2];
; #pragma unroll
;             for (int ks = 0; ks < 4; ++ks) { ka[ks][0] = *(const LAS bf16x8*)(Kb + kbase[ks]); ka[ks][1] = *(const LAS bf16x8*)(Kb + kbase[ks] + 8192); }
;             __builtin_amdgcn_sched_barrier(0);
; #pragma unroll
;             for (int ks = 0; ks < 4; ++ks) {
;                 s0 = __builtin_amdgcn_mfma_f32_32x32x16_bf16(ka[ks][0], qf[ks], s0, 0, 0, 0);
;                 s1 = __builtin_amdgcn_mfma_f32_32x32x16_bf16(ka[ks][1], qf[ks], s1, 0, 0, 0);
;             }
;             if (kb + 63 > qw0) {
; #pragma unroll
;                 for (int j = 0; j < 16; ++j) { const int key = kb + crow(j, hi); if (key > qrow) s0[j] = -INFINITY; if (key + 32 > qrow) s1[j] = -INFINITY; }
;             }
;             float mxa = max3f(s0[0], s1[0], s0[1]), mxb = max3f(s1[1], s0[2], s1[2]), mxc = max3f(s0[3], s1[3], s0[4]), mxd = max3f(s1[4], s0[5], s1[5]);
;             mxa = max3f(mxa, s0[6], s1[6]); mxb = max3f(mxb, s0[7], s1[7]); mxc = max3f(mxc, s0[8], s1[8]); mxd = max3f(mxd, s0[9], s1[9]);
;     ...
;             for (int s = 0; s < 4; ++s) {
; #pragma unroll
;                 for (int c = 0; c < 4; ++c) {
;                     const s16x4 v0 = vtr(Vb + vbase[c][0] + 4096 * s);
;                     const s16x4 v1 = vtr(Vb + vbase[c][1] + 4096 * s);
;                     o[c] = __builtin_amdgcn_mfma_f32_32x32x16_bf16(cat8(v0, v1), pb[s], o[c], 0, 0, 0);
;                 }
;             }
	v_mfma_f32_32x32x16_bf16 v[18:33], v[204:207], v[184:187], v[18:33]
	ds_read_b64_tr_b16 v[136:137], v168 offset:40960
	ds_read_b64_tr_b16 v[138:139], v175 offset:40960
	v_exp_f32_e32 v72, v72
	v_exp_f32_e32 v73, v73
	v_cvt_pk_bf16_f32 v192, v66, v67
	v_mfma_f32_32x32x16_bf16 v[2:17], v[208:211], v[184:187], v[2:17]
	ds_read_b64_tr_b16 v[140:141], v172 offset:40960
	ds_read_b64_tr_b16 v[142:143], v174 offset:40960
	v_cvt_pk_bf16_f32 v193, v68, v69
	v_cvt_pk_bf16_f32 v194, v70, v71
	v_cvt_pk_bf16_f32 v195, v72, v73
	s_waitcnt lgkmcnt(8)
	v_mfma_f32_32x32x16_bf16 v[50:65], v[238:241], v[188:191], v[50:65]
	ds_read_b64_tr_b16 v[204:205], v170 offset:40960
	ds_read_b64_tr_b16 v[206:207], v173 offset:40960
	v_exp_f32_e32 v74, v74
	v_exp_f32_e32 v75, v75
	v_exp_f32_e32 v76, v76
	v_mfma_f32_32x32x16_bf16 v[34:49], v[242:245], v[188:191], v[34:49]
	ds_read_b64_tr_b16 v[208:209], v169 offset:40960
	ds_read_b64_tr_b16 v[210:211], v171 offset:40960
	v_exp_f32_e32 v77, v77
	v_exp_f32_e32 v78, v78
	v_exp_f32_e32 v79, v79
	s_waitcnt lgkmcnt(8)
	v_mfma_f32_32x32x16_bf16 v[18:33], v[246:249], v[188:191], v[18:33]
	ds_read_b64_tr_b16 v[238:239], v168 offset:45056
	ds_read_b64_tr_b16 v[240:241], v175 offset:45056
	v_exp_f32_e32 v80, v80
	v_exp_f32_e32 v81, v81
	v_cvt_pk_bf16_f32 v196, v74, v75
	v_mfma_f32_32x32x16_bf16 v[2:17], v[250:253], v[188:191], v[2:17]
	ds_read_b64_tr_b16 v[242:243], v172 offset:45056
	ds_read_b64_tr_b16 v[244:245], v174 offset:45056
	v_cvt_pk_bf16_f32 v197, v76, v77
	v_cvt_pk_bf16_f32 v198, v78, v79
	v_cvt_pk_bf16_f32 v199, v80, v81
	s_waitcnt lgkmcnt(8)
	v_mfma_f32_32x32x16_bf16 v[50:65], v[136:139], v[192:195], v[50:65]
	ds_read_b64_tr_b16 v[246:247], v170 offset:45056
	ds_read_b64_tr_b16 v[248:249], v173 offset:45056
	v_add_f32_e32 v0, v66, v67
	v_add_f32_e32 v203, v68, v69
	v_add_f32_e32 v0, v0, v70
	v_mfma_f32_32x32x16_bf16 v[34:49], v[140:143], v[192:195], v[34:49]
	ds_read_b64_tr_b16 v[250:251], v169 offset:45056
	ds_read_b64_tr_b16 v[252:253], v171 offset:45056
	v_add_f32_e32 v203, v203, v71
	v_add_f32_e32 v0, v0, v72
	v_add_f32_e32 v203, v203, v73
	s_waitcnt lgkmcnt(8)
	v_mfma_f32_32x32x16_bf16 v[18:33], v[204:207], v[192:195], v[18:33]
	v_add_f32_e32 v0, v0, v203
	v_add_f32_e32 v167, v167, v0
	v_add_f32_e32 v0, v74, v75
	v_mfma_f32_32x32x16_bf16 v[2:17], v[208:211], v[192:195], v[2:17]
	v_add_f32_e32 v203, v76, v77
	v_add_f32_e32 v0, v0, v78
	v_add_f32_e32 v203, v203, v79
	s_waitcnt lgkmcnt(4)
	v_mfma_f32_32x32x16_bf16 v[50:65], v[238:241], v[196:199], v[50:65]
	v_add_f32_e32 v0, v0, v80
	v_add_f32_e32 v203, v203, v81
	v_add_f32_e32 v0, v0, v203
	v_mfma_f32_32x32x16_bf16 v[34:49], v[242:245], v[196:199], v[34:49]
	v_add_f32_e32 v167, v167, v0
	s_waitcnt lgkmcnt(0)
	v_mfma_f32_32x32x16_bf16 v[18:33], v[246:249], v[196:199], v[18:33]
	v_mfma_f32_32x32x16_bf16 v[2:17], v[250:253], v[196:199], v[2:17]
	ds_read_b128 v[136:139], v178 offset:16384
	ds_read_b128 v[140:143], v178 offset:24576
	ds_read_b128 v[204:207], v181 offset:16384
	ds_read_b128 v[208:211], v181 offset:24576
	ds_read_b128 v[238:241], v180 offset:16384
	ds_read_b128 v[242:245], v180 offset:24576
	ds_read_b128 v[246:249], v179 offset:16384
	ds_read_b128 v[250:253], v179 offset:24576
	s_waitcnt vmcnt(6)
	s_add_i32 s50, s50, 64
	s_barrier
	s_add_i32 m0, s62, 0x0
	s_nop 0
	global_load_lds_dwordx4 v[134:135], off
	s_add_i32 m0, s62, 0x2000
	s_nop 0
	global_load_lds_dwordx4 v[200:201], off
	s_waitcnt lgkmcnt(6)
	v_mfma_f32_32x32x16_bf16 v[82:97], v[136:139], v[110:113], v[222:237]
	v_mfma_f32_32x32x16_bf16 v[66:81], v[140:143], v[110:113], v[222:237]
	s_waitcnt lgkmcnt(4)
	v_mfma_f32_32x32x16_bf16 v[82:97], v[204:207], v[106:109], v[82:97]
	v_mfma_f32_32x32x16_bf16 v[66:81], v[208:211], v[106:109], v[66:81]
	s_waitcnt lgkmcnt(2)
	v_mfma_f32_32x32x16_bf16 v[82:97], v[238:241], v[102:105], v[82:97]
	v_mfma_f32_32x32x16_bf16 v[66:81], v[242:245], v[102:105], v[66:81]
	s_waitcnt lgkmcnt(0)
	v_mfma_f32_32x32x16_bf16 v[82:97], v[246:249], v[98:101], v[82:97]
	v_mfma_f32_32x32x16_bf16 v[66:81], v[250:253], v[98:101], v[66:81]
	ds_read_b64_tr_b16 v[136:137], v168 offset:49152
	ds_read_b64_tr_b16 v[138:139], v175 offset:49152
	ds_read_b64_tr_b16 v[140:141], v172 offset:49152
	ds_read_b64_tr_b16 v[142:143], v174 offset:49152
	ds_read_b64_tr_b16 v[204:205], v170 offset:49152
	ds_read_b64_tr_b16 v[206:207], v173 offset:49152
	ds_read_b64_tr_b16 v[208:209], v169 offset:49152
	ds_read_b64_tr_b16 v[210:211], v171 offset:49152
	ds_read_b64_tr_b16 v[238:239], v168 offset:53248
	ds_read_b64_tr_b16 v[240:241], v175 offset:53248
	ds_read_b64_tr_b16 v[242:243], v172 offset:53248
	ds_read_b64_tr_b16 v[244:245], v174 offset:53248
	v_max3_f32 v122, v82, v66, v83
	v_max3_f32 v123, v67, v84, v68
	v_max3_f32 v124, v85, v69, v86
	v_max3_f32 v125, v70, v87, v71
	v_max3_f32 v122, v122, v88, v72
	v_max3_f32 v123, v123, v89, v73
	v_max3_f32 v124, v124, v90, v74
	v_max3_f32 v125, v125, v91, v75
	v_max3_f32 v122, v122, v92, v76
	v_max3_f32 v123, v123, v93, v77
	v_max3_f32 v124, v124, v94, v78
	v_max3_f32 v125, v125, v95, v79
	v_max3_f32 v122, v122, v96, v80
	v_max3_f32 v123, v123, v97, v81
	v_max3_f32 v122, v122, v123, v124
	v_max_f32_e32 v122, v122, v125
	v_mov_b32_e32 v203, v122
	s_nop 1
	v_permlane32_swap_b32_e32 v122, v203
	s_nop 1
	v_max_f32_e32 v122, v122, v203
	s_mov_b32 s39, 0
	v_cmp_lt_f32_e32 vcc, 0x41000000, v122
	s_cmp_eq_u32 s50, 0
	s_cbranch_scc1 .Lat2_u1_first
	s_cbranch_vccz .Lat2_u1_norescale
	s_branch .Lat2_u1_rescale

; __device__ __forceinline__ unsigned pk2(float lo, float hi) { f32x2 v = {lo, hi}; bf16x2_t b = __builtin_convertvector(v, bf16x2_t); return __builtin_bit_cast(unsigned, b); }
; __device__ __forceinline__ s16x4 vtr(LAS const unsigned char* p) { return __builtin_bit_cast(s16x4, __builtin_amdgcn_ds_read_tr16_b64_v4i16((LAS v4i16_t*)p)); }
; __device__ __forceinline__ bf16x8 cat8(s16x4 a, s16x4 b) { return (bf16x8){a[0], a[1], a[2], a[3], b[0], b[1], b[2], b[3]}; }
; __device__ __forceinline__ void attn_block(LAS unsigned char* lds, const bf16_t* P, bf16_t* mix, int b, int h, int qb, float lam, float outscale, const float* subln) {
;     ...
;             for (int j = 0; j < 16; ++j) { s0[j] = __builtin_amdgcn_exp2f(s0[j] - mrun); s1[j] = __builtin_amdgcn_exp2f(s1[j] - mrun); }
;             float ps0 = 0.f, ps1 = 0.f, ps2 = 0.f, ps3 = 0.f;
; #pragma unroll
;             for (int j = 0; j < 16; j += 2) { ps0 += s0[j]; ps1 += s1[j]; ps2 += s0[j + 1]; ps3 += s1[j + 1]; }
;             lrun += (ps0 + ps1) + (ps2 + ps3);
;             bf16x8 pb[4];
; #pragma unroll
;             for (int s2 = 0; s2 < 2; ++s2) {
;                 u32x4 w0, w1;
;                 w0.x = pk2(s0[8 * s2 + 0], s0[8 * s2 + 1]); w0.y = pk2(s0[8 * s2 + 2], s0[8 * s2 + 3]); w0.z = pk2(s0[8 * s2 + 4], s0[8 * s2 + 5]); w0.w = pk2(s0[8 * s2 + 6], s0[8 * s2 + 7]);
;                 w1.x = pk2(s1[8 * s2 + 0], s1[8 * s2 + 1]); w1.y = pk2(s1[8 * s2 + 2], s1[8 * s2 + 3]); w1.z = pk2(s1[8 * s2 + 4], s1[8 * s2 + 5]); w1.w = pk2(s1[8 * s2 + 6], s1[8 * s2 + 7]);
;                 pb[s2] = __builtin_bit_cast(bf16x8, w0); pb[2 + s2] = __builtin_bit_cast(bf16x8, w1);
;             }
; #pragma unroll
;             for (int s = 0; s < 4; ++s) {
; #pragma unroll
;                 for (int c = 0; c < 4; ++c) {
;                     const s16x4 v0 = vtr(Vb + vbase[c][0] + 4096 * s);
;                     const s16x4 v1 = vtr(Vb + vbase[c][1] + 4096 * s);
;                     o[c] = __builtin_amdgcn_mfma_f32_32x32x16_bf16(cat8(v0, v1), pb[s], o[c], 0, 0, 0);
;                 }
;             }
.Lat2_u1_norescale:
	v_exp_f32_e32 v82, v82
	v_exp_f32_e32 v83, v83
	v_exp_f32_e32 v84, v84
	v_exp_f32_e32 v85, v85
	v_exp_f32_e32 v86, v86
	v_exp_f32_e32 v87, v87
	v_exp_f32_e32 v88, v88
	v_exp_f32_e32 v89, v89
	v_exp_f32_e32 v90, v90
	v_exp_f32_e32 v91, v91
	v_exp_f32_e32 v92, v92
	v_exp_f32_e32 v93, v93
	v_exp_f32_e32 v94, v94
	v_exp_f32_e32 v95, v95
	v_exp_f32_e32 v96, v96
	v_exp_f32_e32 v97, v97
	v_cvt_pk_bf16_f32 v184, v82, v83
	v_cvt_pk_bf16_f32 v185, v84, v85
	v_cvt_pk_bf16_f32 v186, v86, v87
	v_cvt_pk_bf16_f32 v187, v88, v89
	v_cvt_pk_bf16_f32 v188, v90, v91
	v_cvt_pk_bf16_f32 v189, v92, v93
	v_cvt_pk_bf16_f32 v190, v94, v95
	v_cvt_pk_bf16_f32 v191, v96, v97
	v_add_f32_e32 v122, v82, v83
	v_add_f32_e32 v123, v84, v85
	v_add_f32_e32 v122, v122, v86
	v_add_f32_e32 v123, v123, v87
	v_add_f32_e32 v122, v122, v88
	v_add_f32_e32 v123, v123, v89
	v_add_f32_e32 v122, v122, v123
	v_add_f32_e32 v167, v167, v122
	v_add_f32_e32 v124, v90, v91
	v_add_f32_e32 v125, v92, v93
	v_add_f32_e32 v124, v124, v94
	v_add_f32_e32 v125, v125, v95
	v_add_f32_e32 v124, v124, v96
	v_add_f32_e32 v125, v125, v97
	v_add_f32_e32 v124, v124, v125
	v_add_f32_e32 v167, v167, v124
	s_add_i32 m0, s62, 0x7800
	s_nop 0
	global_load_lds_dwordx4 v[134:135], off offset:2048
	s_add_i32 m0, s62, 0x9800
	s_nop 0
	global_load_lds_dwordx4 v[200:201], off offset:2048
	v_lshl_add_u64 v[134:135], v[134:135], 0, s[40:41]
	v_lshl_add_u64 v[200:201], v[200:201], 0, s[40:41]
	s_waitcnt lgkmcnt(8)
	v_mfma_f32_32x32x16_bf16 v[50:65], v[136:139], v[184:187], v[50:65]
	ds_read_b64_tr_b16 v[246:247], v170 offset:53248
	ds_read_b64_tr_b16 v[248:249], v173 offset:53248
	v_exp_f32_e32 v66, v66
	v_exp_f32_e32 v67, v67
	v_exp_f32_e32 v68, v68
	v_mfma_f32_32x32x16_bf16 v[34:49], v[140:143], v[184:187], v[34:49]
	ds_read_b64_tr_b16 v[250:251], v169 offset:53248
	ds_read_b64_tr_b16 v[252:253], v171 offset:53248
	v_exp_f32_e32 v69, v69
	v_exp_f32_e32 v70, v70
	v_exp_f32_e32 v71, v71
	s_waitcnt lgkmcnt(8)
	v_mfma_f32_32x32x16_bf16 v[18:33], v[204:207], v[184:187], v[18:33]
	ds_read_b64_tr_b16 v[136:137], v168 offset:57344
	ds_read_b64_tr_b16 v[138:139], v175 offset:57344
	v_exp_f32_e32 v72, v72
	v_exp_f32_e32 v73, v73
	v_cvt_pk_bf16_f32 v192, v66, v67
	v_mfma_f32_32x32x16_bf16 v[2:17], v[208:211], v[184:187], v[2:17]
	ds_read_b64_tr_b16 v[140:141], v172 offset:57344
	ds_read_b64_tr_b16 v[142:143], v174 offset:57344
	v_cvt_pk_bf16_f32 v193, v68, v69
	v_cvt_pk_bf16_f32 v194, v70, v71
	v_cvt_pk_bf16_f32 v195, v72, v73
	s_waitcnt lgkmcnt(8)
	v_mfma_f32_32x32x16_bf16 v[50:65], v[238:241], v[188:191], v[50:65]
	ds_read_b64_tr_b16 v[204:205], v170 offset:57344
	ds_read_b64_tr_b16 v[206:207], v173 offset:57344
	v_exp_f32_e32 v74, v74
	v_exp_f32_e32 v75, v75
	v_exp_f32_e32 v76, v76
	v_mfma_f32_32x32x16_bf16 v[34:49], v[242:245], v[188:191], v[34:49]
	ds_read_b64_tr_b16 v[208:209], v169 offset:57344
	ds_read_b64_tr_b16 v[210:211], v171 offset:57344
	v_exp_f32_e32 v77, v77
	v_exp_f32_e32 v78, v78
	v_exp_f32_e32 v79, v79
	s_waitcnt lgkmcnt(8)
	v_mfma_f32_32x32x16_bf16 v[18:33], v[246:249], v[188:191], v[18:33]
	ds_read_b64_tr_b16 v[238:239], v168 offset:61440
	ds_read_b64_tr_b16 v[240:241], v175 offset:61440
	v_exp_f32_e32 v80, v80
	v_exp_f32_e32 v81, v81
	v_cvt_pk_bf16_f32 v196, v74, v75
	v_mfma_f32_32x32x16_bf16 v[2:17], v[250:253], v[188:191], v[2:17]
	ds_read_b64_tr_b16 v[242:243], v172 offset:61440
	ds_read_b64_tr_b16 v[244:245], v174 offset:61440
	v_cvt_pk_bf16_f32 v197, v76, v77
	v_cvt_pk_bf16_f32 v198, v78, v79
	v_cvt_pk_bf16_f32 v199, v80, v81
	s_waitcnt lgkmcnt(8)
	v_mfma_f32_32x32x16_bf16 v[50:65], v[136:139], v[192:195], v[50:65]
	ds_read_b64_tr_b16 v[246:247], v170 offset:61440
	ds_read_b64_tr_b16 v[248:249], v173 offset:61440
	v_add_f32_e32 v0, v66, v67
	v_add_f32_e32 v203, v68, v69
	v_add_f32_e32 v0, v0, v70
	v_mfma_f32_32x32x16_bf16 v[34:49], v[140:143], v[192:195], v[34:49]
	ds_read_b64_tr_b16 v[250:251], v169 offset:61440
	ds_read_b64_tr_b16 v[252:253], v171 offset:61440
	v_add_f32_e32 v203, v203, v71
	v_add_f32_e32 v0, v0, v72
	v_add_f32_e32 v203, v203, v73
	s_waitcnt lgkmcnt(8)
	v_mfma_f32_32x32x16_bf16 v[18:33], v[204:207], v[192:195], v[18:33]
	v_add_f32_e32 v0, v0, v203
	v_add_f32_e32 v167, v167, v0
	v_add_f32_e32 v0, v74, v75
	v_mfma_f32_32x32x16_bf16 v[2:17], v[208:211], v[192:195], v[2:17]
	v_add_f32_e32 v203, v76, v77
	v_add_f32_e32 v0, v0, v78
	v_add_f32_e32 v203, v203, v79
	s_waitcnt lgkmcnt(4)
	v_mfma_f32_32x32x16_bf16 v[50:65], v[238:241], v[196:199], v[50:65]
	v_add_f32_e32 v0, v0, v80
	v_add_f32_e32 v203, v203, v81
	v_add_f32_e32 v0, v0, v203
	v_mfma_f32_32x32x16_bf16 v[34:49], v[242:245], v[196:199], v[34:49]
	v_add_f32_e32 v167, v167, v0
	s_waitcnt lgkmcnt(0)
	v_mfma_f32_32x32x16_bf16 v[18:33], v[246:249], v[196:199], v[18:33]
	v_mfma_f32_32x32x16_bf16 v[2:17], v[250:253], v[196:199], v[2:17]
	ds_read_b128 v[136:139], v126 offset:0
	ds_read_b128 v[140:143], v126 offset:8192
	ds_read_b128 v[204:207], v127 offset:0
	ds_read_b128 v[208:211], v127 offset:8192
	ds_read_b128 v[238:241], v128 offset:0
	ds_read_b128 v[242:245], v128 offset:8192
	ds_read_b128 v[246:249], v129 offset:0
	ds_read_b128 v[250:253], v129 offset:8192
	s_waitcnt vmcnt(6)
	s_add_i32 s50, s50, 64
	s_barrier
; #define LAS __attribute__((address_space(3)))
; __device__ __forceinline__ void attn_block(LAS unsigned char* lds, const bf16_t* P, bf16_t* mix, int b, int h, int qb, float lam, float outscale, const float* subln) {
;     ...
;         if (kt + 1 < ntiles) {
;             const size_t ro = (size_t)(64 * (kt + 1)) * INC;
;             kr0 = *(const u32x4*)(kg + ro + (size_t)srow * INC); kr1 = *(const u32x4*)(kg + ro + (size_t)(srow + 32) * INC);
;             vr0 = *(const u32x4*)(vg + ro + (size_t)srow * INC); vr1 = *(const u32x4*)(vg + ro + (size_t)(srow + 32) * INC);
;         }
;         const int kb = 64 * kt;
;         if (kb <= qw0 + 31) {
;             LAS const unsigned char* Kb = lds + ATT_K0 + buf * 16384;
;             LAS const unsigned char* Vb = lds + ATT_V0 + buf * 16384;
;             f32x16 s0, s1;
; #pragma unroll
;             for (int j = 0; j < 16; ++j) { s0[j] = 0.f; s1[j] = 0.f; }
;             bf16x8 ka[4][2];
; #pragma unroll
;             for (int ks = 0; ks < 4; ++ks) { ka[ks][0] = *(const LAS bf16x8*)(Kb + kbase[ks]); ka[ks][1] = *(const LAS bf16x8*)(Kb + kbase[ks] + 8192); }
;             __builtin_amdgcn_sched_barrier(0);
; #pragma unroll
;             for (int ks = 0; ks < 4; ++ks) {
;                 s0 = __builtin_amdgcn_mfma_f32_32x32x16_bf16(ka[ks][0], qf[ks], s0, 0, 0, 0);
;                 s1 = __builtin_amdgcn_mfma_f32_32x32x16_bf16(ka[ks][1], qf[ks], s1, 0, 0, 0);
;             }
;             if (kb + 63 > qw0) {
; #pragma unroll
;                 for (int j = 0; j < 16; ++j) { const int key = kb + crow(j, hi); if (key > qrow) s0[j] = -INFINITY; if (key + 32 > qrow) s1[j] = -INFINITY; }
;             }
;             float mxa = max3f(s0[0], s1[0], s0[1]), mxb = max3f(s1[1], s0[2], s1[2]), mxc = max3f(s0[3], s1[3], s0[4]), mxd = max3f(s1[4], s0[5], s1[5]);
;             mxa = max3f(mxa, s0[6], s1[6]); mxb = max3f(mxb, s0[7], s1[7]); mxc = max3f(mxc, s0[8], s1[8]); mxd = max3f(mxd, s0[9], s1[9]);
;             mxa = max3f(mxa, s0[10], s1[10]); mxb = max3f(mxb, s0[11], s1[11]); mxc = max3f(mxc, s0[12], s1[12]); mxd = max3f(mxd, s0[13], s1[13]);
;             mxa = max3f(mxa, s0[14], s1[14]); mxb = max3f(mxb, s0[15], s1[15]);
;             float mx = max3f(mxa, mxb, max3f(mxc, mxd, mxd));
;             { auto rr = __builtin_amdgcn_permlane32_swap(__builtin_bit_cast(unsigned, mx), __builtin_bit_cast(unsigned, mx), false, false);
	s_add_i32 m0, s62, 0x4000
	s_nop 0
	global_load_lds_dwordx4 v[134:135], off
	s_add_i32 m0, s62, 0x6000
	s_nop 0
	global_load_lds_dwordx4 v[200:201], off
	s_waitcnt lgkmcnt(6)
	v_mfma_f32_32x32x16_bf16 v[82:97], v[136:139], v[110:113], v[222:237]
	v_mfma_f32_32x32x16_bf16 v[66:81], v[140:143], v[110:113], v[222:237]
	s_waitcnt lgkmcnt(4)
	v_mfma_f32_32x32x16_bf16 v[82:97], v[204:207], v[106:109], v[82:97]
	v_mfma_f32_32x32x16_bf16 v[66:81], v[208:211], v[106:109], v[66:81]
	s_waitcnt lgkmcnt(2)
	v_mfma_f32_32x32x16_bf16 v[82:97], v[238:241], v[102:105], v[82:97]
	v_mfma_f32_32x32x16_bf16 v[66:81], v[242:245], v[102:105], v[66:81]
	s_waitcnt lgkmcnt(0)
	v_mfma_f32_32x32x16_bf16 v[82:97], v[246:249], v[98:101], v[82:97]
	v_mfma_f32_32x32x16_bf16 v[66:81], v[250:253], v[98:101], v[66:81]
	ds_read_b64_tr_b16 v[136:137], v114 offset:32768
	ds_read_b64_tr_b16 v[138:139], v115 offset:32768
	ds_read_b64_tr_b16 v[140:141], v116 offset:32768
	ds_read_b64_tr_b16 v[142:143], v117 offset:32768
	ds_read_b64_tr_b16 v[204:205], v118 offset:32768
	ds_read_b64_tr_b16 v[206:207], v119 offset:32768
	ds_read_b64_tr_b16 v[208:209], v120 offset:32768
	ds_read_b64_tr_b16 v[210:211], v121 offset:32768
	ds_read_b64_tr_b16 v[238:239], v114 offset:36864
	ds_read_b64_tr_b16 v[240:241], v115 offset:36864
	ds_read_b64_tr_b16 v[242:243], v116 offset:36864
	ds_read_b64_tr_b16 v[244:245], v117 offset:36864
	v_max3_f32 v122, v82, v66, v83
	v_max3_f32 v123, v67, v84, v68
	v_max3_f32 v124, v85, v69, v86
	v_max3_f32 v125, v70, v87, v71
	v_max3_f32 v122, v122, v88, v72
	v_max3_f32 v123, v123, v89, v73
	v_max3_f32 v124, v124, v90, v74
	v_max3_f32 v125, v125, v91, v75
	v_max3_f32 v122, v122, v92, v76
	v_max3_f32 v123, v123, v93, v77
	v_max3_f32 v124, v124, v94, v78
	v_max3_f32 v125, v125, v95, v79
	v_max3_f32 v122, v122, v96, v80
	v_max3_f32 v123, v123, v97, v81
	v_max3_f32 v122, v122, v123, v124
	v_max_f32_e32 v122, v122, v125
	v_mov_b32_e32 v203, v122
	s_nop 1
	v_permlane32_swap_b32_e32 v122, v203
	s_nop 1
	v_max_f32_e32 v122, v122, v203
	s_mov_b32 s39, 0
	v_cmp_lt_f32_e32 vcc, 0x41000000, v122
	s_cmp_eq_u32 s50, 0
	s_cbranch_scc1 .Lat2_u2_first
	s_cbranch_vccz .Lat2_u2_norescale
	s_branch .Lat2_u2_rescale

; __device__ __forceinline__ unsigned pk2(float lo, float hi) { f32x2 v = {lo, hi}; bf16x2_t b = __builtin_convertvector(v, bf16x2_t); return __builtin_bit_cast(unsigned, b); }
; __device__ __forceinline__ s16x4 vtr(LAS const unsigned char* p) { return __builtin_bit_cast(s16x4, __builtin_amdgcn_ds_read_tr16_b64_v4i16((LAS v4i16_t*)p)); }
; __device__ __forceinline__ bf16x8 cat8(s16x4 a, s16x4 b) { return (bf16x8){a[0], a[1], a[2], a[3], b[0], b[1], b[2], b[3]}; }
; __device__ __forceinline__ void attn_block(LAS unsigned char* lds, const bf16_t* P, bf16_t* mix, int b, int h, int qb, float lam, float outscale, const float* subln) {
;     ...
;             for (int j = 0; j < 16; ++j) { s0[j] = __builtin_amdgcn_exp2f(s0[j] - mrun); s1[j] = __builtin_amdgcn_exp2f(s1[j] - mrun); }
;             float ps0 = 0.f, ps1 = 0.f, ps2 = 0.f, ps3 = 0.f;
; #pragma unroll
;             for (int j = 0; j < 16; j += 2) { ps0 += s0[j]; ps1 += s1[j]; ps2 += s0[j + 1]; ps3 += s1[j + 1]; }
;             lrun += (ps0 + ps1) + (ps2 + ps3);
;             bf16x8 pb[4];
; #pragma unroll
;             for (int s2 = 0; s2 < 2; ++s2) {
;                 u32x4 w0, w1;
;                 w0.x = pk2(s0[8 * s2 + 0], s0[8 * s2 + 1]); w0.y = pk2(s0[8 * s2 + 2], s0[8 * s2 + 3]); w0.z = pk2(s0[8 * s2 + 4], s0[8 * s2 + 5]); w0.w = pk2(s0[8 * s2 + 6], s0[8 * s2 + 7]);
;                 w1.x = pk2(s1[8 * s2 + 0], s1[8 * s2 + 1]); w1.y = pk2(s1[8 * s2 + 2], s1[8 * s2 + 3]); w1.z = pk2(s1[8 * s2 + 4], s1[8 * s2 + 5]); w1.w = pk2(s1[8 * s2 + 6], s1[8 * s2 + 7]);
;                 pb[s2] = __builtin_bit_cast(bf16x8, w0); pb[2 + s2] = __builtin_bit_cast(bf16x8, w1);
;             }
; #pragma unroll
;             for (int s = 0; s < 4; ++s) {
; #pragma unroll
;                 for (int c = 0; c < 4; ++c) {
;                     const s16x4 v0 = vtr(Vb + vbase[c][0] + 4096 * s);
;                     const s16x4 v1 = vtr(Vb + vbase[c][1] + 4096 * s);
;                     o[c] = __builtin_amdgcn_mfma_f32_32x32x16_bf16(cat8(v0, v1), pb[s], o[c], 0, 0, 0);
;                 }
;             }
.Lat2_u2_norescale:
	v_exp_f32_e32 v82, v82
	v_exp_f32_e32 v83, v83
	v_exp_f32_e32 v84, v84
	v_exp_f32_e32 v85, v85
	v_exp_f32_e32 v86, v86
	v_exp_f32_e32 v87, v87
	v_exp_f32_e32 v88, v88
	v_exp_f32_e32 v89, v89
	v_exp_f32_e32 v90, v90
	v_exp_f32_e32 v91, v91
	v_exp_f32_e32 v92, v92
	v_exp_f32_e32 v93, v93
	v_exp_f32_e32 v94, v94
	v_exp_f32_e32 v95, v95
	v_exp_f32_e32 v96, v96
	v_exp_f32_e32 v97, v97
	v_cvt_pk_bf16_f32 v184, v82, v83
	v_cvt_pk_bf16_f32 v185, v84, v85
	v_cvt_pk_bf16_f32 v186, v86, v87
	v_cvt_pk_bf16_f32 v187, v88, v89
	v_cvt_pk_bf16_f32 v188, v90, v91
	v_cvt_pk_bf16_f32 v189, v92, v93
	v_cvt_pk_bf16_f32 v190, v94, v95
	v_cvt_pk_bf16_f32 v191, v96, v97
	v_add_f32_e32 v122, v82, v83
	v_add_f32_e32 v123, v84, v85
	v_add_f32_e32 v122, v122, v86
	v_add_f32_e32 v123, v123, v87
	v_add_f32_e32 v122, v122, v88
	v_add_f32_e32 v123, v123, v89
	v_add_f32_e32 v122, v122, v123
	v_add_f32_e32 v167, v167, v122
	v_add_f32_e32 v124, v90, v91
	v_add_f32_e32 v125, v92, v93
	v_add_f32_e32 v124, v124, v94
	v_add_f32_e32 v125, v125, v95
	v_add_f32_e32 v124, v124, v96
	v_add_f32_e32 v125, v125, v97
	v_add_f32_e32 v124, v124, v125
	v_add_f32_e32 v167, v167, v124
	s_add_i32 m0, s62, 0xb800
	s_nop 0
	global_load_lds_dwordx4 v[134:135], off offset:2048
	s_add_i32 m0, s62, 0xd800
	s_nop 0
	global_load_lds_dwordx4 v[200:201], off offset:2048
	v_lshl_add_u64 v[134:135], v[134:135], 0, s[40:41]
	v_lshl_add_u64 v[200:201], v[200:201], 0, s[40:41]
	s_waitcnt lgkmcnt(8)
	v_mfma_f32_32x32x16_bf16 v[50:65], v[136:139], v[184:187], v[50:65]
	ds_read_b64_tr_b16 v[246:247], v118 offset:36864
	ds_read_b64_tr_b16 v[248:249], v119 offset:36864
	v_exp_f32_e32 v66, v66
	v_exp_f32_e32 v67, v67
	v_exp_f32_e32 v68, v68
	v_mfma_f32_32x32x16_bf16 v[34:49], v[140:143], v[184:187], v[34:49]
	ds_read_b64_tr_b16 v[250:251], v120 offset:36864
	ds_read_b64_tr_b16 v[252:253], v121 offset:36864
	v_exp_f32_e32 v69, v69
	v_exp_f32_e32 v70, v70
	v_exp_f32_e32 v71, v71
	s_waitcnt lgkmcnt(8)
	v_mfma_f32_32x32x16_bf16 v[18:33], v[204:207], v[184:187], v[18:33]
	ds_read_b64_tr_b16 v[136:137], v114 offset:40960
	ds_read_b64_tr_b16 v[138:139], v115 offset:40960
	v_exp_f32_e32 v72, v72
	v_exp_f32_e32 v73, v73
	v_cvt_pk_bf16_f32 v192, v66, v67
	v_mfma_f32_32x32x16_bf16 v[2:17], v[208:211], v[184:187], v[2:17]
	ds_read_b64_tr_b16 v[140:141], v116 offset:40960
	ds_read_b64_tr_b16 v[142:143], v117 offset:40960
	v_cvt_pk_bf16_f32 v193, v68, v69
	v_cvt_pk_bf16_f32 v194, v70, v71
	v_cvt_pk_bf16_f32 v195, v72, v73
	s_waitcnt lgkmcnt(8)
	v_mfma_f32_32x32x16_bf16 v[50:65], v[238:241], v[188:191], v[50:65]
	ds_read_b64_tr_b16 v[204:205], v118 offset:40960
	ds_read_b64_tr_b16 v[206:207], v119 offset:40960
	v_exp_f32_e32 v74, v74
	v_exp_f32_e32 v75, v75
	v_exp_f32_e32 v76, v76
	v_mfma_f32_32x32x16_bf16 v[34:49], v[242:245], v[188:191], v[34:49]
	ds_read_b64_tr_b16 v[208:209], v120 offset:40960
	ds_read_b64_tr_b16 v[210:211], v121 offset:40960
	v_exp_f32_e32 v77, v77
	v_exp_f32_e32 v78, v78
	v_exp_f32_e32 v79, v79
	s_waitcnt lgkmcnt(8)
	v_mfma_f32_32x32x16_bf16 v[18:33], v[246:249], v[188:191], v[18:33]
	ds_read_b64_tr_b16 v[238:239], v114 offset:45056
	ds_read_b64_tr_b16 v[240:241], v115 offset:45056
	v_exp_f32_e32 v80, v80
	v_exp_f32_e32 v81, v81
	v_cvt_pk_bf16_f32 v196, v74, v75
	v_mfma_f32_32x32x16_bf16 v[2:17], v[250:253], v[188:191], v[2:17]
	ds_read_b64_tr_b16 v[242:243], v116 offset:45056
	ds_read_b64_tr_b16 v[244:245], v117 offset:45056
	v_cvt_pk_bf16_f32 v197, v76, v77
	v_cvt_pk_bf16_f32 v198, v78, v79
	v_cvt_pk_bf16_f32 v199, v80, v81
	s_waitcnt lgkmcnt(8)
	v_mfma_f32_32x32x16_bf16 v[50:65], v[136:139], v[192:195], v[50:65]
	ds_read_b64_tr_b16 v[246:247], v118 offset:45056
	ds_read_b64_tr_b16 v[248:249], v119 offset:45056
	v_add_f32_e32 v0, v66, v67
	v_add_f32_e32 v203, v68, v69
	v_add_f32_e32 v0, v0, v70
	v_mfma_f32_32x32x16_bf16 v[34:49], v[140:143], v[192:195], v[34:49]
	ds_read_b64_tr_b16 v[250:251], v120 offset:45056
	ds_read_b64_tr_b16 v[252:253], v121 offset:45056
	v_add_f32_e32 v203, v203, v71
	v_add_f32_e32 v0, v0, v72
	v_add_f32_e32 v203, v203, v73
	s_waitcnt lgkmcnt(8)
	v_mfma_f32_32x32x16_bf16 v[18:33], v[204:207], v[192:195], v[18:33]
	v_add_f32_e32 v0, v0, v203
	v_add_f32_e32 v167, v167, v0
	v_add_f32_e32 v0, v74, v75
	v_mfma_f32_32x32x16_bf16 v[2:17], v[208:211], v[192:195], v[2:17]
	v_add_f32_e32 v203, v76, v77
	v_add_f32_e32 v0, v0, v78
	v_add_f32_e32 v203, v203, v79
	s_waitcnt lgkmcnt(4)
	v_mfma_f32_32x32x16_bf16 v[50:65], v[238:241], v[196:199], v[50:65]
	v_add_f32_e32 v0, v0, v80
	v_add_f32_e32 v203, v203, v81
	v_add_f32_e32 v0, v0, v203
	v_mfma_f32_32x32x16_bf16 v[34:49], v[242:245], v[196:199], v[34:49]
	v_add_f32_e32 v167, v167, v0
	s_waitcnt lgkmcnt(0)
	v_mfma_f32_32x32x16_bf16 v[18:33], v[246:249], v[196:199], v[18:33]
	v_mfma_f32_32x32x16_bf16 v[2:17], v[250:253], v[196:199], v[2:17]
	ds_read_b128 v[136:139], v126 offset:16384
	ds_read_b128 v[140:143], v126 offset:24576
	ds_read_b128 v[204:207], v127 offset:16384
	ds_read_b128 v[208:211], v127 offset:24576
	ds_read_b128 v[238:241], v128 offset:16384
	ds_read_b128 v[242:245], v128 offset:24576
	ds_read_b128 v[246:249], v129 offset:16384
	ds_read_b128 v[250:253], v129 offset:24576
	s_waitcnt vmcnt(6)
	s_add_i32 s50, s50, 64
	s_barrier
; #define LAS __attribute__((address_space(3)))
; __device__ __forceinline__ void attn_block(LAS unsigned char* lds, const bf16_t* P, bf16_t* mix, int b, int h, int qb, float lam, float outscale, const float* subln) {
;     ...
;         if (kt + 1 < ntiles) {
;             const size_t ro = (size_t)(64 * (kt + 1)) * INC;
;             kr0 = *(const u32x4*)(kg + ro + (size_t)srow * INC); kr1 = *(const u32x4*)(kg + ro + (size_t)(srow + 32) * INC);
;             vr0 = *(const u32x4*)(vg + ro + (size_t)srow * INC); vr1 = *(const u32x4*)(vg + ro + (size_t)(srow + 32) * INC);
;         }
;         const int kb = 64 * kt;
;         if (kb <= qw0 + 31) {
;             LAS const unsigned char* Kb = lds + ATT_K0 + buf * 16384;
;             LAS const unsigned char* Vb = lds + ATT_V0 + buf * 16384;
;             f32x16 s0, s1;
; #pragma unroll
;             for (int j = 0; j < 16; ++j) { s0[j] = 0.f; s1[j] = 0.f; }
;             bf16x8 ka[4][2];
; #pragma unroll
;             for (int ks = 0; ks < 4; ++ks) { ka[ks][0] = *(const LAS bf16x8*)(Kb + kbase[ks]); ka[ks][1] = *(const LAS bf16x8*)(Kb + kbase[ks] + 8192); }
;             __builtin_amdgcn_sched_barrier(0);
; #pragma unroll
;             for (int ks = 0; ks < 4; ++ks) {
;                 s0 = __builtin_amdgcn_mfma_f32_32x32x16_bf16(ka[ks][0], qf[ks], s0, 0, 0, 0);
;                 s1 = __builtin_amdgcn_mfma_f32_32x32x16_bf16(ka[ks][1], qf[ks], s1, 0, 0, 0);
;             }
;             if (kb + 63 > qw0) {
; #pragma unroll
;                 for (int j = 0; j < 16; ++j) { const int key = kb + crow(j, hi); if (key > qrow) s0[j] = -INFINITY; if (key + 32 > qrow) s1[j] = -INFINITY; }
;             }
;             float mxa = max3f(s0[0], s1[0], s0[1]), mxb = max3f(s1[1], s0[2], s1[2]), mxc = max3f(s0[3], s1[3], s0[4]), mxd = max3f(s1[4], s0[5], s1[5]);
;             mxa = max3f(mxa, s0[6], s1[6]); mxb = max3f(mxb, s0[7], s1[7]); mxc = max3f(mxc, s0[8], s1[8]); mxd = max3f(mxd, s0[9], s1[9]);
;             mxa = max3f(mxa, s0[10], s1[10]); mxb = max3f(mxb, s0[11], s1[11]); mxc = max3f(mxc, s0[12], s1[12]); mxd = max3f(mxd, s0[13], s1[13]);
;             mxa = max3f(mxa, s0[14], s1[14]); mxb = max3f(mxb, s0[15], s1[15]);
;             float mx = max3f(mxa, mxb, max3f(mxc, mxd, mxd));
;             { auto rr = __builtin_amdgcn_permlane32_swap(__builtin_bit_cast(unsigned, mx), __builtin_bit_cast(unsigned, mx), false, false);
	s_add_i32 m0, s62, 0x10000
	s_nop 0
	global_load_lds_dwordx4 v[134:135], off
	s_add_i32 m0, s62, 0x12000
	s_nop 0
	global_load_lds_dwordx4 v[200:201], off
	s_waitcnt lgkmcnt(6)
	v_mfma_f32_32x32x16_bf16 v[82:97], v[136:139], v[110:113], v[222:237]
	v_mfma_f32_32x32x16_bf16 v[66:81], v[140:143], v[110:113], v[222:237]
	s_waitcnt lgkmcnt(4)
	v_mfma_f32_32x32x16_bf16 v[82:97], v[204:207], v[106:109], v[82:97]
	v_mfma_f32_32x32x16_bf16 v[66:81], v[208:211], v[106:109], v[66:81]
	s_waitcnt lgkmcnt(2)
	v_mfma_f32_32x32x16_bf16 v[82:97], v[238:241], v[102:105], v[82:97]
	v_mfma_f32_32x32x16_bf16 v[66:81], v[242:245], v[102:105], v[66:81]
	s_waitcnt lgkmcnt(0)
	v_mfma_f32_32x32x16_bf16 v[82:97], v[246:249], v[98:101], v[82:97]
	v_mfma_f32_32x32x16_bf16 v[66:81], v[250:253], v[98:101], v[66:81]
	ds_read_b64_tr_b16 v[136:137], v114 offset:49152
	ds_read_b64_tr_b16 v[138:139], v115 offset:49152
	ds_read_b64_tr_b16 v[140:141], v116 offset:49152
	ds_read_b64_tr_b16 v[142:143], v117 offset:49152
	ds_read_b64_tr_b16 v[204:205], v118 offset:49152
	ds_read_b64_tr_b16 v[206:207], v119 offset:49152
	ds_read_b64_tr_b16 v[208:209], v120 offset:49152
	ds_read_b64_tr_b16 v[210:211], v121 offset:49152
	ds_read_b64_tr_b16 v[238:239], v114 offset:53248
	ds_read_b64_tr_b16 v[240:241], v115 offset:53248
	ds_read_b64_tr_b16 v[242:243], v116 offset:53248
	ds_read_b64_tr_b16 v[244:245], v117 offset:53248
	v_max3_f32 v122, v82, v66, v83
	v_max3_f32 v123, v67, v84, v68
	v_max3_f32 v124, v85, v69, v86
	v_max3_f32 v125, v70, v87, v71
	v_max3_f32 v122, v122, v88, v72
	v_max3_f32 v123, v123, v89, v73
	v_max3_f32 v124, v124, v90, v74
	v_max3_f32 v125, v125, v91, v75
	v_max3_f32 v122, v122, v92, v76
	v_max3_f32 v123, v123, v93, v77
	v_max3_f32 v124, v124, v94, v78
	v_max3_f32 v125, v125, v95, v79
	v_max3_f32 v122, v122, v96, v80
	v_max3_f32 v123, v123, v97, v81
	v_max3_f32 v122, v122, v123, v124
	v_max_f32_e32 v122, v122, v125
	v_mov_b32_e32 v203, v122
	s_nop 1
	v_permlane32_swap_b32_e32 v122, v203
	s_nop 1
	v_max_f32_e32 v122, v122, v203
	s_mov_b32 s39, 0
	v_cmp_lt_f32_e32 vcc, 0x41000000, v122
	s_cmp_eq_u32 s50, 0
	s_cbranch_scc1 .Lat2_u3_first
	s_cbranch_vccz .Lat2_u3_norescale
	s_branch .Lat2_u3_rescale

; #define LAS __attribute__((address_space(3)))
; __device__ __forceinline__ unsigned pk2(float lo, float hi) { f32x2 v = {lo, hi}; bf16x2_t b = __builtin_convertvector(v, bf16x2_t); return __builtin_bit_cast(unsigned, b); }
; __device__ __forceinline__ s16x4 vtr(LAS const unsigned char* p) { return __builtin_bit_cast(s16x4, __builtin_amdgcn_ds_read_tr16_b64_v4i16((LAS v4i16_t*)p)); }
; __device__ __forceinline__ void attn_block(LAS unsigned char* lds, const bf16_t* P, bf16_t* mix, int b, int h, int qb, float lam, float outscale, const float* subln) {
;     ...
;             for (int j = 0; j < 16; ++j) { s0[j] = __builtin_amdgcn_exp2f(s0[j] - mrun); s1[j] = __builtin_amdgcn_exp2f(s1[j] - mrun); }
;             float ps0 = 0.f, ps1 = 0.f, ps2 = 0.f, ps3 = 0.f;
; #pragma unroll
;             for (int j = 0; j < 16; j += 2) { ps0 += s0[j]; ps1 += s1[j]; ps2 += s0[j + 1]; ps3 += s1[j + 1]; }
;             lrun += (ps0 + ps1) + (ps2 + ps3);
;             bf16x8 pb[4];
; #pragma unroll
;             for (int s2 = 0; s2 < 2; ++s2) {
;                 u32x4 w0, w1;
;                 w0.x = pk2(s0[8 * s2 + 0], s0[8 * s2 + 1]); w0.y = pk2(s0[8 * s2 + 2], s0[8 * s2 + 3]); w0.z = pk2(s0[8 * s2 + 4], s0[8 * s2 + 5]); w0.w = pk2(s0[8 * s2 + 6], s0[8 * s2 + 7]);
;                 w1.x = pk2(s1[8 * s2 + 0], s1[8 * s2 + 1]); w1.y = pk2(s1[8 * s2 + 2], s1[8 * s2 + 3]); w1.z = pk2(s1[8 * s2 + 4], s1[8 * s2 + 5]); w1.w = pk2(s1[8 * s2 + 6], s1[8 * s2 + 7]);
;                 pb[s2] = __builtin_bit_cast(bf16x8, w0); pb[2 + s2] = __builtin_bit_cast(bf16x8, w1);
;             }
; #pragma unroll
;             for (int s = 0; s < 4; ++s) {
; #pragma unroll
;                 for (int c = 0; c < 4; ++c) {
;                     const s16x4 v0 = vtr(Vb + vbase[c][0] + 4096 * s);
;                     const s16x4 v1 = vtr(Vb + vbase[c][1] + 4096 * s);
;                     o[c] = __builtin_amdgcn_mfma_f32_32x32x16_bf16(cat8(v0, v1), pb[s], o[c], 0, 0, 0);
;                 }
;             }
;         }
;         if (kt + 1 < ntiles) {
;             const int nb = (kt + 1) & 1;
;             *(LAS u32x4*)(lds + ATT_K0 + nb * 16384 + so0) = kr0; *(LAS u32x4*)(lds + ATT_K0 + nb * 16384 + so1) = kr1;
;             *(LAS u32x4*)(lds + ATT_V0 + nb * 16384 + so0) = vr0; *(LAS u32x4*)(lds + ATT_V0 + nb * 16384 + so1) = vr1;
;         }
;     }
.Lat2_u3_norescale:
	v_exp_f32_e32 v82, v82
	v_exp_f32_e32 v83, v83
	v_exp_f32_e32 v84, v84
	v_exp_f32_e32 v85, v85
	v_exp_f32_e32 v86, v86
	v_exp_f32_e32 v87, v87
	v_exp_f32_e32 v88, v88
	v_exp_f32_e32 v89, v89
	v_exp_f32_e32 v90, v90
	v_exp_f32_e32 v91, v91
	v_exp_f32_e32 v92, v92
	v_exp_f32_e32 v93, v93
	v_exp_f32_e32 v94, v94
	v_exp_f32_e32 v95, v95
	v_exp_f32_e32 v96, v96
	v_exp_f32_e32 v97, v97
	v_cvt_pk_bf16_f32 v184, v82, v83
	v_cvt_pk_bf16_f32 v185, v84, v85
	v_cvt_pk_bf16_f32 v186, v86, v87
	v_cvt_pk_bf16_f32 v187, v88, v89
	v_cvt_pk_bf16_f32 v188, v90, v91
	v_cvt_pk_bf16_f32 v189, v92, v93
	v_cvt_pk_bf16_f32 v190, v94, v95
	v_cvt_pk_bf16_f32 v191, v96, v97
	v_add_f32_e32 v122, v82, v83
	v_add_f32_e32 v123, v84, v85
	v_add_f32_e32 v122, v122, v86
	v_add_f32_e32 v123, v123, v87
	v_add_f32_e32 v122, v122, v88
	v_add_f32_e32 v123, v123, v89
	v_add_f32_e32 v122, v122, v123
	v_add_f32_e32 v167, v167, v122
	v_add_f32_e32 v124, v90, v91
	v_add_f32_e32 v125, v92, v93
	v_add_f32_e32 v124, v124, v94
	v_add_f32_e32 v125, v125, v95
	v_add_f32_e32 v124, v124, v96
	v_add_f32_e32 v125, v125, v97
	v_add_f32_e32 v124, v124, v125
	v_add_f32_e32 v167, v167, v124
	s_add_i32 m0, s62, 0x17800
	s_nop 0
	global_load_lds_dwordx4 v[134:135], off offset:2048
	s_add_i32 m0, s62, 0x19800
	s_nop 0
	global_load_lds_dwordx4 v[200:201], off offset:2048
	v_lshl_add_u64 v[134:135], v[134:135], 0, s[40:41]
	v_lshl_add_u64 v[200:201], v[200:201], 0, s[40:41]
	s_waitcnt lgkmcnt(8)
	v_mfma_f32_32x32x16_bf16 v[50:65], v[136:139], v[184:187], v[50:65]
	ds_read_b64_tr_b16 v[246:247], v118 offset:53248
	ds_read_b64_tr_b16 v[248:249], v119 offset:53248
	v_exp_f32_e32 v66, v66
	v_exp_f32_e32 v67, v67
	v_exp_f32_e32 v68, v68
	v_mfma_f32_32x32x16_bf16 v[34:49], v[140:143], v[184:187], v[34:49]
	ds_read_b64_tr_b16 v[250:251], v120 offset:53248
	ds_read_b64_tr_b16 v[252:253], v121 offset:53248
	v_exp_f32_e32 v69, v69
	v_exp_f32_e32 v70, v70
	v_exp_f32_e32 v71, v71
	s_waitcnt lgkmcnt(8)
	v_mfma_f32_32x32x16_bf16 v[18:33], v[204:207], v[184:187], v[18:33]
	ds_read_b64_tr_b16 v[136:137], v114 offset:57344
	ds_read_b64_tr_b16 v[138:139], v115 offset:57344
	v_exp_f32_e32 v72, v72
	v_exp_f32_e32 v73, v73
	v_cvt_pk_bf16_f32 v192, v66, v67
	v_mfma_f32_32x32x16_bf16 v[2:17], v[208:211], v[184:187], v[2:17]
	ds_read_b64_tr_b16 v[140:141], v116 offset:57344
	ds_read_b64_tr_b16 v[142:143], v117 offset:57344
	v_cvt_pk_bf16_f32 v193, v68, v69
	v_cvt_pk_bf16_f32 v194, v70, v71
	v_cvt_pk_bf16_f32 v195, v72, v73
	s_waitcnt lgkmcnt(8)
	v_mfma_f32_32x32x16_bf16 v[50:65], v[238:241], v[188:191], v[50:65]
	ds_read_b64_tr_b16 v[204:205], v118 offset:57344
	ds_read_b64_tr_b16 v[206:207], v119 offset:57344
	v_exp_f32_e32 v74, v74
	v_exp_f32_e32 v75, v75
	v_exp_f32_e32 v76, v76
	v_mfma_f32_32x32x16_bf16 v[34:49], v[242:245], v[188:191], v[34:49]
	ds_read_b64_tr_b16 v[208:209], v120 offset:57344
	ds_read_b64_tr_b16 v[210:211], v121 offset:57344
	v_exp_f32_e32 v77, v77
	v_exp_f32_e32 v78, v78
	v_exp_f32_e32 v79, v79
	s_waitcnt lgkmcnt(8)
	v_mfma_f32_32x32x16_bf16 v[18:33], v[246:249], v[188:191], v[18:33]
	ds_read_b64_tr_b16 v[238:239], v114 offset:61440
	ds_read_b64_tr_b16 v[240:241], v115 offset:61440
	v_exp_f32_e32 v80, v80
	v_exp_f32_e32 v81, v81
	v_cvt_pk_bf16_f32 v196, v74, v75
	v_mfma_f32_32x32x16_bf16 v[2:17], v[250:253], v[188:191], v[2:17]
	ds_read_b64_tr_b16 v[242:243], v116 offset:61440
	ds_read_b64_tr_b16 v[244:245], v117 offset:61440
	v_cvt_pk_bf16_f32 v197, v76, v77
	v_cvt_pk_bf16_f32 v198, v78, v79
	v_cvt_pk_bf16_f32 v199, v80, v81
	s_waitcnt lgkmcnt(8)
	v_mfma_f32_32x32x16_bf16 v[50:65], v[136:139], v[192:195], v[50:65]
	ds_read_b64_tr_b16 v[246:247], v118 offset:61440
	ds_read_b64_tr_b16 v[248:249], v119 offset:61440
	v_add_f32_e32 v0, v66, v67
	v_add_f32_e32 v203, v68, v69
	v_add_f32_e32 v0, v0, v70
	v_mfma_f32_32x32x16_bf16 v[34:49], v[140:143], v[192:195], v[34:49]
	ds_read_b64_tr_b16 v[250:251], v120 offset:61440
	ds_read_b64_tr_b16 v[252:253], v121 offset:61440
	v_add_f32_e32 v203, v203, v71
	v_add_f32_e32 v0, v0, v72
	v_add_f32_e32 v203, v203, v73
	s_waitcnt lgkmcnt(8)
	v_mfma_f32_32x32x16_bf16 v[18:33], v[204:207], v[192:195], v[18:33]
	v_add_f32_e32 v0, v0, v203
	v_add_f32_e32 v167, v167, v0
	v_add_f32_e32 v0, v74, v75
	v_mfma_f32_32x32x16_bf16 v[2:17], v[208:211], v[192:195], v[2:17]
	v_add_f32_e32 v203, v76, v77
	v_add_f32_e32 v0, v0, v78
	v_add_f32_e32 v203, v203, v79
	s_waitcnt lgkmcnt(4)
	v_mfma_f32_32x32x16_bf16 v[50:65], v[238:241], v[196:199], v[50:65]
	v_add_f32_e32 v0, v0, v80
	v_add_f32_e32 v203, v203, v81
	v_add_f32_e32 v0, v0, v203
	v_mfma_f32_32x32x16_bf16 v[34:49], v[242:245], v[196:199], v[34:49]
	v_add_f32_e32 v167, v167, v0
	s_waitcnt lgkmcnt(0)
	v_mfma_f32_32x32x16_bf16 v[18:33], v[246:249], v[196:199], v[18:33]
	v_mfma_f32_32x32x16_bf16 v[2:17], v[250:253], v[196:199], v[2:17]
	ds_read_b128 v[136:139], v178 offset:0
	ds_read_b128 v[140:143], v178 offset:8192
	ds_read_b128 v[204:207], v181 offset:0
	ds_read_b128 v[208:211], v181 offset:8192
	ds_read_b128 v[238:241], v180 offset:0
	ds_read_b128 v[242:245], v180 offset:8192
	ds_read_b128 v[246:249], v179 offset:0
	ds_read_b128 v[250:253], v179 offset:8192
	s_waitcnt vmcnt(6)
	s_add_i32 s50, s50, 64
	s_add_i32 s51, s50, 384
	s_cmp_le_u32 s51, s2
	s_barrier
	s_cbranch_scc1 .Lat2_U_top

; #define LAS __attribute__((address_space(3)))
; __device__ __forceinline__ void attn_block(LAS unsigned char* lds, const bf16_t* P, bf16_t* mix, int b, int h, int qb, float lam, float outscale, const float* subln) {
;     ...
;     for (int kt = 0; kt < ntiles; ++kt) {
;         __syncthreads();
;         const int buf = kt & 1;
;         if (kt + 1 < ntiles) {
;             const size_t ro = (size_t)(64 * (kt + 1)) * INC;
;             kr0 = *(const u32x4*)(kg + ro + (size_t)srow * INC); kr1 = *(const u32x4*)(kg + ro + (size_t)(srow + 32) * INC);
;             vr0 = *(const u32x4*)(vg + ro + (size_t)srow * INC); vr1 = *(const u32x4*)(vg + ro + (size_t)(srow + 32) * INC);
;         }
;         const int kb = 64 * kt;
;         if (kb <= qw0 + 31) {
;             LAS const unsigned char* Kb = lds + ATT_K0 + buf * 16384;
;             LAS const unsigned char* Vb = lds + ATT_V0 + buf * 16384;
;             f32x16 s0, s1;
; #pragma unroll
;             for (int j = 0; j < 16; ++j) { s0[j] = 0.f; s1[j] = 0.f; }
;             bf16x8 ka[4][2];
; #pragma unroll
;             for (int ks = 0; ks < 4; ++ks) { ka[ks][0] = *(const LAS bf16x8*)(Kb + kbase[ks]); ka[ks][1] = *(const LAS bf16x8*)(Kb + kbase[ks] + 8192); }
;             __builtin_amdgcn_sched_barrier(0);
; #pragma unroll
;             for (int ks = 0; ks < 4; ++ks) {
;                 s0 = __builtin_amdgcn_mfma_f32_32x32x16_bf16(ka[ks][0], qf[ks], s0, 0, 0, 0);
;                 s1 = __builtin_amdgcn_mfma_f32_32x32x16_bf16(ka[ks][1], qf[ks], s1, 0, 0, 0);
;             }
;             if (kb + 63 > qw0) {
; #pragma unroll
;                 for (int j = 0; j < 16; ++j) { const int key = kb + crow(j, hi); if (key > qrow) s0[j] = -INFINITY; if (key + 32 > qrow) s1[j] = -INFINITY; }
;             }
;             float mxa = max3f(s0[0], s1[0], s0[1]), mxb = max3f(s1[1], s0[2], s1[2]), mxc = max3f(s0[3], s1[3], s0[4]), mxd = max3f(s1[4], s0[5], s1[5]);
;             mxa = max3f(mxa, s0[6], s1[6]); mxb = max3f(mxb, s0[7], s1[7]); mxc = max3f(mxc, s0[8], s1[8]); mxd = max3f(mxd, s0[9], s1[9]);
;             mxa = max3f(mxa, s0[10], s1[10]); mxb = max3f(mxb, s0[11], s1[11]); mxc = max3f(mxc, s0[12], s1[12]); mxd = max3f(mxd, s0[13], s1[13]);
;             mxa = max3f(mxa, s0[14], s1[14]); mxb = max3f(mxb, s0[15], s1[15]);
;             float mx = max3f(mxa, mxb, max3f(mxc, mxd, mxd));
.Lat2_S_top:
	s_add_i32 s62, s50, 192
	s_lshl_b32 s39, s62, 8
	s_lshl_b32 s62, s62, 9
	s_and_b32 s39, s39, 0x4000
	s_and_b32 s62, s62, 0x10000
	s_or_b32 s62, s62, s39
	s_lshl_b32 s39, s33, 4
	s_and_b32 s39, s39, 0x1c00
	s_add_i32 s62, s62, s39
	s_add_i32 m0, s62, 0x0
	s_nop 0
	global_load_lds_dwordx4 v[134:135], off
	s_add_i32 m0, s62, 0x2000
	s_nop 0
	global_load_lds_dwordx4 v[200:201], off
	s_lshl_b32 s39, s50, 8
	s_lshl_b32 s51, s50, 9
	s_and_b32 s39, s39, 0x4000
	s_and_b32 s51, s51, 0x10000
	s_or_b32 s51, s51, s39
	s_waitcnt lgkmcnt(6)
	v_mfma_f32_32x32x16_bf16 v[82:97], v[136:139], v[110:113], v[222:237]
	v_mfma_f32_32x32x16_bf16 v[66:81], v[140:143], v[110:113], v[222:237]
	s_waitcnt lgkmcnt(4)
	v_mfma_f32_32x32x16_bf16 v[82:97], v[204:207], v[106:109], v[82:97]
	v_mfma_f32_32x32x16_bf16 v[66:81], v[208:211], v[106:109], v[66:81]
	s_waitcnt lgkmcnt(2)
	v_mfma_f32_32x32x16_bf16 v[82:97], v[238:241], v[102:105], v[82:97]
	v_mfma_f32_32x32x16_bf16 v[66:81], v[242:245], v[102:105], v[66:81]
	s_waitcnt lgkmcnt(0)
	v_mfma_f32_32x32x16_bf16 v[82:97], v[246:249], v[98:101], v[82:97]
	v_mfma_f32_32x32x16_bf16 v[66:81], v[250:253], v[98:101], v[66:81]
	v_add_u32_e32 v114, s51, v168
	v_add_u32_e32 v115, s51, v175
	v_add_u32_e32 v116, s51, v172
	v_add_u32_e32 v117, s51, v174
	v_add_u32_e32 v118, s51, v170
	v_add_u32_e32 v119, s51, v173
	v_add_u32_e32 v120, s51, v169
	v_add_u32_e32 v121, s51, v171
	s_nop 3
	v_max3_f32 v122, v82, v66, v83
	v_max3_f32 v123, v67, v84, v68
	v_max3_f32 v124, v85, v69, v86
	v_max3_f32 v125, v70, v87, v71
	v_max3_f32 v122, v122, v88, v72
	v_max3_f32 v123, v123, v89, v73
	v_max3_f32 v124, v124, v90, v74
	v_max3_f32 v125, v125, v91, v75
	v_max3_f32 v122, v122, v92, v76
	v_max3_f32 v123, v123, v93, v77
	v_max3_f32 v124, v124, v94, v78
	v_max3_f32 v125, v125, v95, v79
	v_max3_f32 v122, v122, v96, v80
	v_max3_f32 v123, v123, v97, v81
	v_max3_f32 v122, v122, v123, v124
	v_max_f32_e32 v122, v122, v125
	v_mov_b32_e32 v203, v122
	s_nop 1
	v_permlane32_swap_b32_e32 v122, v203
	s_nop 1
	v_max_f32_e32 v122, v122, v203
	s_mov_b32 s39, 0
	v_cmp_lt_f32_e32 vcc, 0x41000000, v122
	s_cmp_eq_u32 s50, 0
	s_cbranch_scc1 .Lat2_sA_first
	s_cbranch_vccz .Lat2_sA_norescale
	s_branch .Lat2_sA_rescale

; #define LAS __attribute__((address_space(3)))
; __device__ __forceinline__ unsigned pk2(float lo, float hi) { f32x2 v = {lo, hi}; bf16x2_t b = __builtin_convertvector(v, bf16x2_t); return __builtin_bit_cast(unsigned, b); }
; __device__ __forceinline__ s16x4 vtr(LAS const unsigned char* p) { return __builtin_bit_cast(s16x4, __builtin_amdgcn_ds_read_tr16_b64_v4i16((LAS v4i16_t*)p)); }
; __device__ __forceinline__ void attn_block(LAS unsigned char* lds, const bf16_t* P, bf16_t* mix, int b, int h, int qb, float lam, float outscale, const float* subln) {
;     ...
;             for (int j = 0; j < 16; ++j) { s0[j] = __builtin_amdgcn_exp2f(s0[j] - mrun); s1[j] = __builtin_amdgcn_exp2f(s1[j] - mrun); }
;             float ps0 = 0.f, ps1 = 0.f, ps2 = 0.f, ps3 = 0.f;
; #pragma unroll
;             for (int j = 0; j < 16; j += 2) { ps0 += s0[j]; ps1 += s1[j]; ps2 += s0[j + 1]; ps3 += s1[j + 1]; }
;             lrun += (ps0 + ps1) + (ps2 + ps3);
;             bf16x8 pb[4];
; #pragma unroll
;             for (int s2 = 0; s2 < 2; ++s2) {
;                 u32x4 w0, w1;
;                 w0.x = pk2(s0[8 * s2 + 0], s0[8 * s2 + 1]); w0.y = pk2(s0[8 * s2 + 2], s0[8 * s2 + 3]); w0.z = pk2(s0[8 * s2 + 4], s0[8 * s2 + 5]); w0.w = pk2(s0[8 * s2 + 6], s0[8 * s2 + 7]);
;                 w1.x = pk2(s1[8 * s2 + 0], s1[8 * s2 + 1]); w1.y = pk2(s1[8 * s2 + 2], s1[8 * s2 + 3]); w1.z = pk2(s1[8 * s2 + 4], s1[8 * s2 + 5]); w1.w = pk2(s1[8 * s2 + 6], s1[8 * s2 + 7]);
;                 pb[s2] = __builtin_bit_cast(bf16x8, w0); pb[2 + s2] = __builtin_bit_cast(bf16x8, w1);
;             }
; #pragma unroll
;             for (int s = 0; s < 4; ++s) {
; #pragma unroll
;                 for (int c = 0; c < 4; ++c) {
;                     const s16x4 v0 = vtr(Vb + vbase[c][0] + 4096 * s);
;                     const s16x4 v1 = vtr(Vb + vbase[c][1] + 4096 * s);
;                     o[c] = __builtin_amdgcn_mfma_f32_32x32x16_bf16(cat8(v0, v1), pb[s], o[c], 0, 0, 0);
;                 }
;             }
;         }
;         if (kt + 1 < ntiles) {
;             const int nb = (kt + 1) & 1;
;             *(LAS u32x4*)(lds + ATT_K0 + nb * 16384 + so0) = kr0; *(LAS u32x4*)(lds + ATT_K0 + nb * 16384 + so1) = kr1;
;             *(LAS u32x4*)(lds + ATT_V0 + nb * 16384 + so0) = vr0; *(LAS u32x4*)(lds + ATT_V0 + nb * 16384 + so1) = vr1;
;         }
.Lat2_sA_norescale:
	ds_read_b64_tr_b16 v[136:137], v114 offset:32768
	ds_read_b64_tr_b16 v[138:139], v115 offset:32768
	ds_read_b64_tr_b16 v[140:141], v116 offset:32768
	ds_read_b64_tr_b16 v[142:143], v117 offset:32768
	ds_read_b64_tr_b16 v[204:205], v118 offset:32768
	ds_read_b64_tr_b16 v[206:207], v119 offset:32768
	ds_read_b64_tr_b16 v[208:209], v120 offset:32768
	ds_read_b64_tr_b16 v[210:211], v121 offset:32768
	ds_read_b64_tr_b16 v[238:239], v114 offset:36864
	ds_read_b64_tr_b16 v[240:241], v115 offset:36864
	ds_read_b64_tr_b16 v[242:243], v116 offset:36864
	ds_read_b64_tr_b16 v[244:245], v117 offset:36864
	v_exp_f32_e32 v82, v82
	v_exp_f32_e32 v83, v83
	v_exp_f32_e32 v84, v84
	v_exp_f32_e32 v85, v85
	v_exp_f32_e32 v86, v86
	v_exp_f32_e32 v87, v87
	v_exp_f32_e32 v88, v88
	v_exp_f32_e32 v89, v89
	v_exp_f32_e32 v90, v90
	v_exp_f32_e32 v91, v91
	v_exp_f32_e32 v92, v92
	v_exp_f32_e32 v93, v93
	v_exp_f32_e32 v94, v94
	v_exp_f32_e32 v95, v95
	v_exp_f32_e32 v96, v96
	v_exp_f32_e32 v97, v97
	v_cvt_pk_bf16_f32 v184, v82, v83
	v_cvt_pk_bf16_f32 v185, v84, v85
	v_cvt_pk_bf16_f32 v186, v86, v87
	v_cvt_pk_bf16_f32 v187, v88, v89
	v_cvt_pk_bf16_f32 v188, v90, v91
	v_cvt_pk_bf16_f32 v189, v92, v93
	v_cvt_pk_bf16_f32 v190, v94, v95
	v_cvt_pk_bf16_f32 v191, v96, v97
	v_add_f32_e32 v122, v82, v83
	v_add_f32_e32 v123, v84, v85
	v_add_f32_e32 v122, v122, v86
	v_add_f32_e32 v123, v123, v87
	v_add_f32_e32 v122, v122, v88
	v_add_f32_e32 v123, v123, v89
	v_add_f32_e32 v122, v122, v123
	v_add_f32_e32 v167, v167, v122
	v_add_f32_e32 v124, v90, v91
	v_add_f32_e32 v125, v92, v93
	v_add_f32_e32 v124, v124, v94
	v_add_f32_e32 v125, v125, v95
	v_add_f32_e32 v124, v124, v96
	v_add_f32_e32 v125, v125, v97
	v_add_f32_e32 v124, v124, v125
	v_add_f32_e32 v167, v167, v124
	s_add_i32 m0, s62, 0x7800
	s_nop 0
	global_load_lds_dwordx4 v[134:135], off offset:2048
	s_add_i32 m0, s62, 0x9800
	s_nop 0
	global_load_lds_dwordx4 v[200:201], off offset:2048
	v_lshl_add_u64 v[134:135], v[134:135], 0, s[40:41]
	v_lshl_add_u64 v[200:201], v[200:201], 0, s[40:41]
	s_waitcnt lgkmcnt(8)
	v_mfma_f32_32x32x16_bf16 v[50:65], v[136:139], v[184:187], v[50:65]
	ds_read_b64_tr_b16 v[246:247], v118 offset:36864
	ds_read_b64_tr_b16 v[248:249], v119 offset:36864
	v_exp_f32_e32 v66, v66
	v_exp_f32_e32 v67, v67
	v_exp_f32_e32 v68, v68
	v_mfma_f32_32x32x16_bf16 v[34:49], v[140:143], v[184:187], v[34:49]
	ds_read_b64_tr_b16 v[250:251], v120 offset:36864
	ds_read_b64_tr_b16 v[252:253], v121 offset:36864
	v_exp_f32_e32 v69, v69
	v_exp_f32_e32 v70, v70
	v_exp_f32_e32 v71, v71
	s_waitcnt lgkmcnt(8)
	v_mfma_f32_32x32x16_bf16 v[18:33], v[204:207], v[184:187], v[18:33]
	ds_read_b64_tr_b16 v[136:137], v114 offset:40960
	ds_read_b64_tr_b16 v[138:139], v115 offset:40960
	v_exp_f32_e32 v72, v72
	v_exp_f32_e32 v73, v73
	v_cvt_pk_bf16_f32 v192, v66, v67
	v_mfma_f32_32x32x16_bf16 v[2:17], v[208:211], v[184:187], v[2:17]
	ds_read_b64_tr_b16 v[140:141], v116 offset:40960
	ds_read_b64_tr_b16 v[142:143], v117 offset:40960
	v_cvt_pk_bf16_f32 v193, v68, v69
	v_cvt_pk_bf16_f32 v194, v70, v71
	v_cvt_pk_bf16_f32 v195, v72, v73
	s_waitcnt lgkmcnt(8)
	v_mfma_f32_32x32x16_bf16 v[50:65], v[238:241], v[188:191], v[50:65]
	ds_read_b64_tr_b16 v[204:205], v118 offset:40960
	ds_read_b64_tr_b16 v[206:207], v119 offset:40960
	v_exp_f32_e32 v74, v74
	v_exp_f32_e32 v75, v75
	v_exp_f32_e32 v76, v76
	v_mfma_f32_32x32x16_bf16 v[34:49], v[242:245], v[188:191], v[34:49]
	ds_read_b64_tr_b16 v[208:209], v120 offset:40960
	ds_read_b64_tr_b16 v[210:211], v121 offset:40960
	v_exp_f32_e32 v77, v77
	v_exp_f32_e32 v78, v78
	v_exp_f32_e32 v79, v79
	s_waitcnt lgkmcnt(8)
	v_mfma_f32_32x32x16_bf16 v[18:33], v[246:249], v[188:191], v[18:33]
	ds_read_b64_tr_b16 v[238:239], v114 offset:45056
	ds_read_b64_tr_b16 v[240:241], v115 offset:45056
	v_exp_f32_e32 v80, v80
	v_exp_f32_e32 v81, v81
	v_cvt_pk_bf16_f32 v196, v74, v75
	v_mfma_f32_32x32x16_bf16 v[2:17], v[250:253], v[188:191], v[2:17]
	ds_read_b64_tr_b16 v[242:243], v116 offset:45056
	ds_read_b64_tr_b16 v[244:245], v117 offset:45056
	v_cvt_pk_bf16_f32 v197, v76, v77
	v_cvt_pk_bf16_f32 v198, v78, v79
	v_cvt_pk_bf16_f32 v199, v80, v81
	s_waitcnt lgkmcnt(8)
	v_mfma_f32_32x32x16_bf16 v[50:65], v[136:139], v[192:195], v[50:65]
	ds_read_b64_tr_b16 v[246:247], v118 offset:45056
	ds_read_b64_tr_b16 v[248:249], v119 offset:45056
	v_add_f32_e32 v0, v66, v67
	v_add_f32_e32 v203, v68, v69
	v_add_f32_e32 v0, v0, v70
	v_mfma_f32_32x32x16_bf16 v[34:49], v[140:143], v[192:195], v[34:49]
	ds_read_b64_tr_b16 v[250:251], v120 offset:45056
	ds_read_b64_tr_b16 v[252:253], v121 offset:45056
	v_add_f32_e32 v203, v203, v71
	v_add_f32_e32 v0, v0, v72
	v_add_f32_e32 v203, v203, v73
	s_waitcnt lgkmcnt(8)
	v_mfma_f32_32x32x16_bf16 v[18:33], v[204:207], v[192:195], v[18:33]
	v_add_f32_e32 v0, v0, v203
	v_add_f32_e32 v167, v167, v0
	v_add_f32_e32 v0, v74, v75
	v_mfma_f32_32x32x16_bf16 v[2:17], v[208:211], v[192:195], v[2:17]
	v_add_f32_e32 v203, v76, v77
	v_add_f32_e32 v0, v0, v78
	v_add_f32_e32 v203, v203, v79
	s_waitcnt lgkmcnt(4)
	v_mfma_f32_32x32x16_bf16 v[50:65], v[238:241], v[196:199], v[50:65]
	v_add_f32_e32 v0, v0, v80
	v_add_f32_e32 v203, v203, v81
	v_add_f32_e32 v0, v0, v203
	v_mfma_f32_32x32x16_bf16 v[34:49], v[242:245], v[196:199], v[34:49]
	v_add_f32_e32 v167, v167, v0
	s_waitcnt lgkmcnt(0)
	v_mfma_f32_32x32x16_bf16 v[18:33], v[246:249], v[196:199], v[18:33]
	v_mfma_f32_32x32x16_bf16 v[2:17], v[250:253], v[196:199], v[2:17]
	s_add_i32 s62, s50, 64
	s_lshl_b32 s39, s62, 8
	s_lshl_b32 s62, s62, 9
	s_and_b32 s39, s39, 0x4000
	s_and_b32 s62, s62, 0x10000
	s_or_b32 s62, s62, s39
	v_add_u32_e32 v0, s62, v178
	ds_read_b128 v[136:139], v0
	ds_read_b128 v[140:143], v0 offset:8192
	v_add_u32_e32 v0, s62, v181
	ds_read_b128 v[204:207], v0
	ds_read_b128 v[208:211], v0 offset:8192
	v_add_u32_e32 v0, s62, v180
	ds_read_b128 v[238:241], v0
	ds_read_b128 v[242:245], v0 offset:8192
	v_add_u32_e32 v0, s62, v179
	ds_read_b128 v[246:249], v0
	ds_read_b128 v[250:253], v0 offset:8192

; #define LAS __attribute__((address_space(3)))
; __device__ __forceinline__ void attn_block(LAS unsigned char* lds, const bf16_t* P, bf16_t* mix, int b, int h, int qb, float lam, float outscale, const float* subln) {
;     ...
;     for (int kt = 0; kt < ntiles; ++kt) {
;         __syncthreads();
;         const int buf = kt & 1;
;         if (kt + 1 < ntiles) {
;             const size_t ro = (size_t)(64 * (kt + 1)) * INC;
;             kr0 = *(const u32x4*)(kg + ro + (size_t)srow * INC); kr1 = *(const u32x4*)(kg + ro + (size_t)(srow + 32) * INC);
;             vr0 = *(const u32x4*)(vg + ro + (size_t)srow * INC); vr1 = *(const u32x4*)(vg + ro + (size_t)(srow + 32) * INC);
;         }
;         const int kb = 64 * kt;
;         if (kb <= qw0 + 31) {
;             LAS const unsigned char* Kb = lds + ATT_K0 + buf * 16384;
;             LAS const unsigned char* Vb = lds + ATT_V0 + buf * 16384;
;             f32x16 s0, s1;
; #pragma unroll
;             for (int j = 0; j < 16; ++j) { s0[j] = 0.f; s1[j] = 0.f; }
;             bf16x8 ka[4][2];
; #pragma unroll
;             for (int ks = 0; ks < 4; ++ks) { ka[ks][0] = *(const LAS bf16x8*)(Kb + kbase[ks]); ka[ks][1] = *(const LAS bf16x8*)(Kb + kbase[ks] + 8192); }
;             __builtin_amdgcn_sched_barrier(0);
; #pragma unroll
;             for (int ks = 0; ks < 4; ++ks) {
;                 s0 = __builtin_amdgcn_mfma_f32_32x32x16_bf16(ka[ks][0], qf[ks], s0, 0, 0, 0);
;                 s1 = __builtin_amdgcn_mfma_f32_32x32x16_bf16(ka[ks][1], qf[ks], s1, 0, 0, 0);
;             }
;             if (kb + 63 > qw0) {
; #pragma unroll
;                 for (int j = 0; j < 16; ++j) { const int key = kb + crow(j, hi); if (key > qrow) s0[j] = -INFINITY; if (key + 32 > qrow) s1[j] = -INFINITY; }
;             }
;             float mxa = max3f(s0[0], s1[0], s0[1]), mxb = max3f(s1[1], s0[2], s1[2]), mxc = max3f(s0[3], s1[3], s0[4]), mxd = max3f(s1[4], s0[5], s1[5]);
;             mxa = max3f(mxa, s0[6], s1[6]); mxb = max3f(mxb, s0[7], s1[7]); mxc = max3f(mxc, s0[8], s1[8]); mxd = max3f(mxd, s0[9], s1[9]);
;             mxa = max3f(mxa, s0[10], s1[10]); mxb = max3f(mxb, s0[11], s1[11]); mxc = max3f(mxc, s0[12], s1[12]); mxd = max3f(mxd, s0[13], s1[13]);
;             mxa = max3f(mxa, s0[14], s1[14]); mxb = max3f(mxb, s0[15], s1[15]);
;             float mx = max3f(mxa, mxb, max3f(mxc, mxd, mxd));
.Lat2_T_top:
	s_add_i32 s62, s50, 192
	s_cmp_le_u32 s62, s2
	s_cbranch_scc0 .Lat2_tA_noload
	s_add_i32 s62, s50, 192
	s_lshl_b32 s39, s62, 8
	s_lshl_b32 s62, s62, 9
	s_and_b32 s39, s39, 0x4000
	s_and_b32 s62, s62, 0x10000
	s_or_b32 s62, s62, s39
	s_lshl_b32 s39, s33, 4
	s_and_b32 s39, s39, 0x1c00
	s_add_i32 s62, s62, s39
	s_add_i32 m0, s62, 0x0
	s_nop 0
	global_load_lds_dwordx4 v[134:135], off
	s_add_i32 m0, s62, 0x2000
	s_nop 0
	global_load_lds_dwordx4 v[200:201], off
.Lat2_tA_noload:
	s_lshl_b32 s39, s50, 8
	s_lshl_b32 s51, s50, 9
	s_and_b32 s39, s39, 0x4000
	s_and_b32 s51, s51, 0x10000
	s_or_b32 s51, s51, s39
	s_cmp_gt_u32 s50, s38
	s_cbranch_scc1 .Lat2_tB_skip
	s_waitcnt lgkmcnt(6)
	v_mfma_f32_32x32x16_bf16 v[82:97], v[136:139], v[110:113], v[222:237]
	v_mfma_f32_32x32x16_bf16 v[66:81], v[140:143], v[110:113], v[222:237]
	s_waitcnt lgkmcnt(4)
	v_mfma_f32_32x32x16_bf16 v[82:97], v[204:207], v[106:109], v[82:97]
	v_mfma_f32_32x32x16_bf16 v[66:81], v[208:211], v[106:109], v[66:81]
	s_waitcnt lgkmcnt(2)
	v_mfma_f32_32x32x16_bf16 v[82:97], v[238:241], v[102:105], v[82:97]
	v_mfma_f32_32x32x16_bf16 v[66:81], v[242:245], v[102:105], v[66:81]
	s_waitcnt lgkmcnt(0)
	v_mfma_f32_32x32x16_bf16 v[82:97], v[246:249], v[98:101], v[82:97]
	v_mfma_f32_32x32x16_bf16 v[66:81], v[250:253], v[98:101], v[66:81]
	v_add_u32_e32 v114, s51, v168
	v_add_u32_e32 v115, s51, v175
	v_add_u32_e32 v116, s51, v172
	v_add_u32_e32 v117, s51, v174
	v_add_u32_e32 v118, s51, v170
	v_add_u32_e32 v119, s51, v173
	v_add_u32_e32 v120, s51, v169
	v_add_u32_e32 v121, s51, v171
	s_nop 3
	s_add_i32 s62, s50, 63
	s_cmp_gt_u32 s62, s61
	s_cbranch_scc0 .Lat2_tA_nomask
	v_add_u32_e32 v0, s50, v164
	v_sub_u32_e32 v0, v177, v0
	v_cmp_le_i32_e32 vcc, 0, v0
	s_nop 1
	v_cndmask_b32_e32 v82, v218, v82, vcc
	v_cmp_le_i32_e32 vcc, 1, v0
	s_nop 1
	v_cndmask_b32_e32 v83, v218, v83, vcc
	v_cmp_le_i32_e32 vcc, 2, v0
	s_nop 1
	v_cndmask_b32_e32 v84, v218, v84, vcc
	v_cmp_le_i32_e32 vcc, 3, v0
	s_nop 1
	v_cndmask_b32_e32 v85, v218, v85, vcc
	v_cmp_le_i32_e32 vcc, 8, v0
	s_nop 1
	v_cndmask_b32_e32 v86, v218, v86, vcc
	v_cmp_le_i32_e32 vcc, 9, v0
	s_nop 1
	v_cndmask_b32_e32 v87, v218, v87, vcc
	v_cmp_le_i32_e32 vcc, 10, v0
	s_nop 1
	v_cndmask_b32_e32 v88, v218, v88, vcc
	v_cmp_le_i32_e32 vcc, 11, v0
	s_nop 1
	v_cndmask_b32_e32 v89, v218, v89, vcc
	v_cmp_le_i32_e32 vcc, 16, v0
	s_nop 1
	v_cndmask_b32_e32 v90, v218, v90, vcc
	v_cmp_le_i32_e32 vcc, 17, v0
	s_nop 1
	v_cndmask_b32_e32 v91, v218, v91, vcc
	v_cmp_le_i32_e32 vcc, 18, v0
	s_nop 1
	v_cndmask_b32_e32 v92, v218, v92, vcc
	v_cmp_le_i32_e32 vcc, 19, v0
	s_nop 1
	v_cndmask_b32_e32 v93, v218, v93, vcc
	v_cmp_le_i32_e32 vcc, 24, v0
	s_nop 1
	v_cndmask_b32_e32 v94, v218, v94, vcc
	v_cmp_le_i32_e32 vcc, 25, v0
	s_nop 1
	v_cndmask_b32_e32 v95, v218, v95, vcc
	v_cmp_le_i32_e32 vcc, 26, v0
	s_nop 1
	v_cndmask_b32_e32 v96, v218, v96, vcc
	v_cmp_le_i32_e32 vcc, 27, v0
	s_nop 1
	v_cndmask_b32_e32 v97, v218, v97, vcc
	v_cmp_le_i32_e32 vcc, 32, v0
	s_nop 1
	v_cndmask_b32_e32 v66, v218, v66, vcc
	v_cmp_le_i32_e32 vcc, 33, v0
	s_nop 1
	v_cndmask_b32_e32 v67, v218, v67, vcc
	v_cmp_le_i32_e32 vcc, 34, v0
	s_nop 1
	v_cndmask_b32_e32 v68, v218, v68, vcc
	v_cmp_le_i32_e32 vcc, 35, v0
	s_nop 1
	v_cndmask_b32_e32 v69, v218, v69, vcc
	v_cmp_le_i32_e32 vcc, 40, v0
	s_nop 1
	v_cndmask_b32_e32 v70, v218, v70, vcc
	v_cmp_le_i32_e32 vcc, 41, v0
	s_nop 1
	v_cndmask_b32_e32 v71, v218, v71, vcc
	v_cmp_le_i32_e32 vcc, 42, v0
	s_nop 1
	v_cndmask_b32_e32 v72, v218, v72, vcc
	v_cmp_le_i32_e32 vcc, 43, v0
	s_nop 1
	v_cndmask_b32_e32 v73, v218, v73, vcc
	v_cmp_le_i32_e32 vcc, 48, v0
	s_nop 1
	v_cndmask_b32_e32 v74, v218, v74, vcc
	v_cmp_le_i32_e32 vcc, 49, v0
	s_nop 1
	v_cndmask_b32_e32 v75, v218, v75, vcc
	v_cmp_le_i32_e32 vcc, 50, v0
	s_nop 1
	v_cndmask_b32_e32 v76, v218, v76, vcc
	v_cmp_le_i32_e32 vcc, 51, v0
	s_nop 1
	v_cndmask_b32_e32 v77, v218, v77, vcc
	v_cmp_le_i32_e32 vcc, 56, v0
	s_nop 1
	v_cndmask_b32_e32 v78, v218, v78, vcc
	v_cmp_le_i32_e32 vcc, 57, v0
	s_nop 1
	v_cndmask_b32_e32 v79, v218, v79, vcc
	v_cmp_le_i32_e32 vcc, 58, v0
	s_nop 1
	v_cndmask_b32_e32 v80, v218, v80, vcc
	v_cmp_le_i32_e32 vcc, 59, v0
	s_nop 1
	v_cndmask_b32_e32 v81, v218, v81, vcc
.Lat2_tA_nomask:
	v_max3_f32 v122, v82, v66, v83
	v_max3_f32 v123, v67, v84, v68
	v_max3_f32 v124, v85, v69, v86
	v_max3_f32 v125, v70, v87, v71
	v_max3_f32 v122, v122, v88, v72
	v_max3_f32 v123, v123, v89, v73
	v_max3_f32 v124, v124, v90, v74
	v_max3_f32 v125, v125, v91, v75
	v_max3_f32 v122, v122, v92, v76
	v_max3_f32 v123, v123, v93, v77
	v_max3_f32 v124, v124, v94, v78
	v_max3_f32 v125, v125, v95, v79
	v_max3_f32 v122, v122, v96, v80
	v_max3_f32 v123, v123, v97, v81
	v_max3_f32 v122, v122, v123, v124
	v_max_f32_e32 v122, v122, v125
	v_mov_b32_e32 v203, v122
	s_nop 1
	v_permlane32_swap_b32_e32 v122, v203
	s_nop 1
	v_max_f32_e32 v122, v122, v203
	s_mov_b32 s39, 0
	v_cmp_lt_f32_e32 vcc, 0x41000000, v122
	s_cmp_eq_u32 s50, 0
	s_cbranch_scc1 .Lat2_tA_first
	s_cbranch_vccz .Lat2_tA_norescale
	s_branch .Lat2_tA_rescale

; #define LAS __attribute__((address_space(3)))
; __device__ __forceinline__ s16x4 vtr(LAS const unsigned char* p) { return __builtin_bit_cast(s16x4, __builtin_amdgcn_ds_read_tr16_b64_v4i16((LAS v4i16_t*)p)); }
; __device__ __forceinline__ bf16x8 cat8(s16x4 a, s16x4 b) { return (bf16x8){a[0], a[1], a[2], a[3], b[0], b[1], b[2], b[3]}; }
; __device__ __forceinline__ void attn_block(LAS unsigned char* lds, const bf16_t* P, bf16_t* mix, int b, int h, int qb, float lam, float outscale, const float* subln) {
;     ...
; #pragma unroll
;             for (int s = 0; s < 4; ++s) {
; #pragma unroll
;                 for (int c = 0; c < 4; ++c) {
;                     const s16x4 v0 = vtr(Vb + vbase[c][0] + 4096 * s);
;                     const s16x4 v1 = vtr(Vb + vbase[c][1] + 4096 * s);
;                     o[c] = __builtin_amdgcn_mfma_f32_32x32x16_bf16(cat8(v0, v1), pb[s], o[c], 0, 0, 0);
;                 }
;             }
;         }
;         if (kt + 1 < ntiles) {
;             const int nb = (kt + 1) & 1;
;             *(LAS u32x4*)(lds + ATT_K0 + nb * 16384 + so0) = kr0; *(LAS u32x4*)(lds + ATT_K0 + nb * 16384 + so1) = kr1;
;             *(LAS u32x4*)(lds + ATT_V0 + nb * 16384 + so0) = vr0; *(LAS u32x4*)(lds + ATT_V0 + nb * 16384 + so1) = vr1;
;         }
.Lat2_tB_noload:
	s_cmp_gt_u32 s50, s38
	s_cbranch_scc1 .Lat2_tB_end
	s_waitcnt lgkmcnt(8)
	v_mfma_f32_32x32x16_bf16 v[50:65], v[136:139], v[184:187], v[50:65]
	ds_read_b64_tr_b16 v[246:247], v118 offset:36864
	ds_read_b64_tr_b16 v[248:249], v119 offset:36864
	v_exp_f32_e32 v66, v66
	v_exp_f32_e32 v67, v67
	v_exp_f32_e32 v68, v68
	v_mfma_f32_32x32x16_bf16 v[34:49], v[140:143], v[184:187], v[34:49]
	ds_read_b64_tr_b16 v[250:251], v120 offset:36864
	ds_read_b64_tr_b16 v[252:253], v121 offset:36864
	v_exp_f32_e32 v69, v69
	v_exp_f32_e32 v70, v70
	v_exp_f32_e32 v71, v71
	s_waitcnt lgkmcnt(8)
	v_mfma_f32_32x32x16_bf16 v[18:33], v[204:207], v[184:187], v[18:33]
	ds_read_b64_tr_b16 v[136:137], v114 offset:40960
	ds_read_b64_tr_b16 v[138:139], v115 offset:40960
	v_exp_f32_e32 v72, v72
	v_exp_f32_e32 v73, v73
	v_cvt_pk_bf16_f32 v192, v66, v67
	v_mfma_f32_32x32x16_bf16 v[2:17], v[208:211], v[184:187], v[2:17]
	ds_read_b64_tr_b16 v[140:141], v116 offset:40960
	ds_read_b64_tr_b16 v[142:143], v117 offset:40960
	v_cvt_pk_bf16_f32 v193, v68, v69
	v_cvt_pk_bf16_f32 v194, v70, v71
	v_cvt_pk_bf16_f32 v195, v72, v73
	s_waitcnt lgkmcnt(8)
	v_mfma_f32_32x32x16_bf16 v[50:65], v[238:241], v[188:191], v[50:65]
	ds_read_b64_tr_b16 v[204:205], v118 offset:40960
	ds_read_b64_tr_b16 v[206:207], v119 offset:40960
	v_exp_f32_e32 v74, v74
	v_exp_f32_e32 v75, v75
	v_exp_f32_e32 v76, v76
	v_mfma_f32_32x32x16_bf16 v[34:49], v[242:245], v[188:191], v[34:49]
	ds_read_b64_tr_b16 v[208:209], v120 offset:40960
	ds_read_b64_tr_b16 v[210:211], v121 offset:40960
	v_exp_f32_e32 v77, v77
	v_exp_f32_e32 v78, v78
	v_exp_f32_e32 v79, v79
	s_waitcnt lgkmcnt(8)
	v_mfma_f32_32x32x16_bf16 v[18:33], v[246:249], v[188:191], v[18:33]
	ds_read_b64_tr_b16 v[238:239], v114 offset:45056
	ds_read_b64_tr_b16 v[240:241], v115 offset:45056
	v_exp_f32_e32 v80, v80
	v_exp_f32_e32 v81, v81
	v_cvt_pk_bf16_f32 v196, v74, v75
	v_mfma_f32_32x32x16_bf16 v[2:17], v[250:253], v[188:191], v[2:17]
	ds_read_b64_tr_b16 v[242:243], v116 offset:45056
	ds_read_b64_tr_b16 v[244:245], v117 offset:45056
	v_cvt_pk_bf16_f32 v197, v76, v77
	v_cvt_pk_bf16_f32 v198, v78, v79
	v_cvt_pk_bf16_f32 v199, v80, v81
	s_waitcnt lgkmcnt(8)
	v_mfma_f32_32x32x16_bf16 v[50:65], v[136:139], v[192:195], v[50:65]
	ds_read_b64_tr_b16 v[246:247], v118 offset:45056
	ds_read_b64_tr_b16 v[248:249], v119 offset:45056
	v_add_f32_e32 v0, v66, v67
	v_add_f32_e32 v203, v68, v69
	v_add_f32_e32 v0, v0, v70
	v_mfma_f32_32x32x16_bf16 v[34:49], v[140:143], v[192:195], v[34:49]
	ds_read_b64_tr_b16 v[250:251], v120 offset:45056
	ds_read_b64_tr_b16 v[252:253], v121 offset:45056
	v_add_f32_e32 v203, v203, v71
	v_add_f32_e32 v0, v0, v72
	v_add_f32_e32 v203, v203, v73
	s_waitcnt lgkmcnt(8)
	v_mfma_f32_32x32x16_bf16 v[18:33], v[204:207], v[192:195], v[18:33]
	v_add_f32_e32 v0, v0, v203
	v_add_f32_e32 v167, v167, v0
	v_add_f32_e32 v0, v74, v75
	v_mfma_f32_32x32x16_bf16 v[2:17], v[208:211], v[192:195], v[2:17]
	v_add_f32_e32 v203, v76, v77
	v_add_f32_e32 v0, v0, v78
	v_add_f32_e32 v203, v203, v79
	s_waitcnt lgkmcnt(4)
	v_mfma_f32_32x32x16_bf16 v[50:65], v[238:241], v[196:199], v[50:65]
	v_add_f32_e32 v0, v0, v80
	v_add_f32_e32 v203, v203, v81
	v_add_f32_e32 v0, v0, v203
	v_mfma_f32_32x32x16_bf16 v[34:49], v[242:245], v[196:199], v[34:49]
	v_add_f32_e32 v167, v167, v0
	s_waitcnt lgkmcnt(0)
	v_mfma_f32_32x32x16_bf16 v[18:33], v[246:249], v[196:199], v[18:33]
	v_mfma_f32_32x32x16_bf16 v[2:17], v[250:253], v[196:199], v[2:17]
	s_add_i32 s62, s50, 64
	s_cmp_gt_u32 s62, s2
	s_cbranch_scc1 .Lat2_tB_end
	s_cmp_gt_u32 s62, s38
	s_cbranch_scc1 .Lat2_tB_end
	s_add_i32 s62, s50, 64
	s_lshl_b32 s39, s62, 8
	s_lshl_b32 s62, s62, 9
	s_and_b32 s39, s39, 0x4000
	s_and_b32 s62, s62, 0x10000
	s_or_b32 s62, s62, s39
	v_add_u32_e32 v0, s62, v178
	ds_read_b128 v[136:139], v0
	ds_read_b128 v[140:143], v0 offset:8192
	v_add_u32_e32 v0, s62, v181
	ds_read_b128 v[204:207], v0
	ds_read_b128 v[208:211], v0 offset:8192
	v_add_u32_e32 v0, s62, v180
	ds_read_b128 v[238:241], v0
	ds_read_b128 v[242:245], v0 offset:8192
	v_add_u32_e32 v0, s62, v179
	ds_read_b128 v[246:249], v0
	ds_read_b128 v[250:253], v0 offset:8192
